# gdn_prep forward substitution rewritten with v_pk_fma_f32 on row pairs (A stored row-pair interleaved in LDS; same f32 FMA order per row), 1024 instead of 2016 FMA instructions per thread
# speedup vs baseline: 1.0095x; 1.0033x over previous
.LBB0_473:
	s_or_b64 exec, exec, s[6:7]
	v_mul_lo_u32 v20, v18, s71
	v_lshlrev_b32_e32 v12, 3, v11
	v_add3_u32 v23, v143, v20, v12
	ds_write_b32 v23, v16 offset:62464
	v_mul_f32_e32 v2, v2, v21
	ds_read_b32 v21, v17 offset:34820
	v_lshlrev_b32_e32 v6, 2, v42
	v_and_b32_e32 v6, 48, v6
	s_lshl_b32 s6, s53, 5
	v_and_or_b32 v15, s6, 64, v6
	s_lshl_b32 s6, s8, 7
	s_waitcnt lgkmcnt(0)
	v_sub_f32_e32 v21, v21, v19
	v_or3_b32 v6, v15, s6, v43
	v_and_b32_e32 v44, 3, v102
	s_lshr_b32 s6, s54, 4
	v_mul_f32_e32 v21, 0x3fb8aa3b, v21
	v_and_or_b32 v22, s6, 4, v44
	v_exp_f32_e32 v21, v21
	v_cvt_pk_bf16_f32 v2, v2, s0
	v_cmp_ge_i32_e32 vcc, v18, v11
	v_lshlrev_b32_e32 v6, 4, v6
	v_lshlrev_b32_e32 v16, 1, v22
	v_cndmask_b32_e32 v2, 0, v2, vcc
	v_add3_u32 v6, v143, v6, v16
	ds_write_b16 v6, v2 offset:36864
	v_mov_b32_e32 v2, 0
	v_mov_b32_e32 v22, 0
	s_and_saveexec_b64 s[6:7], vcc
	s_cbranch_execz .LBB0_475
	ds_read_b32 v22, v17 offset:35076
	s_waitcnt lgkmcnt(0)
	v_mul_f32_e32 v22, v21, v22
	v_mul_f32_e32 v22, v7, v22
.LBB0_475:
	s_or_b64 exec, exec, s[6:7]
	v_add_u32_e32 v7, 0x110, v20
	v_add3_u32 v20, v143, v7, v12
	ds_write_b32 v20, v22 offset:62196
	ds_read_b32 v20, v17 offset:34824
	v_mul_f32_e32 v3, v3, v21
	v_or_b32_e32 v23, 1, v18
	v_cvt_pk_bf16_f32 v3, v3, s0
	v_cmp_ge_i32_e32 vcc, v23, v11
	s_waitcnt lgkmcnt(0)
	v_sub_f32_e32 v20, v20, v19
	v_mul_f32_e32 v20, 0x3fb8aa3b, v20
	v_exp_f32_e32 v21, v20
	v_or_b32_e32 v20, 2, v18
	v_cndmask_b32_e32 v3, 0, v3, vcc
	v_cmp_gt_i32_e32 vcc, v20, v11
	ds_write_b16 v6, v3 offset:36880
	s_and_saveexec_b64 s[6:7], vcc
	s_cbranch_execz .LBB0_477
	ds_read_b32 v2, v17 offset:35080
	s_waitcnt lgkmcnt(0)
	v_mul_f32_e32 v2, v21, v2
	v_mul_f32_e32 v2, v8, v2

.LBB0_479:
	s_or_b64 exec, exec, s[6:7]
	s_ashr_i32 s52, s54, 6
	ds_write_b32 v3, v8 offset:62468
	v_mul_f32_e32 v3, v5, v7
	s_add_i32 s6, s52, 4
	v_cvt_pk_bf16_f32 v3, v3, s0
	v_cmp_ge_i32_e32 vcc, v4, v11
	s_ashr_i32 s7, s6, 2
	s_lshl_b32 s8, s7, 4
	v_cndmask_b32_e32 v3, 0, v3, vcc
	ds_write_b16 v6, v3 offset:36912
	s_cmp_gt_i32 s53, s7
	v_mov_b32_e32 v3, 0
	v_mov_b32_e32 v4, 0
	v_mov_b32_e32 v5, 0
	v_mov_b32_e32 v6, 0
	v_mov_b32_e32 v7, 0
	v_mov_b32_e32 v8, 0
	v_mov_b32_e32 v9, 0
	s_cbranch_scc1 .LBB0_481
	v_or_b32_e32 v2, s8, v42
	v_mad_u64_u32 v[34:35], s[54:55], v2, s71, v[10:11]
	ds_read_b128 v[2:5], v34 offset:17408
	ds_read_b128 v[6:9], v13 offset:17408
	ds_read_b128 v[18:21], v13 offset:17472
	ds_read_b128 v[22:25], v34 offset:17472
	ds_read_b128 v[26:29], v34
	ds_read_b128 v[30:33], v34 offset:64
	s_waitcnt lgkmcnt(4)
	v_mfma_f32_16x16x32_bf16 v[2:5], v[2:5], v[6:9], 0
	s_waitcnt lgkmcnt(2)
	v_mfma_f32_16x16x32_bf16 v[2:5], v[22:25], v[18:21], v[2:5]
	ds_read_b128 v[22:25], v34 offset:17536
	s_waitcnt lgkmcnt(2)
	v_mfma_f32_16x16x32_bf16 v[6:9], v[26:29], v[6:9], 0
	s_waitcnt lgkmcnt(1)
	v_mfma_f32_16x16x32_bf16 v[6:9], v[30:33], v[18:21], v[6:9]
	ds_read_b128 v[18:21], v13 offset:17536
	ds_read_b128 v[26:29], v13 offset:17600
	ds_read_b128 v[30:33], v34 offset:17600
	s_waitcnt lgkmcnt(2)
	v_mfma_f32_16x16x32_bf16 v[2:5], v[22:25], v[18:21], v[2:5]
	ds_read_b128 v[22:25], v34 offset:128
	ds_read_b128 v[34:37], v34 offset:192
	s_waitcnt lgkmcnt(1)
	v_mfma_f32_16x16x32_bf16 v[18:21], v[22:25], v[18:21], v[6:9]
	v_mfma_f32_16x16x32_bf16 v[6:9], v[30:33], v[26:29], v[2:5]
	s_waitcnt lgkmcnt(0)
	v_mfma_f32_16x16x32_bf16 v[2:5], v[34:37], v[26:29], v[18:21]

.LBB0_485:
	s_or_b64 exec, exec, s[8:9]
	v_add_u32_e32 v6, 0x110, v6
	v_add3_u32 v22, v143, v6, v12
	ds_write_b32 v22, v20 offset:62196
	ds_read_b32 v20, v17 offset:34824
	v_or_b32_e32 v7, 1, v18
	v_mul_f32_e32 v3, v3, v21
	v_cvt_pk_bf16_f32 v3, v3, s0
	v_cmp_ge_i32_e32 vcc, v7, v11
	v_or_b32_e32 v7, 2, v18
	v_mov_b32_e32 v21, 0
	v_cndmask_b32_e32 v3, 0, v3, vcc
	ds_write_b16 v2, v3 offset:36880
	s_waitcnt lgkmcnt(1)
	v_sub_f32_e32 v3, v20, v19
	v_mul_f32_e32 v3, 0x3fb8aa3b, v3
	v_exp_f32_e32 v20, v3
	v_cmp_gt_i32_e32 vcc, v7, v11
	v_mov_b32_e32 v3, 0
	s_and_saveexec_b64 s[8:9], vcc
	s_cbranch_execz .LBB0_487
	ds_read_b32 v21, v17 offset:35080
	s_waitcnt lgkmcnt(0)
	v_mul_f32_e32 v21, v20, v21
	v_mul_f32_e32 v21, v8, v21

.LBB0_489:
	s_or_b64 exec, exec, s[8:9]
	ds_write_b32 v6, v3 offset:62468
	v_mul_f32_e32 v3, v5, v7
	s_add_i32 s8, s52, 8
	v_cvt_pk_bf16_f32 v3, v3, s0
	v_cmp_ge_i32_e32 vcc, v4, v11
	s_ashr_i32 s7, s8, 2
	s_lshl_b32 s9, s7, 4
	v_cndmask_b32_e32 v3, 0, v3, vcc
	ds_write_b16 v2, v3 offset:36912
	s_cmp_gt_i32 s53, s7
	v_mov_b32_e32 v20, 0
	v_mov_b32_e32 v2, 0
	v_mov_b32_e32 v3, 0
	v_mov_b32_e32 v4, 0
	v_mov_b32_e32 v5, 0
	v_mov_b32_e32 v6, 0
	v_mov_b32_e32 v7, 0
	v_mov_b32_e32 v8, 0
	v_mov_b32_e32 v9, 0
	s_cbranch_scc1 .LBB0_491
	v_or_b32_e32 v2, s9, v42
	v_mad_u64_u32 v[18:19], s[54:55], v2, s71, v[10:11]
	ds_read_b128 v[2:5], v18 offset:17408
	ds_read_b128 v[6:9], v13 offset:17408
	ds_read_b128 v[22:25], v13 offset:17472
	ds_read_b128 v[26:29], v18 offset:17472
	ds_read_b128 v[30:33], v18
	ds_read_b128 v[34:37], v18 offset:64
	s_waitcnt lgkmcnt(4)
	v_mfma_f32_16x16x32_bf16 v[2:5], v[2:5], v[6:9], 0
	s_waitcnt lgkmcnt(2)
	v_mfma_f32_16x16x32_bf16 v[2:5], v[26:29], v[22:25], v[2:5]
	ds_read_b128 v[26:29], v18 offset:17536
	s_waitcnt lgkmcnt(2)
	v_mfma_f32_16x16x32_bf16 v[6:9], v[30:33], v[6:9], 0
	s_waitcnt lgkmcnt(1)
	v_mfma_f32_16x16x32_bf16 v[6:9], v[34:37], v[22:25], v[6:9]
	ds_read_b128 v[22:25], v13 offset:17536
	ds_read_b128 v[30:33], v13 offset:17600
	ds_read_b128 v[34:37], v18 offset:17600
	s_waitcnt lgkmcnt(2)
	v_mfma_f32_16x16x32_bf16 v[2:5], v[26:29], v[22:25], v[2:5]
	ds_read_b128 v[26:29], v18 offset:128
	ds_read_b128 v[38:41], v18 offset:192
	s_waitcnt lgkmcnt(1)
	v_mfma_f32_16x16x32_bf16 v[22:25], v[26:29], v[22:25], v[6:9]
	v_mfma_f32_16x16x32_bf16 v[6:9], v[34:37], v[30:33], v[2:5]
	s_waitcnt lgkmcnt(0)
	v_mfma_f32_16x16x32_bf16 v[2:5], v[38:41], v[30:33], v[22:25]

.LBB0_495:
	s_or_b64 exec, exec, s[54:55]
	v_add_u32_e32 v7, 0x110, v21
	v_add3_u32 v21, v143, v7, v12
	ds_write_b32 v21, v22 offset:62196
	ds_read_b32 v21, v17 offset:34824
	v_mul_f32_e32 v3, v3, v20
	v_or_b32_e32 v23, 1, v18
	v_cvt_pk_bf16_f32 v3, v3, s0
	v_cmp_ge_i32_e32 vcc, v23, v11
	s_waitcnt lgkmcnt(0)
	v_sub_f32_e32 v20, v21, v19
	v_mul_f32_e32 v20, 0x3fb8aa3b, v20
	v_exp_f32_e32 v21, v20
	v_or_b32_e32 v20, 2, v18
	v_cndmask_b32_e32 v3, 0, v3, vcc
	v_cmp_gt_i32_e32 vcc, v20, v11
	ds_write_b16 v6, v3 offset:36880
	s_and_saveexec_b64 s[54:55], vcc
	s_cbranch_execz .LBB0_497
	ds_read_b32 v2, v17 offset:35080
	s_waitcnt lgkmcnt(0)
	v_mul_f32_e32 v2, v21, v2
	v_mul_f32_e32 v2, v8, v2

.LBB0_499:
	s_or_b64 exec, exec, s[54:55]
	ds_write_b32 v3, v8 offset:62468
	v_mul_f32_e32 v3, v5, v7
	s_add_i32 s54, s52, 12
	v_cvt_pk_bf16_f32 v3, v3, s0
	v_cmp_ge_i32_e32 vcc, v4, v11
	s_ashr_i32 s7, s54, 2
	s_lshl_b32 s9, s7, 4
	v_cndmask_b32_e32 v3, 0, v3, vcc
	ds_write_b16 v6, v3 offset:36912
	s_cmp_gt_i32 s53, s7
	v_mov_b32_e32 v3, 0
	v_mov_b32_e32 v4, 0
	v_mov_b32_e32 v5, 0
	v_mov_b32_e32 v6, 0
	v_mov_b32_e32 v7, 0
	v_mov_b32_e32 v8, 0
	v_mov_b32_e32 v9, 0
	s_cbranch_scc1 .LBB0_501
	v_or_b32_e32 v2, s9, v42
	v_mad_u64_u32 v[34:35], s[56:57], v2, s71, v[10:11]
	ds_read_b128 v[2:5], v34 offset:17408
	ds_read_b128 v[6:9], v13 offset:17408
	ds_read_b128 v[18:21], v13 offset:17472
	ds_read_b128 v[22:25], v34 offset:17472
	ds_read_b128 v[26:29], v34
	ds_read_b128 v[30:33], v34 offset:64
	s_waitcnt lgkmcnt(4)
	v_mfma_f32_16x16x32_bf16 v[2:5], v[2:5], v[6:9], 0
	s_waitcnt lgkmcnt(2)
	v_mfma_f32_16x16x32_bf16 v[2:5], v[22:25], v[18:21], v[2:5]
	ds_read_b128 v[22:25], v34 offset:17536
	s_waitcnt lgkmcnt(2)
	v_mfma_f32_16x16x32_bf16 v[6:9], v[26:29], v[6:9], 0
	s_waitcnt lgkmcnt(1)
	v_mfma_f32_16x16x32_bf16 v[6:9], v[30:33], v[18:21], v[6:9]
	ds_read_b128 v[18:21], v13 offset:17536
	ds_read_b128 v[26:29], v13 offset:17600
	ds_read_b128 v[30:33], v34 offset:17600
	s_waitcnt lgkmcnt(2)
	v_mfma_f32_16x16x32_bf16 v[2:5], v[22:25], v[18:21], v[2:5]
	ds_read_b128 v[22:25], v34 offset:128
	ds_read_b128 v[34:37], v34 offset:192
	s_waitcnt lgkmcnt(1)
	v_mfma_f32_16x16x32_bf16 v[18:21], v[22:25], v[18:21], v[6:9]
	v_mfma_f32_16x16x32_bf16 v[6:9], v[30:33], v[26:29], v[2:5]
	s_waitcnt lgkmcnt(0)
	v_mfma_f32_16x16x32_bf16 v[2:5], v[34:37], v[26:29], v[18:21]

.LBB0_505:
	s_or_b64 exec, exec, s[56:57]
	v_add_u32_e32 v6, 0x110, v6
	v_add3_u32 v16, v143, v6, v12
	ds_write_b32 v16, v17 offset:62196
	v_mul_f32_e32 v3, v3, v15
	ds_read_b32 v15, v10 offset:34824
	v_or_b32_e32 v7, 1, v13
	v_cvt_pk_bf16_f32 v3, v3, s0
	v_cmp_ge_i32_e32 vcc, v7, v11
	v_or_b32_e32 v7, 2, v13
	v_mov_b32_e32 v16, 0
	v_cndmask_b32_e32 v3, 0, v3, vcc
	ds_write_b16 v2, v3 offset:36880
	s_waitcnt lgkmcnt(1)
	v_sub_f32_e32 v3, v15, v14
	v_mul_f32_e32 v3, 0x3fb8aa3b, v3
	v_exp_f32_e32 v15, v3
	v_cmp_gt_i32_e32 vcc, v7, v11
	v_mov_b32_e32 v3, 0
	s_and_saveexec_b64 s[56:57], vcc
	s_cbranch_execz .LBB0_507
	ds_read_b32 v16, v10 offset:35080
	s_waitcnt lgkmcnt(0)
	v_mul_f32_e32 v16, v15, v16
	v_mul_f32_e32 v16, v8, v16

.LBB0_509:
	s_or_b64 exec, exec, s[56:57]
	ds_write_b32 v6, v3 offset:62468
	v_mul_f32_e32 v3, v5, v7
	v_cvt_pk_bf16_f32 v3, v3, s0
	v_cmp_ge_i32_e32 vcc, v4, v11
	s_nop 1
	v_cndmask_b32_e32 v3, 0, v3, vcc
	ds_write_b16 v2, v3 offset:36912
	s_waitcnt lgkmcnt(0)
	s_and_saveexec_b64 s[56:57], s[4:5]
	s_xor_b64 s[56:57], exec, s[56:57]
	ds_add_u32 v169, v170 offset:36352
	s_or_b64 exec, exec, s[56:57]
	ds_read_b32 v2, v169 offset:36352
	s_add_i32 s7, s3, 12
	s_waitcnt lgkmcnt(0)
	v_cmp_gt_u32_e32 vcc, s7, v2
	s_and_saveexec_b64 s[56:57], vcc
	s_cbranch_execz .LBB0_514
	s_mov_b64 s[58:59], 0

.LBB0_514:
	s_or_b64 exec, exec, s[56:57]
	v_cmp_gt_i32_e32 vcc, s75, v102
	v_and_b32_e32 v31, 0x7f, v102
	v_add_u32_e32 v32, 0xf400, v143
	v_cndmask_b32_e32 v30, v163, v168, vcc
	v_lshl_add_u32 v30, v31, 1, v30
	v_cndmask_b32_e32 v31, v167, v164, vcc
	ds_read_u16 v26, v30 offset:0
	ds_read_u16 v27, v30 offset:272
	ds_read_b64 v[28:29], v31 offset:0
	ds_read_b128 v[2:5], v32 offset:0
	ds_read_u16 v152, v30 offset:544
	ds_read_u16 v153, v30 offset:816
	ds_read_b64 v[154:155], v31 offset:8
	ds_read_b128 v[120:123], v32 offset:544
	ds_read_b128 v[124:127], v32 offset:560
	s_waitcnt lgkmcnt(5)
	v_lshlrev_b32_e32 v26, 16, v26
	v_lshlrev_b32_e32 v27, 16, v27
	v_pk_mul_f32 v[46:47], v[26:27], v[28:29]
	v_fma_f32 v47, -v3, v46, v47
	ds_read_u16 v26, v30 offset:1088
	ds_read_u16 v27, v30 offset:1360
	ds_read_b64 v[28:29], v31 offset:16
	ds_read_b128 v[2:5], v32 offset:1088
	ds_read_b128 v[6:9], v32 offset:1104
	ds_read_b128 v[10:13], v32 offset:1120
	s_waitcnt lgkmcnt(6)
	v_lshlrev_b32_e32 v152, 16, v152
	v_lshlrev_b32_e32 v153, 16, v153
	v_pk_mul_f32 v[48:49], v[152:153], v[154:155]
	v_pk_fma_f32 v[48:49], v[120:121], v[46:47], v[48:49] op_sel_hi:[1,0,1] neg_lo:[1,0,0] neg_hi:[1,0,0]
	v_pk_fma_f32 v[48:49], v[122:123], v[46:47], v[48:49] op_sel:[0,1,0] op_sel_hi:[1,1,1] neg_lo:[1,0,0] neg_hi:[1,0,0]
	v_fma_f32 v49, -v125, v48, v49
	ds_read_u16 v152, v30 offset:1632
	ds_read_u16 v153, v30 offset:1904
	ds_read_b64 v[154:155], v31 offset:24
	ds_read_b128 v[120:123], v32 offset:1632
	ds_read_b128 v[124:127], v32 offset:1648
	ds_read_b128 v[128:131], v32 offset:1664
	ds_read_b128 v[132:135], v32 offset:1680
	s_waitcnt lgkmcnt(7)
	v_lshlrev_b32_e32 v26, 16, v26
	v_lshlrev_b32_e32 v27, 16, v27
	v_pk_mul_f32 v[50:51], v[26:27], v[28:29]
	v_pk_fma_f32 v[50:51], v[2:3], v[46:47], v[50:51] op_sel_hi:[1,0,1] neg_lo:[1,0,0] neg_hi:[1,0,0]
	v_pk_fma_f32 v[50:51], v[4:5], v[46:47], v[50:51] op_sel:[0,1,0] op_sel_hi:[1,1,1] neg_lo:[1,0,0] neg_hi:[1,0,0]
	v_pk_fma_f32 v[50:51], v[6:7], v[48:49], v[50:51] op_sel_hi:[1,0,1] neg_lo:[1,0,0] neg_hi:[1,0,0]
	v_pk_fma_f32 v[50:51], v[8:9], v[48:49], v[50:51] op_sel:[0,1,0] op_sel_hi:[1,1,1] neg_lo:[1,0,0] neg_hi:[1,0,0]
	v_fma_f32 v51, -v11, v50, v51
	ds_read_u16 v26, v30 offset:2176
	ds_read_u16 v27, v30 offset:2448
	ds_read_b64 v[28:29], v31 offset:32
	ds_read_b128 v[2:5], v32 offset:2176
	ds_read_b128 v[6:9], v32 offset:2192
	ds_read_b128 v[10:13], v32 offset:2208
	ds_read_b128 v[14:17], v32 offset:2224
	ds_read_b128 v[18:21], v32 offset:2240
	s_waitcnt lgkmcnt(8)
	v_lshlrev_b32_e32 v152, 16, v152
	v_lshlrev_b32_e32 v153, 16, v153
	v_pk_mul_f32 v[52:53], v[152:153], v[154:155]
	v_pk_fma_f32 v[52:53], v[120:121], v[46:47], v[52:53] op_sel_hi:[1,0,1] neg_lo:[1,0,0] neg_hi:[1,0,0]
	v_pk_fma_f32 v[52:53], v[122:123], v[46:47], v[52:53] op_sel:[0,1,0] op_sel_hi:[1,1,1] neg_lo:[1,0,0] neg_hi:[1,0,0]
	v_pk_fma_f32 v[52:53], v[124:125], v[48:49], v[52:53] op_sel_hi:[1,0,1] neg_lo:[1,0,0] neg_hi:[1,0,0]
	v_pk_fma_f32 v[52:53], v[126:127], v[48:49], v[52:53] op_sel:[0,1,0] op_sel_hi:[1,1,1] neg_lo:[1,0,0] neg_hi:[1,0,0]
	v_pk_fma_f32 v[52:53], v[128:129], v[50:51], v[52:53] op_sel_hi:[1,0,1] neg_lo:[1,0,0] neg_hi:[1,0,0]
	v_pk_fma_f32 v[52:53], v[130:131], v[50:51], v[52:53] op_sel:[0,1,0] op_sel_hi:[1,1,1] neg_lo:[1,0,0] neg_hi:[1,0,0]
	v_fma_f32 v53, -v133, v52, v53
	ds_read_u16 v152, v30 offset:2720
	ds_read_u16 v153, v30 offset:2992
	ds_read_b64 v[154:155], v31 offset:40
	ds_read_b128 v[120:123], v32 offset:2720
	ds_read_b128 v[124:127], v32 offset:2736
	ds_read_b128 v[128:131], v32 offset:2752
	ds_read_b128 v[132:135], v32 offset:2768
	ds_read_b128 v[144:147], v32 offset:2784
	ds_read_b128 v[148:151], v32 offset:2800
	s_waitcnt lgkmcnt(9)
	v_lshlrev_b32_e32 v26, 16, v26
	v_lshlrev_b32_e32 v27, 16, v27
	v_pk_mul_f32 v[54:55], v[26:27], v[28:29]
	v_pk_fma_f32 v[54:55], v[2:3], v[46:47], v[54:55] op_sel_hi:[1,0,1] neg_lo:[1,0,0] neg_hi:[1,0,0]
	v_pk_fma_f32 v[54:55], v[4:5], v[46:47], v[54:55] op_sel:[0,1,0] op_sel_hi:[1,1,1] neg_lo:[1,0,0] neg_hi:[1,0,0]
	v_pk_fma_f32 v[54:55], v[6:7], v[48:49], v[54:55] op_sel_hi:[1,0,1] neg_lo:[1,0,0] neg_hi:[1,0,0]
	v_pk_fma_f32 v[54:55], v[8:9], v[48:49], v[54:55] op_sel:[0,1,0] op_sel_hi:[1,1,1] neg_lo:[1,0,0] neg_hi:[1,0,0]
	v_pk_fma_f32 v[54:55], v[10:11], v[50:51], v[54:55] op_sel_hi:[1,0,1] neg_lo:[1,0,0] neg_hi:[1,0,0]
	v_pk_fma_f32 v[54:55], v[12:13], v[50:51], v[54:55] op_sel:[0,1,0] op_sel_hi:[1,1,1] neg_lo:[1,0,0] neg_hi:[1,0,0]
	v_pk_fma_f32 v[54:55], v[14:15], v[52:53], v[54:55] op_sel_hi:[1,0,1] neg_lo:[1,0,0] neg_hi:[1,0,0]
	v_pk_fma_f32 v[54:55], v[16:17], v[52:53], v[54:55] op_sel:[0,1,0] op_sel_hi:[1,1,1] neg_lo:[1,0,0] neg_hi:[1,0,0]
	v_fma_f32 v55, -v19, v54, v55
	ds_read_u16 v26, v30 offset:3264
	ds_read_u16 v27, v30 offset:3536
	ds_read_b64 v[28:29], v31 offset:48
	ds_read_b128 v[2:5], v32 offset:3264
	ds_read_b128 v[6:9], v32 offset:3280
	ds_read_b128 v[10:13], v32 offset:3296
	ds_read_b128 v[14:17], v32 offset:3312
	ds_read_b128 v[18:21], v32 offset:3328
	ds_read_b128 v[22:25], v32 offset:3344
	s_waitcnt lgkmcnt(9)
	v_lshlrev_b32_e32 v152, 16, v152
	v_lshlrev_b32_e32 v153, 16, v153
	v_pk_mul_f32 v[56:57], v[152:153], v[154:155]
	v_pk_fma_f32 v[56:57], v[120:121], v[46:47], v[56:57] op_sel_hi:[1,0,1] neg_lo:[1,0,0] neg_hi:[1,0,0]
	v_pk_fma_f32 v[56:57], v[122:123], v[46:47], v[56:57] op_sel:[0,1,0] op_sel_hi:[1,1,1] neg_lo:[1,0,0] neg_hi:[1,0,0]
	v_pk_fma_f32 v[56:57], v[124:125], v[48:49], v[56:57] op_sel_hi:[1,0,1] neg_lo:[1,0,0] neg_hi:[1,0,0]
	v_pk_fma_f32 v[56:57], v[126:127], v[48:49], v[56:57] op_sel:[0,1,0] op_sel_hi:[1,1,1] neg_lo:[1,0,0] neg_hi:[1,0,0]
	v_pk_fma_f32 v[56:57], v[128:129], v[50:51], v[56:57] op_sel_hi:[1,0,1] neg_lo:[1,0,0] neg_hi:[1,0,0]
	v_pk_fma_f32 v[56:57], v[130:131], v[50:51], v[56:57] op_sel:[0,1,0] op_sel_hi:[1,1,1] neg_lo:[1,0,0] neg_hi:[1,0,0]
	v_pk_fma_f32 v[56:57], v[132:133], v[52:53], v[56:57] op_sel_hi:[1,0,1] neg_lo:[1,0,0] neg_hi:[1,0,0]
	v_pk_fma_f32 v[56:57], v[134:135], v[52:53], v[56:57] op_sel:[0,1,0] op_sel_hi:[1,1,1] neg_lo:[1,0,0] neg_hi:[1,0,0]
	v_pk_fma_f32 v[56:57], v[144:145], v[54:55], v[56:57] op_sel_hi:[1,0,1] neg_lo:[1,0,0] neg_hi:[1,0,0]
	v_pk_fma_f32 v[56:57], v[146:147], v[54:55], v[56:57] op_sel:[0,1,0] op_sel_hi:[1,1,1] neg_lo:[1,0,0] neg_hi:[1,0,0]
	v_fma_f32 v57, -v149, v56, v57
	ds_read_b128 v[120:123], v32 offset:3360
	s_waitcnt lgkmcnt(1)
	v_lshlrev_b32_e32 v26, 16, v26
	v_lshlrev_b32_e32 v27, 16, v27
	v_pk_mul_f32 v[58:59], v[26:27], v[28:29]
	v_pk_fma_f32 v[58:59], v[2:3], v[46:47], v[58:59] op_sel_hi:[1,0,1] neg_lo:[1,0,0] neg_hi:[1,0,0]
	v_pk_fma_f32 v[58:59], v[4:5], v[46:47], v[58:59] op_sel:[0,1,0] op_sel_hi:[1,1,1] neg_lo:[1,0,0] neg_hi:[1,0,0]
	v_pk_fma_f32 v[58:59], v[6:7], v[48:49], v[58:59] op_sel_hi:[1,0,1] neg_lo:[1,0,0] neg_hi:[1,0,0]
	v_pk_fma_f32 v[58:59], v[8:9], v[48:49], v[58:59] op_sel:[0,1,0] op_sel_hi:[1,1,1] neg_lo:[1,0,0] neg_hi:[1,0,0]
	v_pk_fma_f32 v[58:59], v[10:11], v[50:51], v[58:59] op_sel_hi:[1,0,1] neg_lo:[1,0,0] neg_hi:[1,0,0]
	v_pk_fma_f32 v[58:59], v[12:13], v[50:51], v[58:59] op_sel:[0,1,0] op_sel_hi:[1,1,1] neg_lo:[1,0,0] neg_hi:[1,0,0]
	v_pk_fma_f32 v[58:59], v[14:15], v[52:53], v[58:59] op_sel_hi:[1,0,1] neg_lo:[1,0,0] neg_hi:[1,0,0]
	v_pk_fma_f32 v[58:59], v[16:17], v[52:53], v[58:59] op_sel:[0,1,0] op_sel_hi:[1,1,1] neg_lo:[1,0,0] neg_hi:[1,0,0]
	v_pk_fma_f32 v[58:59], v[18:19], v[54:55], v[58:59] op_sel_hi:[1,0,1] neg_lo:[1,0,0] neg_hi:[1,0,0]
	v_pk_fma_f32 v[58:59], v[20:21], v[54:55], v[58:59] op_sel:[0,1,0] op_sel_hi:[1,1,1] neg_lo:[1,0,0] neg_hi:[1,0,0]
	v_pk_fma_f32 v[58:59], v[22:23], v[56:57], v[58:59] op_sel_hi:[1,0,1] neg_lo:[1,0,0] neg_hi:[1,0,0]
	v_pk_fma_f32 v[58:59], v[24:25], v[56:57], v[58:59] op_sel:[0,1,0] op_sel_hi:[1,1,1] neg_lo:[1,0,0] neg_hi:[1,0,0]
	ds_read_u16 v26, v30 offset:3808
	ds_read_u16 v27, v30 offset:4080
	ds_read_b64 v[28:29], v31 offset:56
	ds_read_b128 v[2:5], v32 offset:3808
	ds_read_b128 v[6:9], v32 offset:3824
	ds_read_b128 v[10:13], v32 offset:3840
	ds_read_b128 v[14:17], v32 offset:3856
	ds_read_b128 v[18:21], v32 offset:3872
	ds_read_b128 v[22:25], v32 offset:3888
	s_waitcnt lgkmcnt(9)
	v_fma_f32 v59, -v121, v58, v59
	ds_read_b128 v[120:123], v32 offset:3904
	ds_read_b128 v[124:127], v32 offset:3920
	s_waitcnt lgkmcnt(2)
	v_lshlrev_b32_e32 v26, 16, v26
	v_lshlrev_b32_e32 v27, 16, v27
	v_pk_mul_f32 v[60:61], v[26:27], v[28:29]
	v_pk_fma_f32 v[60:61], v[2:3], v[46:47], v[60:61] op_sel_hi:[1,0,1] neg_lo:[1,0,0] neg_hi:[1,0,0]
	v_pk_fma_f32 v[60:61], v[4:5], v[46:47], v[60:61] op_sel:[0,1,0] op_sel_hi:[1,1,1] neg_lo:[1,0,0] neg_hi:[1,0,0]
	v_pk_fma_f32 v[60:61], v[6:7], v[48:49], v[60:61] op_sel_hi:[1,0,1] neg_lo:[1,0,0] neg_hi:[1,0,0]
	v_pk_fma_f32 v[60:61], v[8:9], v[48:49], v[60:61] op_sel:[0,1,0] op_sel_hi:[1,1,1] neg_lo:[1,0,0] neg_hi:[1,0,0]
	v_pk_fma_f32 v[60:61], v[10:11], v[50:51], v[60:61] op_sel_hi:[1,0,1] neg_lo:[1,0,0] neg_hi:[1,0,0]
	v_pk_fma_f32 v[60:61], v[12:13], v[50:51], v[60:61] op_sel:[0,1,0] op_sel_hi:[1,1,1] neg_lo:[1,0,0] neg_hi:[1,0,0]
	v_pk_fma_f32 v[60:61], v[14:15], v[52:53], v[60:61] op_sel_hi:[1,0,1] neg_lo:[1,0,0] neg_hi:[1,0,0]
	v_pk_fma_f32 v[60:61], v[16:17], v[52:53], v[60:61] op_sel:[0,1,0] op_sel_hi:[1,1,1] neg_lo:[1,0,0] neg_hi:[1,0,0]
	v_pk_fma_f32 v[60:61], v[18:19], v[54:55], v[60:61] op_sel_hi:[1,0,1] neg_lo:[1,0,0] neg_hi:[1,0,0]
	v_pk_fma_f32 v[60:61], v[20:21], v[54:55], v[60:61] op_sel:[0,1,0] op_sel_hi:[1,1,1] neg_lo:[1,0,0] neg_hi:[1,0,0]
	v_pk_fma_f32 v[60:61], v[22:23], v[56:57], v[60:61] op_sel_hi:[1,0,1] neg_lo:[1,0,0] neg_hi:[1,0,0]
	v_pk_fma_f32 v[60:61], v[24:25], v[56:57], v[60:61] op_sel:[0,1,0] op_sel_hi:[1,1,1] neg_lo:[1,0,0] neg_hi:[1,0,0]
	ds_read_u16 v26, v30 offset:4352
	ds_read_u16 v27, v30 offset:4624
	ds_read_b64 v[28:29], v31 offset:64
	ds_read_b128 v[2:5], v32 offset:4352
	ds_read_b128 v[6:9], v32 offset:4368
	ds_read_b128 v[10:13], v32 offset:4384
	ds_read_b128 v[14:17], v32 offset:4400
	ds_read_b128 v[18:21], v32 offset:4416
	ds_read_b128 v[22:25], v32 offset:4432
	s_waitcnt lgkmcnt(9)
	v_pk_fma_f32 v[60:61], v[120:121], v[58:59], v[60:61] op_sel_hi:[1,0,1] neg_lo:[1,0,0] neg_hi:[1,0,0]
	v_pk_fma_f32 v[60:61], v[122:123], v[58:59], v[60:61] op_sel:[0,1,0] op_sel_hi:[1,1,1] neg_lo:[1,0,0] neg_hi:[1,0,0]
	v_fma_f32 v61, -v125, v60, v61
	ds_read_b128 v[120:123], v32 offset:4448
	ds_read_b128 v[124:127], v32 offset:4464
	ds_read_b128 v[128:131], v32 offset:4480
	s_waitcnt lgkmcnt(3)
	v_lshlrev_b32_e32 v26, 16, v26
	v_lshlrev_b32_e32 v27, 16, v27
	v_pk_mul_f32 v[62:63], v[26:27], v[28:29]
	v_pk_fma_f32 v[62:63], v[2:3], v[46:47], v[62:63] op_sel_hi:[1,0,1] neg_lo:[1,0,0] neg_hi:[1,0,0]
	v_pk_fma_f32 v[62:63], v[4:5], v[46:47], v[62:63] op_sel:[0,1,0] op_sel_hi:[1,1,1] neg_lo:[1,0,0] neg_hi:[1,0,0]
	v_pk_fma_f32 v[62:63], v[6:7], v[48:49], v[62:63] op_sel_hi:[1,0,1] neg_lo:[1,0,0] neg_hi:[1,0,0]
	v_pk_fma_f32 v[62:63], v[8:9], v[48:49], v[62:63] op_sel:[0,1,0] op_sel_hi:[1,1,1] neg_lo:[1,0,0] neg_hi:[1,0,0]
	v_pk_fma_f32 v[62:63], v[10:11], v[50:51], v[62:63] op_sel_hi:[1,0,1] neg_lo:[1,0,0] neg_hi:[1,0,0]
	v_pk_fma_f32 v[62:63], v[12:13], v[50:51], v[62:63] op_sel:[0,1,0] op_sel_hi:[1,1,1] neg_lo:[1,0,0] neg_hi:[1,0,0]
	v_pk_fma_f32 v[62:63], v[14:15], v[52:53], v[62:63] op_sel_hi:[1,0,1] neg_lo:[1,0,0] neg_hi:[1,0,0]
	v_pk_fma_f32 v[62:63], v[16:17], v[52:53], v[62:63] op_sel:[0,1,0] op_sel_hi:[1,1,1] neg_lo:[1,0,0] neg_hi:[1,0,0]
	v_pk_fma_f32 v[62:63], v[18:19], v[54:55], v[62:63] op_sel_hi:[1,0,1] neg_lo:[1,0,0] neg_hi:[1,0,0]
	v_pk_fma_f32 v[62:63], v[20:21], v[54:55], v[62:63] op_sel:[0,1,0] op_sel_hi:[1,1,1] neg_lo:[1,0,0] neg_hi:[1,0,0]
	v_pk_fma_f32 v[62:63], v[22:23], v[56:57], v[62:63] op_sel_hi:[1,0,1] neg_lo:[1,0,0] neg_hi:[1,0,0]
	v_pk_fma_f32 v[62:63], v[24:25], v[56:57], v[62:63] op_sel:[0,1,0] op_sel_hi:[1,1,1] neg_lo:[1,0,0] neg_hi:[1,0,0]
	ds_read_u16 v26, v30 offset:4896
	ds_read_u16 v27, v30 offset:5168
	ds_read_b64 v[28:29], v31 offset:72
	ds_read_b128 v[2:5], v32 offset:4896
	ds_read_b128 v[6:9], v32 offset:4912
	ds_read_b128 v[10:13], v32 offset:4928
	ds_read_b128 v[14:17], v32 offset:4944
	ds_read_b128 v[18:21], v32 offset:4960
	ds_read_b128 v[22:25], v32 offset:4976
	s_waitcnt lgkmcnt(9)
	v_pk_fma_f32 v[62:63], v[120:121], v[58:59], v[62:63] op_sel_hi:[1,0,1] neg_lo:[1,0,0] neg_hi:[1,0,0]
	v_pk_fma_f32 v[62:63], v[122:123], v[58:59], v[62:63] op_sel:[0,1,0] op_sel_hi:[1,1,1] neg_lo:[1,0,0] neg_hi:[1,0,0]
	v_pk_fma_f32 v[62:63], v[124:125], v[60:61], v[62:63] op_sel_hi:[1,0,1] neg_lo:[1,0,0] neg_hi:[1,0,0]
	v_pk_fma_f32 v[62:63], v[126:127], v[60:61], v[62:63] op_sel:[0,1,0] op_sel_hi:[1,1,1] neg_lo:[1,0,0] neg_hi:[1,0,0]
	v_fma_f32 v63, -v129, v62, v63
	ds_read_b128 v[120:123], v32 offset:4992
	ds_read_b128 v[124:127], v32 offset:5008
	ds_read_b128 v[128:131], v32 offset:5024
	ds_read_b128 v[132:135], v32 offset:5040
	s_waitcnt lgkmcnt(4)
	v_lshlrev_b32_e32 v26, 16, v26
	v_lshlrev_b32_e32 v27, 16, v27
	v_pk_mul_f32 v[64:65], v[26:27], v[28:29]
	v_pk_fma_f32 v[64:65], v[2:3], v[46:47], v[64:65] op_sel_hi:[1,0,1] neg_lo:[1,0,0] neg_hi:[1,0,0]
	v_pk_fma_f32 v[64:65], v[4:5], v[46:47], v[64:65] op_sel:[0,1,0] op_sel_hi:[1,1,1] neg_lo:[1,0,0] neg_hi:[1,0,0]
	v_pk_fma_f32 v[64:65], v[6:7], v[48:49], v[64:65] op_sel_hi:[1,0,1] neg_lo:[1,0,0] neg_hi:[1,0,0]
	v_pk_fma_f32 v[64:65], v[8:9], v[48:49], v[64:65] op_sel:[0,1,0] op_sel_hi:[1,1,1] neg_lo:[1,0,0] neg_hi:[1,0,0]
	v_pk_fma_f32 v[64:65], v[10:11], v[50:51], v[64:65] op_sel_hi:[1,0,1] neg_lo:[1,0,0] neg_hi:[1,0,0]
	v_pk_fma_f32 v[64:65], v[12:13], v[50:51], v[64:65] op_sel:[0,1,0] op_sel_hi:[1,1,1] neg_lo:[1,0,0] neg_hi:[1,0,0]
	v_pk_fma_f32 v[64:65], v[14:15], v[52:53], v[64:65] op_sel_hi:[1,0,1] neg_lo:[1,0,0] neg_hi:[1,0,0]
	v_pk_fma_f32 v[64:65], v[16:17], v[52:53], v[64:65] op_sel:[0,1,0] op_sel_hi:[1,1,1] neg_lo:[1,0,0] neg_hi:[1,0,0]
	v_pk_fma_f32 v[64:65], v[18:19], v[54:55], v[64:65] op_sel_hi:[1,0,1] neg_lo:[1,0,0] neg_hi:[1,0,0]
	v_pk_fma_f32 v[64:65], v[20:21], v[54:55], v[64:65] op_sel:[0,1,0] op_sel_hi:[1,1,1] neg_lo:[1,0,0] neg_hi:[1,0,0]
	v_pk_fma_f32 v[64:65], v[22:23], v[56:57], v[64:65] op_sel_hi:[1,0,1] neg_lo:[1,0,0] neg_hi:[1,0,0]
	v_pk_fma_f32 v[64:65], v[24:25], v[56:57], v[64:65] op_sel:[0,1,0] op_sel_hi:[1,1,1] neg_lo:[1,0,0] neg_hi:[1,0,0]
	ds_read_u16 v26, v30 offset:5440
	ds_read_u16 v27, v30 offset:5712
	ds_read_b64 v[28:29], v31 offset:80
	ds_read_b128 v[2:5], v32 offset:5440
	ds_read_b128 v[6:9], v32 offset:5456
	ds_read_b128 v[10:13], v32 offset:5472
	ds_read_b128 v[14:17], v32 offset:5488
	ds_read_b128 v[18:21], v32 offset:5504
	ds_read_b128 v[22:25], v32 offset:5520
	s_waitcnt lgkmcnt(9)
	v_pk_fma_f32 v[64:65], v[120:121], v[58:59], v[64:65] op_sel_hi:[1,0,1] neg_lo:[1,0,0] neg_hi:[1,0,0]
	v_pk_fma_f32 v[64:65], v[122:123], v[58:59], v[64:65] op_sel:[0,1,0] op_sel_hi:[1,1,1] neg_lo:[1,0,0] neg_hi:[1,0,0]
	v_pk_fma_f32 v[64:65], v[124:125], v[60:61], v[64:65] op_sel_hi:[1,0,1] neg_lo:[1,0,0] neg_hi:[1,0,0]
	v_pk_fma_f32 v[64:65], v[126:127], v[60:61], v[64:65] op_sel:[0,1,0] op_sel_hi:[1,1,1] neg_lo:[1,0,0] neg_hi:[1,0,0]
	v_pk_fma_f32 v[64:65], v[128:129], v[62:63], v[64:65] op_sel_hi:[1,0,1] neg_lo:[1,0,0] neg_hi:[1,0,0]
	v_pk_fma_f32 v[64:65], v[130:131], v[62:63], v[64:65] op_sel:[0,1,0] op_sel_hi:[1,1,1] neg_lo:[1,0,0] neg_hi:[1,0,0]
	v_fma_f32 v65, -v133, v64, v65
	ds_read_b128 v[120:123], v32 offset:5536
	ds_read_b128 v[124:127], v32 offset:5552
	ds_read_b128 v[128:131], v32 offset:5568
	ds_read_b128 v[132:135], v32 offset:5584
	ds_read_b128 v[144:147], v32 offset:5600
	s_waitcnt lgkmcnt(5)
	v_lshlrev_b32_e32 v26, 16, v26
	v_lshlrev_b32_e32 v27, 16, v27
	v_pk_mul_f32 v[66:67], v[26:27], v[28:29]
	v_pk_fma_f32 v[66:67], v[2:3], v[46:47], v[66:67] op_sel_hi:[1,0,1] neg_lo:[1,0,0] neg_hi:[1,0,0]
	v_pk_fma_f32 v[66:67], v[4:5], v[46:47], v[66:67] op_sel:[0,1,0] op_sel_hi:[1,1,1] neg_lo:[1,0,0] neg_hi:[1,0,0]
	v_pk_fma_f32 v[66:67], v[6:7], v[48:49], v[66:67] op_sel_hi:[1,0,1] neg_lo:[1,0,0] neg_hi:[1,0,0]
	v_pk_fma_f32 v[66:67], v[8:9], v[48:49], v[66:67] op_sel:[0,1,0] op_sel_hi:[1,1,1] neg_lo:[1,0,0] neg_hi:[1,0,0]
	v_pk_fma_f32 v[66:67], v[10:11], v[50:51], v[66:67] op_sel_hi:[1,0,1] neg_lo:[1,0,0] neg_hi:[1,0,0]
	v_pk_fma_f32 v[66:67], v[12:13], v[50:51], v[66:67] op_sel:[0,1,0] op_sel_hi:[1,1,1] neg_lo:[1,0,0] neg_hi:[1,0,0]
	v_pk_fma_f32 v[66:67], v[14:15], v[52:53], v[66:67] op_sel_hi:[1,0,1] neg_lo:[1,0,0] neg_hi:[1,0,0]
	v_pk_fma_f32 v[66:67], v[16:17], v[52:53], v[66:67] op_sel:[0,1,0] op_sel_hi:[1,1,1] neg_lo:[1,0,0] neg_hi:[1,0,0]
	v_pk_fma_f32 v[66:67], v[18:19], v[54:55], v[66:67] op_sel_hi:[1,0,1] neg_lo:[1,0,0] neg_hi:[1,0,0]
	v_pk_fma_f32 v[66:67], v[20:21], v[54:55], v[66:67] op_sel:[0,1,0] op_sel_hi:[1,1,1] neg_lo:[1,0,0] neg_hi:[1,0,0]
	v_pk_fma_f32 v[66:67], v[22:23], v[56:57], v[66:67] op_sel_hi:[1,0,1] neg_lo:[1,0,0] neg_hi:[1,0,0]
	v_pk_fma_f32 v[66:67], v[24:25], v[56:57], v[66:67] op_sel:[0,1,0] op_sel_hi:[1,1,1] neg_lo:[1,0,0] neg_hi:[1,0,0]
	ds_read_u16 v26, v30 offset:5984
	ds_read_u16 v27, v30 offset:6256
	ds_read_b64 v[28:29], v31 offset:88
	ds_read_b128 v[2:5], v32 offset:5984
	ds_read_b128 v[6:9], v32 offset:6000
	ds_read_b128 v[10:13], v32 offset:6016
	ds_read_b128 v[14:17], v32 offset:6032
	ds_read_b128 v[18:21], v32 offset:6048
	ds_read_b128 v[22:25], v32 offset:6064
	s_waitcnt lgkmcnt(9)
	v_pk_fma_f32 v[66:67], v[120:121], v[58:59], v[66:67] op_sel_hi:[1,0,1] neg_lo:[1,0,0] neg_hi:[1,0,0]
	v_pk_fma_f32 v[66:67], v[122:123], v[58:59], v[66:67] op_sel:[0,1,0] op_sel_hi:[1,1,1] neg_lo:[1,0,0] neg_hi:[1,0,0]
	v_pk_fma_f32 v[66:67], v[124:125], v[60:61], v[66:67] op_sel_hi:[1,0,1] neg_lo:[1,0,0] neg_hi:[1,0,0]
	v_pk_fma_f32 v[66:67], v[126:127], v[60:61], v[66:67] op_sel:[0,1,0] op_sel_hi:[1,1,1] neg_lo:[1,0,0] neg_hi:[1,0,0]
	v_pk_fma_f32 v[66:67], v[128:129], v[62:63], v[66:67] op_sel_hi:[1,0,1] neg_lo:[1,0,0] neg_hi:[1,0,0]
	v_pk_fma_f32 v[66:67], v[130:131], v[62:63], v[66:67] op_sel:[0,1,0] op_sel_hi:[1,1,1] neg_lo:[1,0,0] neg_hi:[1,0,0]
	v_pk_fma_f32 v[66:67], v[132:133], v[64:65], v[66:67] op_sel_hi:[1,0,1] neg_lo:[1,0,0] neg_hi:[1,0,0]
	v_pk_fma_f32 v[66:67], v[134:135], v[64:65], v[66:67] op_sel:[0,1,0] op_sel_hi:[1,1,1] neg_lo:[1,0,0] neg_hi:[1,0,0]
	v_fma_f32 v67, -v145, v66, v67
	ds_read_b128 v[120:123], v32 offset:6080
	ds_read_b128 v[124:127], v32 offset:6096
	ds_read_b128 v[128:131], v32 offset:6112
	ds_read_b128 v[132:135], v32 offset:6128
	ds_read_b128 v[144:147], v32 offset:6144
	ds_read_b128 v[148:151], v32 offset:6160
	s_waitcnt lgkmcnt(6)
	v_lshlrev_b32_e32 v26, 16, v26
	v_lshlrev_b32_e32 v27, 16, v27
	v_pk_mul_f32 v[68:69], v[26:27], v[28:29]
	v_pk_fma_f32 v[68:69], v[2:3], v[46:47], v[68:69] op_sel_hi:[1,0,1] neg_lo:[1,0,0] neg_hi:[1,0,0]
	v_pk_fma_f32 v[68:69], v[4:5], v[46:47], v[68:69] op_sel:[0,1,0] op_sel_hi:[1,1,1] neg_lo:[1,0,0] neg_hi:[1,0,0]
	v_pk_fma_f32 v[68:69], v[6:7], v[48:49], v[68:69] op_sel_hi:[1,0,1] neg_lo:[1,0,0] neg_hi:[1,0,0]
	v_pk_fma_f32 v[68:69], v[8:9], v[48:49], v[68:69] op_sel:[0,1,0] op_sel_hi:[1,1,1] neg_lo:[1,0,0] neg_hi:[1,0,0]
	v_pk_fma_f32 v[68:69], v[10:11], v[50:51], v[68:69] op_sel_hi:[1,0,1] neg_lo:[1,0,0] neg_hi:[1,0,0]
	v_pk_fma_f32 v[68:69], v[12:13], v[50:51], v[68:69] op_sel:[0,1,0] op_sel_hi:[1,1,1] neg_lo:[1,0,0] neg_hi:[1,0,0]
	v_pk_fma_f32 v[68:69], v[14:15], v[52:53], v[68:69] op_sel_hi:[1,0,1] neg_lo:[1,0,0] neg_hi:[1,0,0]
	v_pk_fma_f32 v[68:69], v[16:17], v[52:53], v[68:69] op_sel:[0,1,0] op_sel_hi:[1,1,1] neg_lo:[1,0,0] neg_hi:[1,0,0]
	v_pk_fma_f32 v[68:69], v[18:19], v[54:55], v[68:69] op_sel_hi:[1,0,1] neg_lo:[1,0,0] neg_hi:[1,0,0]
	v_pk_fma_f32 v[68:69], v[20:21], v[54:55], v[68:69] op_sel:[0,1,0] op_sel_hi:[1,1,1] neg_lo:[1,0,0] neg_hi:[1,0,0]
	v_pk_fma_f32 v[68:69], v[22:23], v[56:57], v[68:69] op_sel_hi:[1,0,1] neg_lo:[1,0,0] neg_hi:[1,0,0]
	v_pk_fma_f32 v[68:69], v[24:25], v[56:57], v[68:69] op_sel:[0,1,0] op_sel_hi:[1,1,1] neg_lo:[1,0,0] neg_hi:[1,0,0]
	ds_read_u16 v26, v30 offset:6528
	ds_read_u16 v27, v30 offset:6800
	ds_read_b64 v[28:29], v31 offset:96
	ds_read_b128 v[2:5], v32 offset:6528
	ds_read_b128 v[6:9], v32 offset:6544
	ds_read_b128 v[10:13], v32 offset:6560
	ds_read_b128 v[14:17], v32 offset:6576
	ds_read_b128 v[18:21], v32 offset:6592
	ds_read_b128 v[22:25], v32 offset:6608
	s_waitcnt lgkmcnt(9)
	v_pk_fma_f32 v[68:69], v[120:121], v[58:59], v[68:69] op_sel_hi:[1,0,1] neg_lo:[1,0,0] neg_hi:[1,0,0]
	v_pk_fma_f32 v[68:69], v[122:123], v[58:59], v[68:69] op_sel:[0,1,0] op_sel_hi:[1,1,1] neg_lo:[1,0,0] neg_hi:[1,0,0]
	v_pk_fma_f32 v[68:69], v[124:125], v[60:61], v[68:69] op_sel_hi:[1,0,1] neg_lo:[1,0,0] neg_hi:[1,0,0]
	v_pk_fma_f32 v[68:69], v[126:127], v[60:61], v[68:69] op_sel:[0,1,0] op_sel_hi:[1,1,1] neg_lo:[1,0,0] neg_hi:[1,0,0]
	v_pk_fma_f32 v[68:69], v[128:129], v[62:63], v[68:69] op_sel_hi:[1,0,1] neg_lo:[1,0,0] neg_hi:[1,0,0]
	v_pk_fma_f32 v[68:69], v[130:131], v[62:63], v[68:69] op_sel:[0,1,0] op_sel_hi:[1,1,1] neg_lo:[1,0,0] neg_hi:[1,0,0]
	v_pk_fma_f32 v[68:69], v[132:133], v[64:65], v[68:69] op_sel_hi:[1,0,1] neg_lo:[1,0,0] neg_hi:[1,0,0]
	v_pk_fma_f32 v[68:69], v[134:135], v[64:65], v[68:69] op_sel:[0,1,0] op_sel_hi:[1,1,1] neg_lo:[1,0,0] neg_hi:[1,0,0]
	v_pk_fma_f32 v[68:69], v[144:145], v[66:67], v[68:69] op_sel_hi:[1,0,1] neg_lo:[1,0,0] neg_hi:[1,0,0]
	v_pk_fma_f32 v[68:69], v[146:147], v[66:67], v[68:69] op_sel:[0,1,0] op_sel_hi:[1,1,1] neg_lo:[1,0,0] neg_hi:[1,0,0]
	v_fma_f32 v69, -v149, v68, v69
	ds_read_b128 v[120:123], v32 offset:6624
	ds_read_b128 v[124:127], v32 offset:6640
	ds_read_b128 v[128:131], v32 offset:6656
	ds_read_b128 v[132:135], v32 offset:6672
	ds_read_b128 v[144:147], v32 offset:6688
	ds_read_b128 v[148:151], v32 offset:6704
	s_waitcnt lgkmcnt(6)
	v_lshlrev_b32_e32 v26, 16, v26
	v_lshlrev_b32_e32 v27, 16, v27
	v_pk_mul_f32 v[70:71], v[26:27], v[28:29]
	v_pk_fma_f32 v[70:71], v[2:3], v[46:47], v[70:71] op_sel_hi:[1,0,1] neg_lo:[1,0,0] neg_hi:[1,0,0]
	v_pk_fma_f32 v[70:71], v[4:5], v[46:47], v[70:71] op_sel:[0,1,0] op_sel_hi:[1,1,1] neg_lo:[1,0,0] neg_hi:[1,0,0]
	v_pk_fma_f32 v[70:71], v[6:7], v[48:49], v[70:71] op_sel_hi:[1,0,1] neg_lo:[1,0,0] neg_hi:[1,0,0]
	v_pk_fma_f32 v[70:71], v[8:9], v[48:49], v[70:71] op_sel:[0,1,0] op_sel_hi:[1,1,1] neg_lo:[1,0,0] neg_hi:[1,0,0]
	v_pk_fma_f32 v[70:71], v[10:11], v[50:51], v[70:71] op_sel_hi:[1,0,1] neg_lo:[1,0,0] neg_hi:[1,0,0]
	v_pk_fma_f32 v[70:71], v[12:13], v[50:51], v[70:71] op_sel:[0,1,0] op_sel_hi:[1,1,1] neg_lo:[1,0,0] neg_hi:[1,0,0]
	v_pk_fma_f32 v[70:71], v[14:15], v[52:53], v[70:71] op_sel_hi:[1,0,1] neg_lo:[1,0,0] neg_hi:[1,0,0]
	v_pk_fma_f32 v[70:71], v[16:17], v[52:53], v[70:71] op_sel:[0,1,0] op_sel_hi:[1,1,1] neg_lo:[1,0,0] neg_hi:[1,0,0]
	v_pk_fma_f32 v[70:71], v[18:19], v[54:55], v[70:71] op_sel_hi:[1,0,1] neg_lo:[1,0,0] neg_hi:[1,0,0]
	v_pk_fma_f32 v[70:71], v[20:21], v[54:55], v[70:71] op_sel:[0,1,0] op_sel_hi:[1,1,1] neg_lo:[1,0,0] neg_hi:[1,0,0]
	v_pk_fma_f32 v[70:71], v[22:23], v[56:57], v[70:71] op_sel_hi:[1,0,1] neg_lo:[1,0,0] neg_hi:[1,0,0]
	v_pk_fma_f32 v[70:71], v[24:25], v[56:57], v[70:71] op_sel:[0,1,0] op_sel_hi:[1,1,1] neg_lo:[1,0,0] neg_hi:[1,0,0]
	ds_read_b128 v[2:5], v32 offset:6720
	s_waitcnt lgkmcnt(1)
	v_pk_fma_f32 v[70:71], v[120:121], v[58:59], v[70:71] op_sel_hi:[1,0,1] neg_lo:[1,0,0] neg_hi:[1,0,0]
	v_pk_fma_f32 v[70:71], v[122:123], v[58:59], v[70:71] op_sel:[0,1,0] op_sel_hi:[1,1,1] neg_lo:[1,0,0] neg_hi:[1,0,0]
	v_pk_fma_f32 v[70:71], v[124:125], v[60:61], v[70:71] op_sel_hi:[1,0,1] neg_lo:[1,0,0] neg_hi:[1,0,0]
	v_pk_fma_f32 v[70:71], v[126:127], v[60:61], v[70:71] op_sel:[0,1,0] op_sel_hi:[1,1,1] neg_lo:[1,0,0] neg_hi:[1,0,0]
	v_pk_fma_f32 v[70:71], v[128:129], v[62:63], v[70:71] op_sel_hi:[1,0,1] neg_lo:[1,0,0] neg_hi:[1,0,0]
	v_pk_fma_f32 v[70:71], v[130:131], v[62:63], v[70:71] op_sel:[0,1,0] op_sel_hi:[1,1,1] neg_lo:[1,0,0] neg_hi:[1,0,0]
	v_pk_fma_f32 v[70:71], v[132:133], v[64:65], v[70:71] op_sel_hi:[1,0,1] neg_lo:[1,0,0] neg_hi:[1,0,0]
	v_pk_fma_f32 v[70:71], v[134:135], v[64:65], v[70:71] op_sel:[0,1,0] op_sel_hi:[1,1,1] neg_lo:[1,0,0] neg_hi:[1,0,0]
	v_pk_fma_f32 v[70:71], v[144:145], v[66:67], v[70:71] op_sel_hi:[1,0,1] neg_lo:[1,0,0] neg_hi:[1,0,0]
	v_pk_fma_f32 v[70:71], v[146:147], v[66:67], v[70:71] op_sel:[0,1,0] op_sel_hi:[1,1,1] neg_lo:[1,0,0] neg_hi:[1,0,0]
	v_pk_fma_f32 v[70:71], v[148:149], v[68:69], v[70:71] op_sel_hi:[1,0,1] neg_lo:[1,0,0] neg_hi:[1,0,0]
	v_pk_fma_f32 v[70:71], v[150:151], v[68:69], v[70:71] op_sel:[0,1,0] op_sel_hi:[1,1,1] neg_lo:[1,0,0] neg_hi:[1,0,0]
	ds_read_u16 v152, v30 offset:7072
	ds_read_u16 v153, v30 offset:7344
	ds_read_b64 v[154:155], v31 offset:104
	ds_read_b128 v[120:123], v32 offset:7072
	ds_read_b128 v[124:127], v32 offset:7088
	ds_read_b128 v[128:131], v32 offset:7104
	ds_read_b128 v[132:135], v32 offset:7120
	ds_read_b128 v[144:147], v32 offset:7136
	ds_read_b128 v[148:151], v32 offset:7152
	s_waitcnt lgkmcnt(9)
	v_fma_f32 v71, -v3, v70, v71
	ds_read_b128 v[2:5], v32 offset:7168
	ds_read_b128 v[6:9], v32 offset:7184
	ds_read_b128 v[10:13], v32 offset:7200
	ds_read_b128 v[14:17], v32 offset:7216
	ds_read_b128 v[18:21], v32 offset:7232
	ds_read_b128 v[22:25], v32 offset:7248
	s_waitcnt lgkmcnt(6)
	v_lshlrev_b32_e32 v152, 16, v152
	v_lshlrev_b32_e32 v153, 16, v153
	v_pk_mul_f32 v[72:73], v[152:153], v[154:155]
	v_pk_fma_f32 v[72:73], v[120:121], v[46:47], v[72:73] op_sel_hi:[1,0,1] neg_lo:[1,0,0] neg_hi:[1,0,0]
	v_pk_fma_f32 v[72:73], v[122:123], v[46:47], v[72:73] op_sel:[0,1,0] op_sel_hi:[1,1,1] neg_lo:[1,0,0] neg_hi:[1,0,0]
	v_pk_fma_f32 v[72:73], v[124:125], v[48:49], v[72:73] op_sel_hi:[1,0,1] neg_lo:[1,0,0] neg_hi:[1,0,0]
	v_pk_fma_f32 v[72:73], v[126:127], v[48:49], v[72:73] op_sel:[0,1,0] op_sel_hi:[1,1,1] neg_lo:[1,0,0] neg_hi:[1,0,0]
	v_pk_fma_f32 v[72:73], v[128:129], v[50:51], v[72:73] op_sel_hi:[1,0,1] neg_lo:[1,0,0] neg_hi:[1,0,0]
	v_pk_fma_f32 v[72:73], v[130:131], v[50:51], v[72:73] op_sel:[0,1,0] op_sel_hi:[1,1,1] neg_lo:[1,0,0] neg_hi:[1,0,0]
	v_pk_fma_f32 v[72:73], v[132:133], v[52:53], v[72:73] op_sel_hi:[1,0,1] neg_lo:[1,0,0] neg_hi:[1,0,0]
	v_pk_fma_f32 v[72:73], v[134:135], v[52:53], v[72:73] op_sel:[0,1,0] op_sel_hi:[1,1,1] neg_lo:[1,0,0] neg_hi:[1,0,0]
	v_pk_fma_f32 v[72:73], v[144:145], v[54:55], v[72:73] op_sel_hi:[1,0,1] neg_lo:[1,0,0] neg_hi:[1,0,0]
	v_pk_fma_f32 v[72:73], v[146:147], v[54:55], v[72:73] op_sel:[0,1,0] op_sel_hi:[1,1,1] neg_lo:[1,0,0] neg_hi:[1,0,0]
	v_pk_fma_f32 v[72:73], v[148:149], v[56:57], v[72:73] op_sel_hi:[1,0,1] neg_lo:[1,0,0] neg_hi:[1,0,0]
	v_pk_fma_f32 v[72:73], v[150:151], v[56:57], v[72:73] op_sel:[0,1,0] op_sel_hi:[1,1,1] neg_lo:[1,0,0] neg_hi:[1,0,0]
	ds_read_b128 v[120:123], v32 offset:7264
	ds_read_b128 v[124:127], v32 offset:7280
	s_waitcnt lgkmcnt(2)
	v_pk_fma_f32 v[72:73], v[2:3], v[58:59], v[72:73] op_sel_hi:[1,0,1] neg_lo:[1,0,0] neg_hi:[1,0,0]
	v_pk_fma_f32 v[72:73], v[4:5], v[58:59], v[72:73] op_sel:[0,1,0] op_sel_hi:[1,1,1] neg_lo:[1,0,0] neg_hi:[1,0,0]
	v_pk_fma_f32 v[72:73], v[6:7], v[60:61], v[72:73] op_sel_hi:[1,0,1] neg_lo:[1,0,0] neg_hi:[1,0,0]
	v_pk_fma_f32 v[72:73], v[8:9], v[60:61], v[72:73] op_sel:[0,1,0] op_sel_hi:[1,1,1] neg_lo:[1,0,0] neg_hi:[1,0,0]
	v_pk_fma_f32 v[72:73], v[10:11], v[62:63], v[72:73] op_sel_hi:[1,0,1] neg_lo:[1,0,0] neg_hi:[1,0,0]
	v_pk_fma_f32 v[72:73], v[12:13], v[62:63], v[72:73] op_sel:[0,1,0] op_sel_hi:[1,1,1] neg_lo:[1,0,0] neg_hi:[1,0,0]
	v_pk_fma_f32 v[72:73], v[14:15], v[64:65], v[72:73] op_sel_hi:[1,0,1] neg_lo:[1,0,0] neg_hi:[1,0,0]
	v_pk_fma_f32 v[72:73], v[16:17], v[64:65], v[72:73] op_sel:[0,1,0] op_sel_hi:[1,1,1] neg_lo:[1,0,0] neg_hi:[1,0,0]
	v_pk_fma_f32 v[72:73], v[18:19], v[66:67], v[72:73] op_sel_hi:[1,0,1] neg_lo:[1,0,0] neg_hi:[1,0,0]
	v_pk_fma_f32 v[72:73], v[20:21], v[66:67], v[72:73] op_sel:[0,1,0] op_sel_hi:[1,1,1] neg_lo:[1,0,0] neg_hi:[1,0,0]
	v_pk_fma_f32 v[72:73], v[22:23], v[68:69], v[72:73] op_sel_hi:[1,0,1] neg_lo:[1,0,0] neg_hi:[1,0,0]
	v_pk_fma_f32 v[72:73], v[24:25], v[68:69], v[72:73] op_sel:[0,1,0] op_sel_hi:[1,1,1] neg_lo:[1,0,0] neg_hi:[1,0,0]
	ds_read_u16 v26, v30 offset:7616
	ds_read_u16 v27, v30 offset:7888
	ds_read_b64 v[28:29], v31 offset:112
	ds_read_b128 v[2:5], v32 offset:7616
	ds_read_b128 v[6:9], v32 offset:7632
	ds_read_b128 v[10:13], v32 offset:7648
	ds_read_b128 v[14:17], v32 offset:7664
	ds_read_b128 v[18:21], v32 offset:7680
	ds_read_b128 v[22:25], v32 offset:7696
	s_waitcnt lgkmcnt(9)
	v_pk_fma_f32 v[72:73], v[120:121], v[70:71], v[72:73] op_sel_hi:[1,0,1] neg_lo:[1,0,0] neg_hi:[1,0,0]
	v_pk_fma_f32 v[72:73], v[122:123], v[70:71], v[72:73] op_sel:[0,1,0] op_sel_hi:[1,1,1] neg_lo:[1,0,0] neg_hi:[1,0,0]
	v_fma_f32 v73, -v125, v72, v73
	ds_read_b128 v[120:123], v32 offset:7712
	ds_read_b128 v[124:127], v32 offset:7728
	ds_read_b128 v[128:131], v32 offset:7744
	ds_read_b128 v[132:135], v32 offset:7760
	ds_read_b128 v[144:147], v32 offset:7776
	ds_read_b128 v[148:151], v32 offset:7792
	s_waitcnt lgkmcnt(6)
	v_lshlrev_b32_e32 v26, 16, v26
	v_lshlrev_b32_e32 v27, 16, v27
	v_pk_mul_f32 v[74:75], v[26:27], v[28:29]
	v_pk_fma_f32 v[74:75], v[2:3], v[46:47], v[74:75] op_sel_hi:[1,0,1] neg_lo:[1,0,0] neg_hi:[1,0,0]
	v_pk_fma_f32 v[74:75], v[4:5], v[46:47], v[74:75] op_sel:[0,1,0] op_sel_hi:[1,1,1] neg_lo:[1,0,0] neg_hi:[1,0,0]
	v_pk_fma_f32 v[74:75], v[6:7], v[48:49], v[74:75] op_sel_hi:[1,0,1] neg_lo:[1,0,0] neg_hi:[1,0,0]
	v_pk_fma_f32 v[74:75], v[8:9], v[48:49], v[74:75] op_sel:[0,1,0] op_sel_hi:[1,1,1] neg_lo:[1,0,0] neg_hi:[1,0,0]
	v_pk_fma_f32 v[74:75], v[10:11], v[50:51], v[74:75] op_sel_hi:[1,0,1] neg_lo:[1,0,0] neg_hi:[1,0,0]
	v_pk_fma_f32 v[74:75], v[12:13], v[50:51], v[74:75] op_sel:[0,1,0] op_sel_hi:[1,1,1] neg_lo:[1,0,0] neg_hi:[1,0,0]
	v_pk_fma_f32 v[74:75], v[14:15], v[52:53], v[74:75] op_sel_hi:[1,0,1] neg_lo:[1,0,0] neg_hi:[1,0,0]
	v_pk_fma_f32 v[74:75], v[16:17], v[52:53], v[74:75] op_sel:[0,1,0] op_sel_hi:[1,1,1] neg_lo:[1,0,0] neg_hi:[1,0,0]
	v_pk_fma_f32 v[74:75], v[18:19], v[54:55], v[74:75] op_sel_hi:[1,0,1] neg_lo:[1,0,0] neg_hi:[1,0,0]
	v_pk_fma_f32 v[74:75], v[20:21], v[54:55], v[74:75] op_sel:[0,1,0] op_sel_hi:[1,1,1] neg_lo:[1,0,0] neg_hi:[1,0,0]
	v_pk_fma_f32 v[74:75], v[22:23], v[56:57], v[74:75] op_sel_hi:[1,0,1] neg_lo:[1,0,0] neg_hi:[1,0,0]
	v_pk_fma_f32 v[74:75], v[24:25], v[56:57], v[74:75] op_sel:[0,1,0] op_sel_hi:[1,1,1] neg_lo:[1,0,0] neg_hi:[1,0,0]
	ds_read_b128 v[2:5], v32 offset:7808
	ds_read_b128 v[6:9], v32 offset:7824
	ds_read_b128 v[10:13], v32 offset:7840
	s_waitcnt lgkmcnt(3)
	v_pk_fma_f32 v[74:75], v[120:121], v[58:59], v[74:75] op_sel_hi:[1,0,1] neg_lo:[1,0,0] neg_hi:[1,0,0]
	v_pk_fma_f32 v[74:75], v[122:123], v[58:59], v[74:75] op_sel:[0,1,0] op_sel_hi:[1,1,1] neg_lo:[1,0,0] neg_hi:[1,0,0]
	v_pk_fma_f32 v[74:75], v[124:125], v[60:61], v[74:75] op_sel_hi:[1,0,1] neg_lo:[1,0,0] neg_hi:[1,0,0]
	v_pk_fma_f32 v[74:75], v[126:127], v[60:61], v[74:75] op_sel:[0,1,0] op_sel_hi:[1,1,1] neg_lo:[1,0,0] neg_hi:[1,0,0]
	v_pk_fma_f32 v[74:75], v[128:129], v[62:63], v[74:75] op_sel_hi:[1,0,1] neg_lo:[1,0,0] neg_hi:[1,0,0]
	v_pk_fma_f32 v[74:75], v[130:131], v[62:63], v[74:75] op_sel:[0,1,0] op_sel_hi:[1,1,1] neg_lo:[1,0,0] neg_hi:[1,0,0]
	v_pk_fma_f32 v[74:75], v[132:133], v[64:65], v[74:75] op_sel_hi:[1,0,1] neg_lo:[1,0,0] neg_hi:[1,0,0]
	v_pk_fma_f32 v[74:75], v[134:135], v[64:65], v[74:75] op_sel:[0,1,0] op_sel_hi:[1,1,1] neg_lo:[1,0,0] neg_hi:[1,0,0]
	v_pk_fma_f32 v[74:75], v[144:145], v[66:67], v[74:75] op_sel_hi:[1,0,1] neg_lo:[1,0,0] neg_hi:[1,0,0]
	v_pk_fma_f32 v[74:75], v[146:147], v[66:67], v[74:75] op_sel:[0,1,0] op_sel_hi:[1,1,1] neg_lo:[1,0,0] neg_hi:[1,0,0]
	v_pk_fma_f32 v[74:75], v[148:149], v[68:69], v[74:75] op_sel_hi:[1,0,1] neg_lo:[1,0,0] neg_hi:[1,0,0]
	v_pk_fma_f32 v[74:75], v[150:151], v[68:69], v[74:75] op_sel:[0,1,0] op_sel_hi:[1,1,1] neg_lo:[1,0,0] neg_hi:[1,0,0]
	ds_read_u16 v152, v30 offset:8160
	ds_read_u16 v153, v30 offset:8432
	ds_read_b64 v[154:155], v31 offset:120
	ds_read_b128 v[120:123], v32 offset:8160
	ds_read_b128 v[124:127], v32 offset:8176
	ds_read_b128 v[128:131], v32 offset:8192
	ds_read_b128 v[132:135], v32 offset:8208
	ds_read_b128 v[144:147], v32 offset:8224
	ds_read_b128 v[148:151], v32 offset:8240
	s_waitcnt lgkmcnt(9)
	v_pk_fma_f32 v[74:75], v[2:3], v[70:71], v[74:75] op_sel_hi:[1,0,1] neg_lo:[1,0,0] neg_hi:[1,0,0]
	v_pk_fma_f32 v[74:75], v[4:5], v[70:71], v[74:75] op_sel:[0,1,0] op_sel_hi:[1,1,1] neg_lo:[1,0,0] neg_hi:[1,0,0]
	v_pk_fma_f32 v[74:75], v[6:7], v[72:73], v[74:75] op_sel_hi:[1,0,1] neg_lo:[1,0,0] neg_hi:[1,0,0]
	v_pk_fma_f32 v[74:75], v[8:9], v[72:73], v[74:75] op_sel:[0,1,0] op_sel_hi:[1,1,1] neg_lo:[1,0,0] neg_hi:[1,0,0]
	v_fma_f32 v75, -v11, v74, v75
	ds_read_b128 v[2:5], v32 offset:8256
	ds_read_b128 v[6:9], v32 offset:8272
	ds_read_b128 v[10:13], v32 offset:8288
	ds_read_b128 v[14:17], v32 offset:8304
	ds_read_b128 v[18:21], v32 offset:8320
	ds_read_b128 v[22:25], v32 offset:8336
	s_waitcnt lgkmcnt(6)
	v_lshlrev_b32_e32 v152, 16, v152
	v_lshlrev_b32_e32 v153, 16, v153
	v_pk_mul_f32 v[76:77], v[152:153], v[154:155]
	v_pk_fma_f32 v[76:77], v[120:121], v[46:47], v[76:77] op_sel_hi:[1,0,1] neg_lo:[1,0,0] neg_hi:[1,0,0]
	v_pk_fma_f32 v[76:77], v[122:123], v[46:47], v[76:77] op_sel:[0,1,0] op_sel_hi:[1,1,1] neg_lo:[1,0,0] neg_hi:[1,0,0]
	v_pk_fma_f32 v[76:77], v[124:125], v[48:49], v[76:77] op_sel_hi:[1,0,1] neg_lo:[1,0,0] neg_hi:[1,0,0]
	v_pk_fma_f32 v[76:77], v[126:127], v[48:49], v[76:77] op_sel:[0,1,0] op_sel_hi:[1,1,1] neg_lo:[1,0,0] neg_hi:[1,0,0]
	v_pk_fma_f32 v[76:77], v[128:129], v[50:51], v[76:77] op_sel_hi:[1,0,1] neg_lo:[1,0,0] neg_hi:[1,0,0]
	v_pk_fma_f32 v[76:77], v[130:131], v[50:51], v[76:77] op_sel:[0,1,0] op_sel_hi:[1,1,1] neg_lo:[1,0,0] neg_hi:[1,0,0]
	v_pk_fma_f32 v[76:77], v[132:133], v[52:53], v[76:77] op_sel_hi:[1,0,1] neg_lo:[1,0,0] neg_hi:[1,0,0]
	v_pk_fma_f32 v[76:77], v[134:135], v[52:53], v[76:77] op_sel:[0,1,0] op_sel_hi:[1,1,1] neg_lo:[1,0,0] neg_hi:[1,0,0]
	v_pk_fma_f32 v[76:77], v[144:145], v[54:55], v[76:77] op_sel_hi:[1,0,1] neg_lo:[1,0,0] neg_hi:[1,0,0]
	v_pk_fma_f32 v[76:77], v[146:147], v[54:55], v[76:77] op_sel:[0,1,0] op_sel_hi:[1,1,1] neg_lo:[1,0,0] neg_hi:[1,0,0]
	v_pk_fma_f32 v[76:77], v[148:149], v[56:57], v[76:77] op_sel_hi:[1,0,1] neg_lo:[1,0,0] neg_hi:[1,0,0]
	v_pk_fma_f32 v[76:77], v[150:151], v[56:57], v[76:77] op_sel:[0,1,0] op_sel_hi:[1,1,1] neg_lo:[1,0,0] neg_hi:[1,0,0]
	ds_read_b128 v[120:123], v32 offset:8352
	ds_read_b128 v[124:127], v32 offset:8368
	ds_read_b128 v[128:131], v32 offset:8384
	ds_read_b128 v[132:135], v32 offset:8400
	s_waitcnt lgkmcnt(4)
	v_pk_fma_f32 v[76:77], v[2:3], v[58:59], v[76:77] op_sel_hi:[1,0,1] neg_lo:[1,0,0] neg_hi:[1,0,0]
	v_pk_fma_f32 v[76:77], v[4:5], v[58:59], v[76:77] op_sel:[0,1,0] op_sel_hi:[1,1,1] neg_lo:[1,0,0] neg_hi:[1,0,0]
	v_pk_fma_f32 v[76:77], v[6:7], v[60:61], v[76:77] op_sel_hi:[1,0,1] neg_lo:[1,0,0] neg_hi:[1,0,0]
	v_pk_fma_f32 v[76:77], v[8:9], v[60:61], v[76:77] op_sel:[0,1,0] op_sel_hi:[1,1,1] neg_lo:[1,0,0] neg_hi:[1,0,0]
	v_pk_fma_f32 v[76:77], v[10:11], v[62:63], v[76:77] op_sel_hi:[1,0,1] neg_lo:[1,0,0] neg_hi:[1,0,0]
	v_pk_fma_f32 v[76:77], v[12:13], v[62:63], v[76:77] op_sel:[0,1,0] op_sel_hi:[1,1,1] neg_lo:[1,0,0] neg_hi:[1,0,0]
	v_pk_fma_f32 v[76:77], v[14:15], v[64:65], v[76:77] op_sel_hi:[1,0,1] neg_lo:[1,0,0] neg_hi:[1,0,0]
	v_pk_fma_f32 v[76:77], v[16:17], v[64:65], v[76:77] op_sel:[0,1,0] op_sel_hi:[1,1,1] neg_lo:[1,0,0] neg_hi:[1,0,0]
	v_pk_fma_f32 v[76:77], v[18:19], v[66:67], v[76:77] op_sel_hi:[1,0,1] neg_lo:[1,0,0] neg_hi:[1,0,0]
	v_pk_fma_f32 v[76:77], v[20:21], v[66:67], v[76:77] op_sel:[0,1,0] op_sel_hi:[1,1,1] neg_lo:[1,0,0] neg_hi:[1,0,0]
	v_pk_fma_f32 v[76:77], v[22:23], v[68:69], v[76:77] op_sel_hi:[1,0,1] neg_lo:[1,0,0] neg_hi:[1,0,0]
	v_pk_fma_f32 v[76:77], v[24:25], v[68:69], v[76:77] op_sel:[0,1,0] op_sel_hi:[1,1,1] neg_lo:[1,0,0] neg_hi:[1,0,0]
	ds_read_u16 v26, v30 offset:8704
	ds_read_u16 v27, v30 offset:8976
	ds_read_b64 v[28:29], v31 offset:128
	ds_read_b128 v[2:5], v32 offset:8704
	ds_read_b128 v[6:9], v32 offset:8720
	ds_read_b128 v[10:13], v32 offset:8736
	ds_read_b128 v[14:17], v32 offset:8752
	ds_read_b128 v[18:21], v32 offset:8768
	ds_read_b128 v[22:25], v32 offset:8784
	s_waitcnt lgkmcnt(9)
	v_pk_fma_f32 v[76:77], v[120:121], v[70:71], v[76:77] op_sel_hi:[1,0,1] neg_lo:[1,0,0] neg_hi:[1,0,0]
	v_pk_fma_f32 v[76:77], v[122:123], v[70:71], v[76:77] op_sel:[0,1,0] op_sel_hi:[1,1,1] neg_lo:[1,0,0] neg_hi:[1,0,0]
	v_pk_fma_f32 v[76:77], v[124:125], v[72:73], v[76:77] op_sel_hi:[1,0,1] neg_lo:[1,0,0] neg_hi:[1,0,0]
	v_pk_fma_f32 v[76:77], v[126:127], v[72:73], v[76:77] op_sel:[0,1,0] op_sel_hi:[1,1,1] neg_lo:[1,0,0] neg_hi:[1,0,0]
	v_pk_fma_f32 v[76:77], v[128:129], v[74:75], v[76:77] op_sel_hi:[1,0,1] neg_lo:[1,0,0] neg_hi:[1,0,0]
	v_pk_fma_f32 v[76:77], v[130:131], v[74:75], v[76:77] op_sel:[0,1,0] op_sel_hi:[1,1,1] neg_lo:[1,0,0] neg_hi:[1,0,0]
	v_fma_f32 v77, -v133, v76, v77
	ds_read_b128 v[120:123], v32 offset:8800
	ds_read_b128 v[124:127], v32 offset:8816
	ds_read_b128 v[128:131], v32 offset:8832
	ds_read_b128 v[132:135], v32 offset:8848
	ds_read_b128 v[144:147], v32 offset:8864
	ds_read_b128 v[148:151], v32 offset:8880
	s_waitcnt lgkmcnt(6)
	v_lshlrev_b32_e32 v26, 16, v26
	v_lshlrev_b32_e32 v27, 16, v27
	v_pk_mul_f32 v[78:79], v[26:27], v[28:29]
	v_pk_fma_f32 v[78:79], v[2:3], v[46:47], v[78:79] op_sel_hi:[1,0,1] neg_lo:[1,0,0] neg_hi:[1,0,0]
	v_pk_fma_f32 v[78:79], v[4:5], v[46:47], v[78:79] op_sel:[0,1,0] op_sel_hi:[1,1,1] neg_lo:[1,0,0] neg_hi:[1,0,0]
	v_pk_fma_f32 v[78:79], v[6:7], v[48:49], v[78:79] op_sel_hi:[1,0,1] neg_lo:[1,0,0] neg_hi:[1,0,0]
	v_pk_fma_f32 v[78:79], v[8:9], v[48:49], v[78:79] op_sel:[0,1,0] op_sel_hi:[1,1,1] neg_lo:[1,0,0] neg_hi:[1,0,0]
	v_pk_fma_f32 v[78:79], v[10:11], v[50:51], v[78:79] op_sel_hi:[1,0,1] neg_lo:[1,0,0] neg_hi:[1,0,0]
	v_pk_fma_f32 v[78:79], v[12:13], v[50:51], v[78:79] op_sel:[0,1,0] op_sel_hi:[1,1,1] neg_lo:[1,0,0] neg_hi:[1,0,0]
	v_pk_fma_f32 v[78:79], v[14:15], v[52:53], v[78:79] op_sel_hi:[1,0,1] neg_lo:[1,0,0] neg_hi:[1,0,0]
	v_pk_fma_f32 v[78:79], v[16:17], v[52:53], v[78:79] op_sel:[0,1,0] op_sel_hi:[1,1,1] neg_lo:[1,0,0] neg_hi:[1,0,0]
	v_pk_fma_f32 v[78:79], v[18:19], v[54:55], v[78:79] op_sel_hi:[1,0,1] neg_lo:[1,0,0] neg_hi:[1,0,0]
	v_pk_fma_f32 v[78:79], v[20:21], v[54:55], v[78:79] op_sel:[0,1,0] op_sel_hi:[1,1,1] neg_lo:[1,0,0] neg_hi:[1,0,0]
	v_pk_fma_f32 v[78:79], v[22:23], v[56:57], v[78:79] op_sel_hi:[1,0,1] neg_lo:[1,0,0] neg_hi:[1,0,0]
	v_pk_fma_f32 v[78:79], v[24:25], v[56:57], v[78:79] op_sel:[0,1,0] op_sel_hi:[1,1,1] neg_lo:[1,0,0] neg_hi:[1,0,0]
	ds_read_b128 v[2:5], v32 offset:8896
	ds_read_b128 v[6:9], v32 offset:8912
	ds_read_b128 v[10:13], v32 offset:8928
	ds_read_b128 v[14:17], v32 offset:8944
	ds_read_b128 v[18:21], v32 offset:8960
	s_waitcnt lgkmcnt(5)
	v_pk_fma_f32 v[78:79], v[120:121], v[58:59], v[78:79] op_sel_hi:[1,0,1] neg_lo:[1,0,0] neg_hi:[1,0,0]
	v_pk_fma_f32 v[78:79], v[122:123], v[58:59], v[78:79] op_sel:[0,1,0] op_sel_hi:[1,1,1] neg_lo:[1,0,0] neg_hi:[1,0,0]
	v_pk_fma_f32 v[78:79], v[124:125], v[60:61], v[78:79] op_sel_hi:[1,0,1] neg_lo:[1,0,0] neg_hi:[1,0,0]
	v_pk_fma_f32 v[78:79], v[126:127], v[60:61], v[78:79] op_sel:[0,1,0] op_sel_hi:[1,1,1] neg_lo:[1,0,0] neg_hi:[1,0,0]
	v_pk_fma_f32 v[78:79], v[128:129], v[62:63], v[78:79] op_sel_hi:[1,0,1] neg_lo:[1,0,0] neg_hi:[1,0,0]
	v_pk_fma_f32 v[78:79], v[130:131], v[62:63], v[78:79] op_sel:[0,1,0] op_sel_hi:[1,1,1] neg_lo:[1,0,0] neg_hi:[1,0,0]
	v_pk_fma_f32 v[78:79], v[132:133], v[64:65], v[78:79] op_sel_hi:[1,0,1] neg_lo:[1,0,0] neg_hi:[1,0,0]
	v_pk_fma_f32 v[78:79], v[134:135], v[64:65], v[78:79] op_sel:[0,1,0] op_sel_hi:[1,1,1] neg_lo:[1,0,0] neg_hi:[1,0,0]
	v_pk_fma_f32 v[78:79], v[144:145], v[66:67], v[78:79] op_sel_hi:[1,0,1] neg_lo:[1,0,0] neg_hi:[1,0,0]
	v_pk_fma_f32 v[78:79], v[146:147], v[66:67], v[78:79] op_sel:[0,1,0] op_sel_hi:[1,1,1] neg_lo:[1,0,0] neg_hi:[1,0,0]
	v_pk_fma_f32 v[78:79], v[148:149], v[68:69], v[78:79] op_sel_hi:[1,0,1] neg_lo:[1,0,0] neg_hi:[1,0,0]
	v_pk_fma_f32 v[78:79], v[150:151], v[68:69], v[78:79] op_sel:[0,1,0] op_sel_hi:[1,1,1] neg_lo:[1,0,0] neg_hi:[1,0,0]
	ds_read_u16 v152, v30 offset:9248
	ds_read_u16 v153, v30 offset:9520
	ds_read_b64 v[154:155], v31 offset:136
	ds_read_b128 v[120:123], v32 offset:9248
	ds_read_b128 v[124:127], v32 offset:9264
	ds_read_b128 v[128:131], v32 offset:9280
	ds_read_b128 v[132:135], v32 offset:9296
	ds_read_b128 v[144:147], v32 offset:9312
	ds_read_b128 v[148:151], v32 offset:9328
	s_waitcnt lgkmcnt(9)
	v_pk_fma_f32 v[78:79], v[2:3], v[70:71], v[78:79] op_sel_hi:[1,0,1] neg_lo:[1,0,0] neg_hi:[1,0,0]
	v_pk_fma_f32 v[78:79], v[4:5], v[70:71], v[78:79] op_sel:[0,1,0] op_sel_hi:[1,1,1] neg_lo:[1,0,0] neg_hi:[1,0,0]
	v_pk_fma_f32 v[78:79], v[6:7], v[72:73], v[78:79] op_sel_hi:[1,0,1] neg_lo:[1,0,0] neg_hi:[1,0,0]
	v_pk_fma_f32 v[78:79], v[8:9], v[72:73], v[78:79] op_sel:[0,1,0] op_sel_hi:[1,1,1] neg_lo:[1,0,0] neg_hi:[1,0,0]
	v_pk_fma_f32 v[78:79], v[10:11], v[74:75], v[78:79] op_sel_hi:[1,0,1] neg_lo:[1,0,0] neg_hi:[1,0,0]
	v_pk_fma_f32 v[78:79], v[12:13], v[74:75], v[78:79] op_sel:[0,1,0] op_sel_hi:[1,1,1] neg_lo:[1,0,0] neg_hi:[1,0,0]
	v_pk_fma_f32 v[78:79], v[14:15], v[76:77], v[78:79] op_sel_hi:[1,0,1] neg_lo:[1,0,0] neg_hi:[1,0,0]
	v_pk_fma_f32 v[78:79], v[16:17], v[76:77], v[78:79] op_sel:[0,1,0] op_sel_hi:[1,1,1] neg_lo:[1,0,0] neg_hi:[1,0,0]
	v_fma_f32 v79, -v19, v78, v79
	ds_read_b128 v[2:5], v32 offset:9344
	ds_read_b128 v[6:9], v32 offset:9360
	ds_read_b128 v[10:13], v32 offset:9376
	ds_read_b128 v[14:17], v32 offset:9392
	ds_read_b128 v[18:21], v32 offset:9408
	ds_read_b128 v[22:25], v32 offset:9424
	s_waitcnt lgkmcnt(6)
	v_lshlrev_b32_e32 v152, 16, v152
	v_lshlrev_b32_e32 v153, 16, v153
	v_pk_mul_f32 v[80:81], v[152:153], v[154:155]
	v_pk_fma_f32 v[80:81], v[120:121], v[46:47], v[80:81] op_sel_hi:[1,0,1] neg_lo:[1,0,0] neg_hi:[1,0,0]
	v_pk_fma_f32 v[80:81], v[122:123], v[46:47], v[80:81] op_sel:[0,1,0] op_sel_hi:[1,1,1] neg_lo:[1,0,0] neg_hi:[1,0,0]
	v_pk_fma_f32 v[80:81], v[124:125], v[48:49], v[80:81] op_sel_hi:[1,0,1] neg_lo:[1,0,0] neg_hi:[1,0,0]
	v_pk_fma_f32 v[80:81], v[126:127], v[48:49], v[80:81] op_sel:[0,1,0] op_sel_hi:[1,1,1] neg_lo:[1,0,0] neg_hi:[1,0,0]
	v_pk_fma_f32 v[80:81], v[128:129], v[50:51], v[80:81] op_sel_hi:[1,0,1] neg_lo:[1,0,0] neg_hi:[1,0,0]
	v_pk_fma_f32 v[80:81], v[130:131], v[50:51], v[80:81] op_sel:[0,1,0] op_sel_hi:[1,1,1] neg_lo:[1,0,0] neg_hi:[1,0,0]
	v_pk_fma_f32 v[80:81], v[132:133], v[52:53], v[80:81] op_sel_hi:[1,0,1] neg_lo:[1,0,0] neg_hi:[1,0,0]
	v_pk_fma_f32 v[80:81], v[134:135], v[52:53], v[80:81] op_sel:[0,1,0] op_sel_hi:[1,1,1] neg_lo:[1,0,0] neg_hi:[1,0,0]
	v_pk_fma_f32 v[80:81], v[144:145], v[54:55], v[80:81] op_sel_hi:[1,0,1] neg_lo:[1,0,0] neg_hi:[1,0,0]
	v_pk_fma_f32 v[80:81], v[146:147], v[54:55], v[80:81] op_sel:[0,1,0] op_sel_hi:[1,1,1] neg_lo:[1,0,0] neg_hi:[1,0,0]
	v_pk_fma_f32 v[80:81], v[148:149], v[56:57], v[80:81] op_sel_hi:[1,0,1] neg_lo:[1,0,0] neg_hi:[1,0,0]
	v_pk_fma_f32 v[80:81], v[150:151], v[56:57], v[80:81] op_sel:[0,1,0] op_sel_hi:[1,1,1] neg_lo:[1,0,0] neg_hi:[1,0,0]
	ds_read_b128 v[120:123], v32 offset:9440
	ds_read_b128 v[124:127], v32 offset:9456
	ds_read_b128 v[128:131], v32 offset:9472
	ds_read_b128 v[132:135], v32 offset:9488
	ds_read_b128 v[144:147], v32 offset:9504
	ds_read_b128 v[148:151], v32 offset:9520
	s_waitcnt lgkmcnt(6)
	v_pk_fma_f32 v[80:81], v[2:3], v[58:59], v[80:81] op_sel_hi:[1,0,1] neg_lo:[1,0,0] neg_hi:[1,0,0]
	v_pk_fma_f32 v[80:81], v[4:5], v[58:59], v[80:81] op_sel:[0,1,0] op_sel_hi:[1,1,1] neg_lo:[1,0,0] neg_hi:[1,0,0]
	v_pk_fma_f32 v[80:81], v[6:7], v[60:61], v[80:81] op_sel_hi:[1,0,1] neg_lo:[1,0,0] neg_hi:[1,0,0]
	v_pk_fma_f32 v[80:81], v[8:9], v[60:61], v[80:81] op_sel:[0,1,0] op_sel_hi:[1,1,1] neg_lo:[1,0,0] neg_hi:[1,0,0]
	v_pk_fma_f32 v[80:81], v[10:11], v[62:63], v[80:81] op_sel_hi:[1,0,1] neg_lo:[1,0,0] neg_hi:[1,0,0]
	v_pk_fma_f32 v[80:81], v[12:13], v[62:63], v[80:81] op_sel:[0,1,0] op_sel_hi:[1,1,1] neg_lo:[1,0,0] neg_hi:[1,0,0]
	v_pk_fma_f32 v[80:81], v[14:15], v[64:65], v[80:81] op_sel_hi:[1,0,1] neg_lo:[1,0,0] neg_hi:[1,0,0]
	v_pk_fma_f32 v[80:81], v[16:17], v[64:65], v[80:81] op_sel:[0,1,0] op_sel_hi:[1,1,1] neg_lo:[1,0,0] neg_hi:[1,0,0]
	v_pk_fma_f32 v[80:81], v[18:19], v[66:67], v[80:81] op_sel_hi:[1,0,1] neg_lo:[1,0,0] neg_hi:[1,0,0]
	v_pk_fma_f32 v[80:81], v[20:21], v[66:67], v[80:81] op_sel:[0,1,0] op_sel_hi:[1,1,1] neg_lo:[1,0,0] neg_hi:[1,0,0]
	v_pk_fma_f32 v[80:81], v[22:23], v[68:69], v[80:81] op_sel_hi:[1,0,1] neg_lo:[1,0,0] neg_hi:[1,0,0]
	v_pk_fma_f32 v[80:81], v[24:25], v[68:69], v[80:81] op_sel:[0,1,0] op_sel_hi:[1,1,1] neg_lo:[1,0,0] neg_hi:[1,0,0]
	ds_read_u16 v26, v30 offset:9792
	ds_read_u16 v27, v30 offset:10064
	ds_read_b64 v[28:29], v31 offset:144
	ds_read_b128 v[2:5], v32 offset:9792
	ds_read_b128 v[6:9], v32 offset:9808
	ds_read_b128 v[10:13], v32 offset:9824
	ds_read_b128 v[14:17], v32 offset:9840
	ds_read_b128 v[18:21], v32 offset:9856
	ds_read_b128 v[22:25], v32 offset:9872
	s_waitcnt lgkmcnt(9)
	v_pk_fma_f32 v[80:81], v[120:121], v[70:71], v[80:81] op_sel_hi:[1,0,1] neg_lo:[1,0,0] neg_hi:[1,0,0]
	v_pk_fma_f32 v[80:81], v[122:123], v[70:71], v[80:81] op_sel:[0,1,0] op_sel_hi:[1,1,1] neg_lo:[1,0,0] neg_hi:[1,0,0]
	v_pk_fma_f32 v[80:81], v[124:125], v[72:73], v[80:81] op_sel_hi:[1,0,1] neg_lo:[1,0,0] neg_hi:[1,0,0]
	v_pk_fma_f32 v[80:81], v[126:127], v[72:73], v[80:81] op_sel:[0,1,0] op_sel_hi:[1,1,1] neg_lo:[1,0,0] neg_hi:[1,0,0]
	v_pk_fma_f32 v[80:81], v[128:129], v[74:75], v[80:81] op_sel_hi:[1,0,1] neg_lo:[1,0,0] neg_hi:[1,0,0]
	v_pk_fma_f32 v[80:81], v[130:131], v[74:75], v[80:81] op_sel:[0,1,0] op_sel_hi:[1,1,1] neg_lo:[1,0,0] neg_hi:[1,0,0]
	v_pk_fma_f32 v[80:81], v[132:133], v[76:77], v[80:81] op_sel_hi:[1,0,1] neg_lo:[1,0,0] neg_hi:[1,0,0]
	v_pk_fma_f32 v[80:81], v[134:135], v[76:77], v[80:81] op_sel:[0,1,0] op_sel_hi:[1,1,1] neg_lo:[1,0,0] neg_hi:[1,0,0]
	v_pk_fma_f32 v[80:81], v[144:145], v[78:79], v[80:81] op_sel_hi:[1,0,1] neg_lo:[1,0,0] neg_hi:[1,0,0]
	v_pk_fma_f32 v[80:81], v[146:147], v[78:79], v[80:81] op_sel:[0,1,0] op_sel_hi:[1,1,1] neg_lo:[1,0,0] neg_hi:[1,0,0]
	v_fma_f32 v81, -v149, v80, v81
	ds_read_b128 v[120:123], v32 offset:9888
	ds_read_b128 v[124:127], v32 offset:9904
	ds_read_b128 v[128:131], v32 offset:9920
	ds_read_b128 v[132:135], v32 offset:9936
	ds_read_b128 v[144:147], v32 offset:9952
	ds_read_b128 v[148:151], v32 offset:9968
	s_waitcnt lgkmcnt(6)
	v_lshlrev_b32_e32 v26, 16, v26
	v_lshlrev_b32_e32 v27, 16, v27
	v_pk_mul_f32 v[82:83], v[26:27], v[28:29]
	v_pk_fma_f32 v[82:83], v[2:3], v[46:47], v[82:83] op_sel_hi:[1,0,1] neg_lo:[1,0,0] neg_hi:[1,0,0]
	v_pk_fma_f32 v[82:83], v[4:5], v[46:47], v[82:83] op_sel:[0,1,0] op_sel_hi:[1,1,1] neg_lo:[1,0,0] neg_hi:[1,0,0]
	v_pk_fma_f32 v[82:83], v[6:7], v[48:49], v[82:83] op_sel_hi:[1,0,1] neg_lo:[1,0,0] neg_hi:[1,0,0]
	v_pk_fma_f32 v[82:83], v[8:9], v[48:49], v[82:83] op_sel:[0,1,0] op_sel_hi:[1,1,1] neg_lo:[1,0,0] neg_hi:[1,0,0]
	v_pk_fma_f32 v[82:83], v[10:11], v[50:51], v[82:83] op_sel_hi:[1,0,1] neg_lo:[1,0,0] neg_hi:[1,0,0]
	v_pk_fma_f32 v[82:83], v[12:13], v[50:51], v[82:83] op_sel:[0,1,0] op_sel_hi:[1,1,1] neg_lo:[1,0,0] neg_hi:[1,0,0]
	v_pk_fma_f32 v[82:83], v[14:15], v[52:53], v[82:83] op_sel_hi:[1,0,1] neg_lo:[1,0,0] neg_hi:[1,0,0]
	v_pk_fma_f32 v[82:83], v[16:17], v[52:53], v[82:83] op_sel:[0,1,0] op_sel_hi:[1,1,1] neg_lo:[1,0,0] neg_hi:[1,0,0]
	v_pk_fma_f32 v[82:83], v[18:19], v[54:55], v[82:83] op_sel_hi:[1,0,1] neg_lo:[1,0,0] neg_hi:[1,0,0]
	v_pk_fma_f32 v[82:83], v[20:21], v[54:55], v[82:83] op_sel:[0,1,0] op_sel_hi:[1,1,1] neg_lo:[1,0,0] neg_hi:[1,0,0]
	v_pk_fma_f32 v[82:83], v[22:23], v[56:57], v[82:83] op_sel_hi:[1,0,1] neg_lo:[1,0,0] neg_hi:[1,0,0]
	v_pk_fma_f32 v[82:83], v[24:25], v[56:57], v[82:83] op_sel:[0,1,0] op_sel_hi:[1,1,1] neg_lo:[1,0,0] neg_hi:[1,0,0]
	ds_read_b128 v[2:5], v32 offset:9984
	ds_read_b128 v[6:9], v32 offset:10000
	ds_read_b128 v[10:13], v32 offset:10016
	ds_read_b128 v[14:17], v32 offset:10032
	ds_read_b128 v[18:21], v32 offset:10048
	ds_read_b128 v[22:25], v32 offset:10064
	s_waitcnt lgkmcnt(6)
	v_pk_fma_f32 v[82:83], v[120:121], v[58:59], v[82:83] op_sel_hi:[1,0,1] neg_lo:[1,0,0] neg_hi:[1,0,0]
	v_pk_fma_f32 v[82:83], v[122:123], v[58:59], v[82:83] op_sel:[0,1,0] op_sel_hi:[1,1,1] neg_lo:[1,0,0] neg_hi:[1,0,0]
	v_pk_fma_f32 v[82:83], v[124:125], v[60:61], v[82:83] op_sel_hi:[1,0,1] neg_lo:[1,0,0] neg_hi:[1,0,0]
	v_pk_fma_f32 v[82:83], v[126:127], v[60:61], v[82:83] op_sel:[0,1,0] op_sel_hi:[1,1,1] neg_lo:[1,0,0] neg_hi:[1,0,0]
	v_pk_fma_f32 v[82:83], v[128:129], v[62:63], v[82:83] op_sel_hi:[1,0,1] neg_lo:[1,0,0] neg_hi:[1,0,0]
	v_pk_fma_f32 v[82:83], v[130:131], v[62:63], v[82:83] op_sel:[0,1,0] op_sel_hi:[1,1,1] neg_lo:[1,0,0] neg_hi:[1,0,0]
	v_pk_fma_f32 v[82:83], v[132:133], v[64:65], v[82:83] op_sel_hi:[1,0,1] neg_lo:[1,0,0] neg_hi:[1,0,0]
	v_pk_fma_f32 v[82:83], v[134:135], v[64:65], v[82:83] op_sel:[0,1,0] op_sel_hi:[1,1,1] neg_lo:[1,0,0] neg_hi:[1,0,0]
	v_pk_fma_f32 v[82:83], v[144:145], v[66:67], v[82:83] op_sel_hi:[1,0,1] neg_lo:[1,0,0] neg_hi:[1,0,0]
	v_pk_fma_f32 v[82:83], v[146:147], v[66:67], v[82:83] op_sel:[0,1,0] op_sel_hi:[1,1,1] neg_lo:[1,0,0] neg_hi:[1,0,0]
	v_pk_fma_f32 v[82:83], v[148:149], v[68:69], v[82:83] op_sel_hi:[1,0,1] neg_lo:[1,0,0] neg_hi:[1,0,0]
	v_pk_fma_f32 v[82:83], v[150:151], v[68:69], v[82:83] op_sel:[0,1,0] op_sel_hi:[1,1,1] neg_lo:[1,0,0] neg_hi:[1,0,0]
	ds_read_b128 v[120:123], v32 offset:10080
	s_waitcnt lgkmcnt(1)
	v_pk_fma_f32 v[82:83], v[2:3], v[70:71], v[82:83] op_sel_hi:[1,0,1] neg_lo:[1,0,0] neg_hi:[1,0,0]
	v_pk_fma_f32 v[82:83], v[4:5], v[70:71], v[82:83] op_sel:[0,1,0] op_sel_hi:[1,1,1] neg_lo:[1,0,0] neg_hi:[1,0,0]
	v_pk_fma_f32 v[82:83], v[6:7], v[72:73], v[82:83] op_sel_hi:[1,0,1] neg_lo:[1,0,0] neg_hi:[1,0,0]
	v_pk_fma_f32 v[82:83], v[8:9], v[72:73], v[82:83] op_sel:[0,1,0] op_sel_hi:[1,1,1] neg_lo:[1,0,0] neg_hi:[1,0,0]
	v_pk_fma_f32 v[82:83], v[10:11], v[74:75], v[82:83] op_sel_hi:[1,0,1] neg_lo:[1,0,0] neg_hi:[1,0,0]
	v_pk_fma_f32 v[82:83], v[12:13], v[74:75], v[82:83] op_sel:[0,1,0] op_sel_hi:[1,1,1] neg_lo:[1,0,0] neg_hi:[1,0,0]
	v_pk_fma_f32 v[82:83], v[14:15], v[76:77], v[82:83] op_sel_hi:[1,0,1] neg_lo:[1,0,0] neg_hi:[1,0,0]
	v_pk_fma_f32 v[82:83], v[16:17], v[76:77], v[82:83] op_sel:[0,1,0] op_sel_hi:[1,1,1] neg_lo:[1,0,0] neg_hi:[1,0,0]
	v_pk_fma_f32 v[82:83], v[18:19], v[78:79], v[82:83] op_sel_hi:[1,0,1] neg_lo:[1,0,0] neg_hi:[1,0,0]
	v_pk_fma_f32 v[82:83], v[20:21], v[78:79], v[82:83] op_sel:[0,1,0] op_sel_hi:[1,1,1] neg_lo:[1,0,0] neg_hi:[1,0,0]
	v_pk_fma_f32 v[82:83], v[22:23], v[80:81], v[82:83] op_sel_hi:[1,0,1] neg_lo:[1,0,0] neg_hi:[1,0,0]
	v_pk_fma_f32 v[82:83], v[24:25], v[80:81], v[82:83] op_sel:[0,1,0] op_sel_hi:[1,1,1] neg_lo:[1,0,0] neg_hi:[1,0,0]
	ds_read_u16 v26, v30 offset:10336
	ds_read_u16 v27, v30 offset:10608
	ds_read_b64 v[28:29], v31 offset:152
	ds_read_b128 v[2:5], v32 offset:10336
	ds_read_b128 v[6:9], v32 offset:10352
	ds_read_b128 v[10:13], v32 offset:10368
	ds_read_b128 v[14:17], v32 offset:10384
	ds_read_b128 v[18:21], v32 offset:10400
	ds_read_b128 v[22:25], v32 offset:10416
	s_waitcnt lgkmcnt(9)
	v_fma_f32 v83, -v121, v82, v83
	ds_read_b128 v[120:123], v32 offset:10432
	ds_read_b128 v[124:127], v32 offset:10448
	ds_read_b128 v[128:131], v32 offset:10464
	ds_read_b128 v[132:135], v32 offset:10480
	ds_read_b128 v[144:147], v32 offset:10496
	ds_read_b128 v[148:151], v32 offset:10512
	s_waitcnt lgkmcnt(6)
	v_lshlrev_b32_e32 v26, 16, v26
	v_lshlrev_b32_e32 v27, 16, v27
	v_pk_mul_f32 v[84:85], v[26:27], v[28:29]
	v_pk_fma_f32 v[84:85], v[2:3], v[46:47], v[84:85] op_sel_hi:[1,0,1] neg_lo:[1,0,0] neg_hi:[1,0,0]
	v_pk_fma_f32 v[84:85], v[4:5], v[46:47], v[84:85] op_sel:[0,1,0] op_sel_hi:[1,1,1] neg_lo:[1,0,0] neg_hi:[1,0,0]
	v_pk_fma_f32 v[84:85], v[6:7], v[48:49], v[84:85] op_sel_hi:[1,0,1] neg_lo:[1,0,0] neg_hi:[1,0,0]
	v_pk_fma_f32 v[84:85], v[8:9], v[48:49], v[84:85] op_sel:[0,1,0] op_sel_hi:[1,1,1] neg_lo:[1,0,0] neg_hi:[1,0,0]
	v_pk_fma_f32 v[84:85], v[10:11], v[50:51], v[84:85] op_sel_hi:[1,0,1] neg_lo:[1,0,0] neg_hi:[1,0,0]
	v_pk_fma_f32 v[84:85], v[12:13], v[50:51], v[84:85] op_sel:[0,1,0] op_sel_hi:[1,1,1] neg_lo:[1,0,0] neg_hi:[1,0,0]
	v_pk_fma_f32 v[84:85], v[14:15], v[52:53], v[84:85] op_sel_hi:[1,0,1] neg_lo:[1,0,0] neg_hi:[1,0,0]
	v_pk_fma_f32 v[84:85], v[16:17], v[52:53], v[84:85] op_sel:[0,1,0] op_sel_hi:[1,1,1] neg_lo:[1,0,0] neg_hi:[1,0,0]
	v_pk_fma_f32 v[84:85], v[18:19], v[54:55], v[84:85] op_sel_hi:[1,0,1] neg_lo:[1,0,0] neg_hi:[1,0,0]
	v_pk_fma_f32 v[84:85], v[20:21], v[54:55], v[84:85] op_sel:[0,1,0] op_sel_hi:[1,1,1] neg_lo:[1,0,0] neg_hi:[1,0,0]
	v_pk_fma_f32 v[84:85], v[22:23], v[56:57], v[84:85] op_sel_hi:[1,0,1] neg_lo:[1,0,0] neg_hi:[1,0,0]
	v_pk_fma_f32 v[84:85], v[24:25], v[56:57], v[84:85] op_sel:[0,1,0] op_sel_hi:[1,1,1] neg_lo:[1,0,0] neg_hi:[1,0,0]
	ds_read_b128 v[2:5], v32 offset:10528
	ds_read_b128 v[6:9], v32 offset:10544
	ds_read_b128 v[10:13], v32 offset:10560
	ds_read_b128 v[14:17], v32 offset:10576
	ds_read_b128 v[18:21], v32 offset:10592
	ds_read_b128 v[22:25], v32 offset:10608
	s_waitcnt lgkmcnt(6)
	v_pk_fma_f32 v[84:85], v[120:121], v[58:59], v[84:85] op_sel_hi:[1,0,1] neg_lo:[1,0,0] neg_hi:[1,0,0]
	v_pk_fma_f32 v[84:85], v[122:123], v[58:59], v[84:85] op_sel:[0,1,0] op_sel_hi:[1,1,1] neg_lo:[1,0,0] neg_hi:[1,0,0]
	v_pk_fma_f32 v[84:85], v[124:125], v[60:61], v[84:85] op_sel_hi:[1,0,1] neg_lo:[1,0,0] neg_hi:[1,0,0]
	v_pk_fma_f32 v[84:85], v[126:127], v[60:61], v[84:85] op_sel:[0,1,0] op_sel_hi:[1,1,1] neg_lo:[1,0,0] neg_hi:[1,0,0]
	v_pk_fma_f32 v[84:85], v[128:129], v[62:63], v[84:85] op_sel_hi:[1,0,1] neg_lo:[1,0,0] neg_hi:[1,0,0]
	v_pk_fma_f32 v[84:85], v[130:131], v[62:63], v[84:85] op_sel:[0,1,0] op_sel_hi:[1,1,1] neg_lo:[1,0,0] neg_hi:[1,0,0]
	v_pk_fma_f32 v[84:85], v[132:133], v[64:65], v[84:85] op_sel_hi:[1,0,1] neg_lo:[1,0,0] neg_hi:[1,0,0]
	v_pk_fma_f32 v[84:85], v[134:135], v[64:65], v[84:85] op_sel:[0,1,0] op_sel_hi:[1,1,1] neg_lo:[1,0,0] neg_hi:[1,0,0]
	v_pk_fma_f32 v[84:85], v[144:145], v[66:67], v[84:85] op_sel_hi:[1,0,1] neg_lo:[1,0,0] neg_hi:[1,0,0]
	v_pk_fma_f32 v[84:85], v[146:147], v[66:67], v[84:85] op_sel:[0,1,0] op_sel_hi:[1,1,1] neg_lo:[1,0,0] neg_hi:[1,0,0]
	v_pk_fma_f32 v[84:85], v[148:149], v[68:69], v[84:85] op_sel_hi:[1,0,1] neg_lo:[1,0,0] neg_hi:[1,0,0]
	v_pk_fma_f32 v[84:85], v[150:151], v[68:69], v[84:85] op_sel:[0,1,0] op_sel_hi:[1,1,1] neg_lo:[1,0,0] neg_hi:[1,0,0]
	ds_read_b128 v[120:123], v32 offset:10624
	ds_read_b128 v[124:127], v32 offset:10640
	s_waitcnt lgkmcnt(2)
	v_pk_fma_f32 v[84:85], v[2:3], v[70:71], v[84:85] op_sel_hi:[1,0,1] neg_lo:[1,0,0] neg_hi:[1,0,0]
	v_pk_fma_f32 v[84:85], v[4:5], v[70:71], v[84:85] op_sel:[0,1,0] op_sel_hi:[1,1,1] neg_lo:[1,0,0] neg_hi:[1,0,0]
	v_pk_fma_f32 v[84:85], v[6:7], v[72:73], v[84:85] op_sel_hi:[1,0,1] neg_lo:[1,0,0] neg_hi:[1,0,0]
	v_pk_fma_f32 v[84:85], v[8:9], v[72:73], v[84:85] op_sel:[0,1,0] op_sel_hi:[1,1,1] neg_lo:[1,0,0] neg_hi:[1,0,0]
	v_pk_fma_f32 v[84:85], v[10:11], v[74:75], v[84:85] op_sel_hi:[1,0,1] neg_lo:[1,0,0] neg_hi:[1,0,0]
	v_pk_fma_f32 v[84:85], v[12:13], v[74:75], v[84:85] op_sel:[0,1,0] op_sel_hi:[1,1,1] neg_lo:[1,0,0] neg_hi:[1,0,0]
	v_pk_fma_f32 v[84:85], v[14:15], v[76:77], v[84:85] op_sel_hi:[1,0,1] neg_lo:[1,0,0] neg_hi:[1,0,0]
	v_pk_fma_f32 v[84:85], v[16:17], v[76:77], v[84:85] op_sel:[0,1,0] op_sel_hi:[1,1,1] neg_lo:[1,0,0] neg_hi:[1,0,0]
	v_pk_fma_f32 v[84:85], v[18:19], v[78:79], v[84:85] op_sel_hi:[1,0,1] neg_lo:[1,0,0] neg_hi:[1,0,0]
	v_pk_fma_f32 v[84:85], v[20:21], v[78:79], v[84:85] op_sel:[0,1,0] op_sel_hi:[1,1,1] neg_lo:[1,0,0] neg_hi:[1,0,0]
	v_pk_fma_f32 v[84:85], v[22:23], v[80:81], v[84:85] op_sel_hi:[1,0,1] neg_lo:[1,0,0] neg_hi:[1,0,0]
	v_pk_fma_f32 v[84:85], v[24:25], v[80:81], v[84:85] op_sel:[0,1,0] op_sel_hi:[1,1,1] neg_lo:[1,0,0] neg_hi:[1,0,0]
	ds_read_u16 v26, v30 offset:10880
	ds_read_u16 v27, v30 offset:11152
	ds_read_b64 v[28:29], v31 offset:160
	ds_read_b128 v[2:5], v32 offset:10880
	ds_read_b128 v[6:9], v32 offset:10896
	ds_read_b128 v[10:13], v32 offset:10912
	ds_read_b128 v[14:17], v32 offset:10928
	ds_read_b128 v[18:21], v32 offset:10944
	ds_read_b128 v[22:25], v32 offset:10960
	s_waitcnt lgkmcnt(9)
	v_pk_fma_f32 v[84:85], v[120:121], v[82:83], v[84:85] op_sel_hi:[1,0,1] neg_lo:[1,0,0] neg_hi:[1,0,0]
	v_pk_fma_f32 v[84:85], v[122:123], v[82:83], v[84:85] op_sel:[0,1,0] op_sel_hi:[1,1,1] neg_lo:[1,0,0] neg_hi:[1,0,0]
	v_fma_f32 v85, -v125, v84, v85
	ds_read_b128 v[120:123], v32 offset:10976
	ds_read_b128 v[124:127], v32 offset:10992
	ds_read_b128 v[128:131], v32 offset:11008
	ds_read_b128 v[132:135], v32 offset:11024
	ds_read_b128 v[144:147], v32 offset:11040
	ds_read_b128 v[148:151], v32 offset:11056
	s_waitcnt lgkmcnt(6)
	v_lshlrev_b32_e32 v26, 16, v26
	v_lshlrev_b32_e32 v27, 16, v27
	v_pk_mul_f32 v[86:87], v[26:27], v[28:29]
	v_pk_fma_f32 v[86:87], v[2:3], v[46:47], v[86:87] op_sel_hi:[1,0,1] neg_lo:[1,0,0] neg_hi:[1,0,0]
	v_pk_fma_f32 v[86:87], v[4:5], v[46:47], v[86:87] op_sel:[0,1,0] op_sel_hi:[1,1,1] neg_lo:[1,0,0] neg_hi:[1,0,0]
	v_pk_fma_f32 v[86:87], v[6:7], v[48:49], v[86:87] op_sel_hi:[1,0,1] neg_lo:[1,0,0] neg_hi:[1,0,0]
	v_pk_fma_f32 v[86:87], v[8:9], v[48:49], v[86:87] op_sel:[0,1,0] op_sel_hi:[1,1,1] neg_lo:[1,0,0] neg_hi:[1,0,0]
	v_pk_fma_f32 v[86:87], v[10:11], v[50:51], v[86:87] op_sel_hi:[1,0,1] neg_lo:[1,0,0] neg_hi:[1,0,0]
	v_pk_fma_f32 v[86:87], v[12:13], v[50:51], v[86:87] op_sel:[0,1,0] op_sel_hi:[1,1,1] neg_lo:[1,0,0] neg_hi:[1,0,0]
	v_pk_fma_f32 v[86:87], v[14:15], v[52:53], v[86:87] op_sel_hi:[1,0,1] neg_lo:[1,0,0] neg_hi:[1,0,0]
	v_pk_fma_f32 v[86:87], v[16:17], v[52:53], v[86:87] op_sel:[0,1,0] op_sel_hi:[1,1,1] neg_lo:[1,0,0] neg_hi:[1,0,0]
	v_pk_fma_f32 v[86:87], v[18:19], v[54:55], v[86:87] op_sel_hi:[1,0,1] neg_lo:[1,0,0] neg_hi:[1,0,0]
	v_pk_fma_f32 v[86:87], v[20:21], v[54:55], v[86:87] op_sel:[0,1,0] op_sel_hi:[1,1,1] neg_lo:[1,0,0] neg_hi:[1,0,0]
	v_pk_fma_f32 v[86:87], v[22:23], v[56:57], v[86:87] op_sel_hi:[1,0,1] neg_lo:[1,0,0] neg_hi:[1,0,0]
	v_pk_fma_f32 v[86:87], v[24:25], v[56:57], v[86:87] op_sel:[0,1,0] op_sel_hi:[1,1,1] neg_lo:[1,0,0] neg_hi:[1,0,0]
	ds_read_b128 v[2:5], v32 offset:11072
	ds_read_b128 v[6:9], v32 offset:11088
	ds_read_b128 v[10:13], v32 offset:11104
	ds_read_b128 v[14:17], v32 offset:11120
	ds_read_b128 v[18:21], v32 offset:11136
	ds_read_b128 v[22:25], v32 offset:11152
	s_waitcnt lgkmcnt(6)
	v_pk_fma_f32 v[86:87], v[120:121], v[58:59], v[86:87] op_sel_hi:[1,0,1] neg_lo:[1,0,0] neg_hi:[1,0,0]
	v_pk_fma_f32 v[86:87], v[122:123], v[58:59], v[86:87] op_sel:[0,1,0] op_sel_hi:[1,1,1] neg_lo:[1,0,0] neg_hi:[1,0,0]
	v_pk_fma_f32 v[86:87], v[124:125], v[60:61], v[86:87] op_sel_hi:[1,0,1] neg_lo:[1,0,0] neg_hi:[1,0,0]
	v_pk_fma_f32 v[86:87], v[126:127], v[60:61], v[86:87] op_sel:[0,1,0] op_sel_hi:[1,1,1] neg_lo:[1,0,0] neg_hi:[1,0,0]
	v_pk_fma_f32 v[86:87], v[128:129], v[62:63], v[86:87] op_sel_hi:[1,0,1] neg_lo:[1,0,0] neg_hi:[1,0,0]
	v_pk_fma_f32 v[86:87], v[130:131], v[62:63], v[86:87] op_sel:[0,1,0] op_sel_hi:[1,1,1] neg_lo:[1,0,0] neg_hi:[1,0,0]
	v_pk_fma_f32 v[86:87], v[132:133], v[64:65], v[86:87] op_sel_hi:[1,0,1] neg_lo:[1,0,0] neg_hi:[1,0,0]
	v_pk_fma_f32 v[86:87], v[134:135], v[64:65], v[86:87] op_sel:[0,1,0] op_sel_hi:[1,1,1] neg_lo:[1,0,0] neg_hi:[1,0,0]
	v_pk_fma_f32 v[86:87], v[144:145], v[66:67], v[86:87] op_sel_hi:[1,0,1] neg_lo:[1,0,0] neg_hi:[1,0,0]
	v_pk_fma_f32 v[86:87], v[146:147], v[66:67], v[86:87] op_sel:[0,1,0] op_sel_hi:[1,1,1] neg_lo:[1,0,0] neg_hi:[1,0,0]
	v_pk_fma_f32 v[86:87], v[148:149], v[68:69], v[86:87] op_sel_hi:[1,0,1] neg_lo:[1,0,0] neg_hi:[1,0,0]
	v_pk_fma_f32 v[86:87], v[150:151], v[68:69], v[86:87] op_sel:[0,1,0] op_sel_hi:[1,1,1] neg_lo:[1,0,0] neg_hi:[1,0,0]
	ds_read_b128 v[120:123], v32 offset:11168
	ds_read_b128 v[124:127], v32 offset:11184
	ds_read_b128 v[128:131], v32 offset:11200
	s_waitcnt lgkmcnt(3)
	v_pk_fma_f32 v[86:87], v[2:3], v[70:71], v[86:87] op_sel_hi:[1,0,1] neg_lo:[1,0,0] neg_hi:[1,0,0]
	v_pk_fma_f32 v[86:87], v[4:5], v[70:71], v[86:87] op_sel:[0,1,0] op_sel_hi:[1,1,1] neg_lo:[1,0,0] neg_hi:[1,0,0]
	v_pk_fma_f32 v[86:87], v[6:7], v[72:73], v[86:87] op_sel_hi:[1,0,1] neg_lo:[1,0,0] neg_hi:[1,0,0]
	v_pk_fma_f32 v[86:87], v[8:9], v[72:73], v[86:87] op_sel:[0,1,0] op_sel_hi:[1,1,1] neg_lo:[1,0,0] neg_hi:[1,0,0]
	v_pk_fma_f32 v[86:87], v[10:11], v[74:75], v[86:87] op_sel_hi:[1,0,1] neg_lo:[1,0,0] neg_hi:[1,0,0]
	v_pk_fma_f32 v[86:87], v[12:13], v[74:75], v[86:87] op_sel:[0,1,0] op_sel_hi:[1,1,1] neg_lo:[1,0,0] neg_hi:[1,0,0]
	v_pk_fma_f32 v[86:87], v[14:15], v[76:77], v[86:87] op_sel_hi:[1,0,1] neg_lo:[1,0,0] neg_hi:[1,0,0]
	v_pk_fma_f32 v[86:87], v[16:17], v[76:77], v[86:87] op_sel:[0,1,0] op_sel_hi:[1,1,1] neg_lo:[1,0,0] neg_hi:[1,0,0]
	v_pk_fma_f32 v[86:87], v[18:19], v[78:79], v[86:87] op_sel_hi:[1,0,1] neg_lo:[1,0,0] neg_hi:[1,0,0]
	v_pk_fma_f32 v[86:87], v[20:21], v[78:79], v[86:87] op_sel:[0,1,0] op_sel_hi:[1,1,1] neg_lo:[1,0,0] neg_hi:[1,0,0]
	v_pk_fma_f32 v[86:87], v[22:23], v[80:81], v[86:87] op_sel_hi:[1,0,1] neg_lo:[1,0,0] neg_hi:[1,0,0]
	v_pk_fma_f32 v[86:87], v[24:25], v[80:81], v[86:87] op_sel:[0,1,0] op_sel_hi:[1,1,1] neg_lo:[1,0,0] neg_hi:[1,0,0]
	ds_read_u16 v26, v30 offset:11424
	ds_read_u16 v27, v30 offset:11696
	ds_read_b64 v[28:29], v31 offset:168
	ds_read_b128 v[2:5], v32 offset:11424
	ds_read_b128 v[6:9], v32 offset:11440
	ds_read_b128 v[10:13], v32 offset:11456
	ds_read_b128 v[14:17], v32 offset:11472
	ds_read_b128 v[18:21], v32 offset:11488
	ds_read_b128 v[22:25], v32 offset:11504
	s_waitcnt lgkmcnt(9)
	v_pk_fma_f32 v[86:87], v[120:121], v[82:83], v[86:87] op_sel_hi:[1,0,1] neg_lo:[1,0,0] neg_hi:[1,0,0]
	v_pk_fma_f32 v[86:87], v[122:123], v[82:83], v[86:87] op_sel:[0,1,0] op_sel_hi:[1,1,1] neg_lo:[1,0,0] neg_hi:[1,0,0]
	v_pk_fma_f32 v[86:87], v[124:125], v[84:85], v[86:87] op_sel_hi:[1,0,1] neg_lo:[1,0,0] neg_hi:[1,0,0]
	v_pk_fma_f32 v[86:87], v[126:127], v[84:85], v[86:87] op_sel:[0,1,0] op_sel_hi:[1,1,1] neg_lo:[1,0,0] neg_hi:[1,0,0]
	v_fma_f32 v87, -v129, v86, v87
	ds_read_b128 v[120:123], v32 offset:11520
	ds_read_b128 v[124:127], v32 offset:11536
	ds_read_b128 v[128:131], v32 offset:11552
	ds_read_b128 v[132:135], v32 offset:11568
	ds_read_b128 v[144:147], v32 offset:11584
	ds_read_b128 v[148:151], v32 offset:11600
	s_waitcnt lgkmcnt(6)
	v_lshlrev_b32_e32 v26, 16, v26
	v_lshlrev_b32_e32 v27, 16, v27
	v_pk_mul_f32 v[88:89], v[26:27], v[28:29]
	v_pk_fma_f32 v[88:89], v[2:3], v[46:47], v[88:89] op_sel_hi:[1,0,1] neg_lo:[1,0,0] neg_hi:[1,0,0]
	v_pk_fma_f32 v[88:89], v[4:5], v[46:47], v[88:89] op_sel:[0,1,0] op_sel_hi:[1,1,1] neg_lo:[1,0,0] neg_hi:[1,0,0]
	v_pk_fma_f32 v[88:89], v[6:7], v[48:49], v[88:89] op_sel_hi:[1,0,1] neg_lo:[1,0,0] neg_hi:[1,0,0]
	v_pk_fma_f32 v[88:89], v[8:9], v[48:49], v[88:89] op_sel:[0,1,0] op_sel_hi:[1,1,1] neg_lo:[1,0,0] neg_hi:[1,0,0]
	v_pk_fma_f32 v[88:89], v[10:11], v[50:51], v[88:89] op_sel_hi:[1,0,1] neg_lo:[1,0,0] neg_hi:[1,0,0]
	v_pk_fma_f32 v[88:89], v[12:13], v[50:51], v[88:89] op_sel:[0,1,0] op_sel_hi:[1,1,1] neg_lo:[1,0,0] neg_hi:[1,0,0]
	v_pk_fma_f32 v[88:89], v[14:15], v[52:53], v[88:89] op_sel_hi:[1,0,1] neg_lo:[1,0,0] neg_hi:[1,0,0]
	v_pk_fma_f32 v[88:89], v[16:17], v[52:53], v[88:89] op_sel:[0,1,0] op_sel_hi:[1,1,1] neg_lo:[1,0,0] neg_hi:[1,0,0]
	v_pk_fma_f32 v[88:89], v[18:19], v[54:55], v[88:89] op_sel_hi:[1,0,1] neg_lo:[1,0,0] neg_hi:[1,0,0]
	v_pk_fma_f32 v[88:89], v[20:21], v[54:55], v[88:89] op_sel:[0,1,0] op_sel_hi:[1,1,1] neg_lo:[1,0,0] neg_hi:[1,0,0]
	v_pk_fma_f32 v[88:89], v[22:23], v[56:57], v[88:89] op_sel_hi:[1,0,1] neg_lo:[1,0,0] neg_hi:[1,0,0]
	v_pk_fma_f32 v[88:89], v[24:25], v[56:57], v[88:89] op_sel:[0,1,0] op_sel_hi:[1,1,1] neg_lo:[1,0,0] neg_hi:[1,0,0]
	ds_read_b128 v[2:5], v32 offset:11616
	ds_read_b128 v[6:9], v32 offset:11632
	ds_read_b128 v[10:13], v32 offset:11648
	ds_read_b128 v[14:17], v32 offset:11664
	ds_read_b128 v[18:21], v32 offset:11680
	ds_read_b128 v[22:25], v32 offset:11696
	s_waitcnt lgkmcnt(6)
	v_pk_fma_f32 v[88:89], v[120:121], v[58:59], v[88:89] op_sel_hi:[1,0,1] neg_lo:[1,0,0] neg_hi:[1,0,0]
	v_pk_fma_f32 v[88:89], v[122:123], v[58:59], v[88:89] op_sel:[0,1,0] op_sel_hi:[1,1,1] neg_lo:[1,0,0] neg_hi:[1,0,0]
	v_pk_fma_f32 v[88:89], v[124:125], v[60:61], v[88:89] op_sel_hi:[1,0,1] neg_lo:[1,0,0] neg_hi:[1,0,0]
	v_pk_fma_f32 v[88:89], v[126:127], v[60:61], v[88:89] op_sel:[0,1,0] op_sel_hi:[1,1,1] neg_lo:[1,0,0] neg_hi:[1,0,0]
	v_pk_fma_f32 v[88:89], v[128:129], v[62:63], v[88:89] op_sel_hi:[1,0,1] neg_lo:[1,0,0] neg_hi:[1,0,0]
	v_pk_fma_f32 v[88:89], v[130:131], v[62:63], v[88:89] op_sel:[0,1,0] op_sel_hi:[1,1,1] neg_lo:[1,0,0] neg_hi:[1,0,0]
	v_pk_fma_f32 v[88:89], v[132:133], v[64:65], v[88:89] op_sel_hi:[1,0,1] neg_lo:[1,0,0] neg_hi:[1,0,0]
	v_pk_fma_f32 v[88:89], v[134:135], v[64:65], v[88:89] op_sel:[0,1,0] op_sel_hi:[1,1,1] neg_lo:[1,0,0] neg_hi:[1,0,0]
	v_pk_fma_f32 v[88:89], v[144:145], v[66:67], v[88:89] op_sel_hi:[1,0,1] neg_lo:[1,0,0] neg_hi:[1,0,0]
	v_pk_fma_f32 v[88:89], v[146:147], v[66:67], v[88:89] op_sel:[0,1,0] op_sel_hi:[1,1,1] neg_lo:[1,0,0] neg_hi:[1,0,0]
	v_pk_fma_f32 v[88:89], v[148:149], v[68:69], v[88:89] op_sel_hi:[1,0,1] neg_lo:[1,0,0] neg_hi:[1,0,0]
	v_pk_fma_f32 v[88:89], v[150:151], v[68:69], v[88:89] op_sel:[0,1,0] op_sel_hi:[1,1,1] neg_lo:[1,0,0] neg_hi:[1,0,0]
	ds_read_b128 v[120:123], v32 offset:11712
	ds_read_b128 v[124:127], v32 offset:11728
	ds_read_b128 v[128:131], v32 offset:11744
	ds_read_b128 v[132:135], v32 offset:11760
	s_waitcnt lgkmcnt(4)
	v_pk_fma_f32 v[88:89], v[2:3], v[70:71], v[88:89] op_sel_hi:[1,0,1] neg_lo:[1,0,0] neg_hi:[1,0,0]
	v_pk_fma_f32 v[88:89], v[4:5], v[70:71], v[88:89] op_sel:[0,1,0] op_sel_hi:[1,1,1] neg_lo:[1,0,0] neg_hi:[1,0,0]
	v_pk_fma_f32 v[88:89], v[6:7], v[72:73], v[88:89] op_sel_hi:[1,0,1] neg_lo:[1,0,0] neg_hi:[1,0,0]
	v_pk_fma_f32 v[88:89], v[8:9], v[72:73], v[88:89] op_sel:[0,1,0] op_sel_hi:[1,1,1] neg_lo:[1,0,0] neg_hi:[1,0,0]
	v_pk_fma_f32 v[88:89], v[10:11], v[74:75], v[88:89] op_sel_hi:[1,0,1] neg_lo:[1,0,0] neg_hi:[1,0,0]
	v_pk_fma_f32 v[88:89], v[12:13], v[74:75], v[88:89] op_sel:[0,1,0] op_sel_hi:[1,1,1] neg_lo:[1,0,0] neg_hi:[1,0,0]
	v_pk_fma_f32 v[88:89], v[14:15], v[76:77], v[88:89] op_sel_hi:[1,0,1] neg_lo:[1,0,0] neg_hi:[1,0,0]
	v_pk_fma_f32 v[88:89], v[16:17], v[76:77], v[88:89] op_sel:[0,1,0] op_sel_hi:[1,1,1] neg_lo:[1,0,0] neg_hi:[1,0,0]
	v_pk_fma_f32 v[88:89], v[18:19], v[78:79], v[88:89] op_sel_hi:[1,0,1] neg_lo:[1,0,0] neg_hi:[1,0,0]
	v_pk_fma_f32 v[88:89], v[20:21], v[78:79], v[88:89] op_sel:[0,1,0] op_sel_hi:[1,1,1] neg_lo:[1,0,0] neg_hi:[1,0,0]
	v_pk_fma_f32 v[88:89], v[22:23], v[80:81], v[88:89] op_sel_hi:[1,0,1] neg_lo:[1,0,0] neg_hi:[1,0,0]
	v_pk_fma_f32 v[88:89], v[24:25], v[80:81], v[88:89] op_sel:[0,1,0] op_sel_hi:[1,1,1] neg_lo:[1,0,0] neg_hi:[1,0,0]
	ds_read_u16 v26, v30 offset:11968
	ds_read_u16 v27, v30 offset:12240
	ds_read_b64 v[28:29], v31 offset:176
	ds_read_b128 v[2:5], v32 offset:11968
	ds_read_b128 v[6:9], v32 offset:11984
	ds_read_b128 v[10:13], v32 offset:12000
	ds_read_b128 v[14:17], v32 offset:12016
	ds_read_b128 v[18:21], v32 offset:12032
	ds_read_b128 v[22:25], v32 offset:12048
	s_waitcnt lgkmcnt(9)
	v_pk_fma_f32 v[88:89], v[120:121], v[82:83], v[88:89] op_sel_hi:[1,0,1] neg_lo:[1,0,0] neg_hi:[1,0,0]
	v_pk_fma_f32 v[88:89], v[122:123], v[82:83], v[88:89] op_sel:[0,1,0] op_sel_hi:[1,1,1] neg_lo:[1,0,0] neg_hi:[1,0,0]
	v_pk_fma_f32 v[88:89], v[124:125], v[84:85], v[88:89] op_sel_hi:[1,0,1] neg_lo:[1,0,0] neg_hi:[1,0,0]
	v_pk_fma_f32 v[88:89], v[126:127], v[84:85], v[88:89] op_sel:[0,1,0] op_sel_hi:[1,1,1] neg_lo:[1,0,0] neg_hi:[1,0,0]
	v_pk_fma_f32 v[88:89], v[128:129], v[86:87], v[88:89] op_sel_hi:[1,0,1] neg_lo:[1,0,0] neg_hi:[1,0,0]
	v_pk_fma_f32 v[88:89], v[130:131], v[86:87], v[88:89] op_sel:[0,1,0] op_sel_hi:[1,1,1] neg_lo:[1,0,0] neg_hi:[1,0,0]
	v_fma_f32 v89, -v133, v88, v89
	ds_read_b128 v[120:123], v32 offset:12064
	ds_read_b128 v[124:127], v32 offset:12080
	ds_read_b128 v[128:131], v32 offset:12096
	ds_read_b128 v[132:135], v32 offset:12112
	ds_read_b128 v[144:147], v32 offset:12128
	ds_read_b128 v[148:151], v32 offset:12144
	s_waitcnt lgkmcnt(6)
	v_lshlrev_b32_e32 v26, 16, v26
	v_lshlrev_b32_e32 v27, 16, v27
	v_pk_mul_f32 v[90:91], v[26:27], v[28:29]
	v_pk_fma_f32 v[90:91], v[2:3], v[46:47], v[90:91] op_sel_hi:[1,0,1] neg_lo:[1,0,0] neg_hi:[1,0,0]
	v_pk_fma_f32 v[90:91], v[4:5], v[46:47], v[90:91] op_sel:[0,1,0] op_sel_hi:[1,1,1] neg_lo:[1,0,0] neg_hi:[1,0,0]
	v_pk_fma_f32 v[90:91], v[6:7], v[48:49], v[90:91] op_sel_hi:[1,0,1] neg_lo:[1,0,0] neg_hi:[1,0,0]
	v_pk_fma_f32 v[90:91], v[8:9], v[48:49], v[90:91] op_sel:[0,1,0] op_sel_hi:[1,1,1] neg_lo:[1,0,0] neg_hi:[1,0,0]
	v_pk_fma_f32 v[90:91], v[10:11], v[50:51], v[90:91] op_sel_hi:[1,0,1] neg_lo:[1,0,0] neg_hi:[1,0,0]
	v_pk_fma_f32 v[90:91], v[12:13], v[50:51], v[90:91] op_sel:[0,1,0] op_sel_hi:[1,1,1] neg_lo:[1,0,0] neg_hi:[1,0,0]
	v_pk_fma_f32 v[90:91], v[14:15], v[52:53], v[90:91] op_sel_hi:[1,0,1] neg_lo:[1,0,0] neg_hi:[1,0,0]
	v_pk_fma_f32 v[90:91], v[16:17], v[52:53], v[90:91] op_sel:[0,1,0] op_sel_hi:[1,1,1] neg_lo:[1,0,0] neg_hi:[1,0,0]
	v_pk_fma_f32 v[90:91], v[18:19], v[54:55], v[90:91] op_sel_hi:[1,0,1] neg_lo:[1,0,0] neg_hi:[1,0,0]
	v_pk_fma_f32 v[90:91], v[20:21], v[54:55], v[90:91] op_sel:[0,1,0] op_sel_hi:[1,1,1] neg_lo:[1,0,0] neg_hi:[1,0,0]
	v_pk_fma_f32 v[90:91], v[22:23], v[56:57], v[90:91] op_sel_hi:[1,0,1] neg_lo:[1,0,0] neg_hi:[1,0,0]
	v_pk_fma_f32 v[90:91], v[24:25], v[56:57], v[90:91] op_sel:[0,1,0] op_sel_hi:[1,1,1] neg_lo:[1,0,0] neg_hi:[1,0,0]
	ds_read_b128 v[2:5], v32 offset:12160
	ds_read_b128 v[6:9], v32 offset:12176
	ds_read_b128 v[10:13], v32 offset:12192
	ds_read_b128 v[14:17], v32 offset:12208
	ds_read_b128 v[18:21], v32 offset:12224
	ds_read_b128 v[22:25], v32 offset:12240
	s_waitcnt lgkmcnt(6)
	v_pk_fma_f32 v[90:91], v[120:121], v[58:59], v[90:91] op_sel_hi:[1,0,1] neg_lo:[1,0,0] neg_hi:[1,0,0]
	v_pk_fma_f32 v[90:91], v[122:123], v[58:59], v[90:91] op_sel:[0,1,0] op_sel_hi:[1,1,1] neg_lo:[1,0,0] neg_hi:[1,0,0]
	v_pk_fma_f32 v[90:91], v[124:125], v[60:61], v[90:91] op_sel_hi:[1,0,1] neg_lo:[1,0,0] neg_hi:[1,0,0]
	v_pk_fma_f32 v[90:91], v[126:127], v[60:61], v[90:91] op_sel:[0,1,0] op_sel_hi:[1,1,1] neg_lo:[1,0,0] neg_hi:[1,0,0]
	v_pk_fma_f32 v[90:91], v[128:129], v[62:63], v[90:91] op_sel_hi:[1,0,1] neg_lo:[1,0,0] neg_hi:[1,0,0]
	v_pk_fma_f32 v[90:91], v[130:131], v[62:63], v[90:91] op_sel:[0,1,0] op_sel_hi:[1,1,1] neg_lo:[1,0,0] neg_hi:[1,0,0]
	v_pk_fma_f32 v[90:91], v[132:133], v[64:65], v[90:91] op_sel_hi:[1,0,1] neg_lo:[1,0,0] neg_hi:[1,0,0]
	v_pk_fma_f32 v[90:91], v[134:135], v[64:65], v[90:91] op_sel:[0,1,0] op_sel_hi:[1,1,1] neg_lo:[1,0,0] neg_hi:[1,0,0]
	v_pk_fma_f32 v[90:91], v[144:145], v[66:67], v[90:91] op_sel_hi:[1,0,1] neg_lo:[1,0,0] neg_hi:[1,0,0]
	v_pk_fma_f32 v[90:91], v[146:147], v[66:67], v[90:91] op_sel:[0,1,0] op_sel_hi:[1,1,1] neg_lo:[1,0,0] neg_hi:[1,0,0]
	v_pk_fma_f32 v[90:91], v[148:149], v[68:69], v[90:91] op_sel_hi:[1,0,1] neg_lo:[1,0,0] neg_hi:[1,0,0]
	v_pk_fma_f32 v[90:91], v[150:151], v[68:69], v[90:91] op_sel:[0,1,0] op_sel_hi:[1,1,1] neg_lo:[1,0,0] neg_hi:[1,0,0]
	ds_read_b128 v[120:123], v32 offset:12256
	ds_read_b128 v[124:127], v32 offset:12272
	ds_read_b128 v[128:131], v32 offset:12288
	ds_read_b128 v[132:135], v32 offset:12304
	ds_read_b128 v[144:147], v32 offset:12320
	s_waitcnt lgkmcnt(5)
	v_pk_fma_f32 v[90:91], v[2:3], v[70:71], v[90:91] op_sel_hi:[1,0,1] neg_lo:[1,0,0] neg_hi:[1,0,0]
	v_pk_fma_f32 v[90:91], v[4:5], v[70:71], v[90:91] op_sel:[0,1,0] op_sel_hi:[1,1,1] neg_lo:[1,0,0] neg_hi:[1,0,0]
	v_pk_fma_f32 v[90:91], v[6:7], v[72:73], v[90:91] op_sel_hi:[1,0,1] neg_lo:[1,0,0] neg_hi:[1,0,0]
	v_pk_fma_f32 v[90:91], v[8:9], v[72:73], v[90:91] op_sel:[0,1,0] op_sel_hi:[1,1,1] neg_lo:[1,0,0] neg_hi:[1,0,0]
	v_pk_fma_f32 v[90:91], v[10:11], v[74:75], v[90:91] op_sel_hi:[1,0,1] neg_lo:[1,0,0] neg_hi:[1,0,0]
	v_pk_fma_f32 v[90:91], v[12:13], v[74:75], v[90:91] op_sel:[0,1,0] op_sel_hi:[1,1,1] neg_lo:[1,0,0] neg_hi:[1,0,0]
	v_pk_fma_f32 v[90:91], v[14:15], v[76:77], v[90:91] op_sel_hi:[1,0,1] neg_lo:[1,0,0] neg_hi:[1,0,0]
	v_pk_fma_f32 v[90:91], v[16:17], v[76:77], v[90:91] op_sel:[0,1,0] op_sel_hi:[1,1,1] neg_lo:[1,0,0] neg_hi:[1,0,0]
	v_pk_fma_f32 v[90:91], v[18:19], v[78:79], v[90:91] op_sel_hi:[1,0,1] neg_lo:[1,0,0] neg_hi:[1,0,0]
	v_pk_fma_f32 v[90:91], v[20:21], v[78:79], v[90:91] op_sel:[0,1,0] op_sel_hi:[1,1,1] neg_lo:[1,0,0] neg_hi:[1,0,0]
	v_pk_fma_f32 v[90:91], v[22:23], v[80:81], v[90:91] op_sel_hi:[1,0,1] neg_lo:[1,0,0] neg_hi:[1,0,0]
	v_pk_fma_f32 v[90:91], v[24:25], v[80:81], v[90:91] op_sel:[0,1,0] op_sel_hi:[1,1,1] neg_lo:[1,0,0] neg_hi:[1,0,0]
	ds_read_u16 v26, v30 offset:12512
	ds_read_u16 v27, v30 offset:12784
	ds_read_b64 v[28:29], v31 offset:184
	ds_read_b128 v[2:5], v32 offset:12512
	ds_read_b128 v[6:9], v32 offset:12528
	ds_read_b128 v[10:13], v32 offset:12544
	ds_read_b128 v[14:17], v32 offset:12560
	ds_read_b128 v[18:21], v32 offset:12576
	ds_read_b128 v[22:25], v32 offset:12592
	s_waitcnt lgkmcnt(9)
	v_pk_fma_f32 v[90:91], v[120:121], v[82:83], v[90:91] op_sel_hi:[1,0,1] neg_lo:[1,0,0] neg_hi:[1,0,0]
	v_pk_fma_f32 v[90:91], v[122:123], v[82:83], v[90:91] op_sel:[0,1,0] op_sel_hi:[1,1,1] neg_lo:[1,0,0] neg_hi:[1,0,0]
	v_pk_fma_f32 v[90:91], v[124:125], v[84:85], v[90:91] op_sel_hi:[1,0,1] neg_lo:[1,0,0] neg_hi:[1,0,0]
	v_pk_fma_f32 v[90:91], v[126:127], v[84:85], v[90:91] op_sel:[0,1,0] op_sel_hi:[1,1,1] neg_lo:[1,0,0] neg_hi:[1,0,0]
	v_pk_fma_f32 v[90:91], v[128:129], v[86:87], v[90:91] op_sel_hi:[1,0,1] neg_lo:[1,0,0] neg_hi:[1,0,0]
	v_pk_fma_f32 v[90:91], v[130:131], v[86:87], v[90:91] op_sel:[0,1,0] op_sel_hi:[1,1,1] neg_lo:[1,0,0] neg_hi:[1,0,0]
	v_pk_fma_f32 v[90:91], v[132:133], v[88:89], v[90:91] op_sel_hi:[1,0,1] neg_lo:[1,0,0] neg_hi:[1,0,0]
	v_pk_fma_f32 v[90:91], v[134:135], v[88:89], v[90:91] op_sel:[0,1,0] op_sel_hi:[1,1,1] neg_lo:[1,0,0] neg_hi:[1,0,0]
	v_fma_f32 v91, -v145, v90, v91
	ds_read_b128 v[120:123], v32 offset:12608
	ds_read_b128 v[124:127], v32 offset:12624
	ds_read_b128 v[128:131], v32 offset:12640
	ds_read_b128 v[132:135], v32 offset:12656
	ds_read_b128 v[144:147], v32 offset:12672
	ds_read_b128 v[148:151], v32 offset:12688
	s_waitcnt lgkmcnt(6)
	v_lshlrev_b32_e32 v26, 16, v26
	v_lshlrev_b32_e32 v27, 16, v27
	v_pk_mul_f32 v[92:93], v[26:27], v[28:29]
	v_pk_fma_f32 v[92:93], v[2:3], v[46:47], v[92:93] op_sel_hi:[1,0,1] neg_lo:[1,0,0] neg_hi:[1,0,0]
	v_pk_fma_f32 v[92:93], v[4:5], v[46:47], v[92:93] op_sel:[0,1,0] op_sel_hi:[1,1,1] neg_lo:[1,0,0] neg_hi:[1,0,0]
	v_pk_fma_f32 v[92:93], v[6:7], v[48:49], v[92:93] op_sel_hi:[1,0,1] neg_lo:[1,0,0] neg_hi:[1,0,0]
	v_pk_fma_f32 v[92:93], v[8:9], v[48:49], v[92:93] op_sel:[0,1,0] op_sel_hi:[1,1,1] neg_lo:[1,0,0] neg_hi:[1,0,0]
	v_pk_fma_f32 v[92:93], v[10:11], v[50:51], v[92:93] op_sel_hi:[1,0,1] neg_lo:[1,0,0] neg_hi:[1,0,0]
	v_pk_fma_f32 v[92:93], v[12:13], v[50:51], v[92:93] op_sel:[0,1,0] op_sel_hi:[1,1,1] neg_lo:[1,0,0] neg_hi:[1,0,0]
	v_pk_fma_f32 v[92:93], v[14:15], v[52:53], v[92:93] op_sel_hi:[1,0,1] neg_lo:[1,0,0] neg_hi:[1,0,0]
	v_pk_fma_f32 v[92:93], v[16:17], v[52:53], v[92:93] op_sel:[0,1,0] op_sel_hi:[1,1,1] neg_lo:[1,0,0] neg_hi:[1,0,0]
	v_pk_fma_f32 v[92:93], v[18:19], v[54:55], v[92:93] op_sel_hi:[1,0,1] neg_lo:[1,0,0] neg_hi:[1,0,0]
	v_pk_fma_f32 v[92:93], v[20:21], v[54:55], v[92:93] op_sel:[0,1,0] op_sel_hi:[1,1,1] neg_lo:[1,0,0] neg_hi:[1,0,0]
	v_pk_fma_f32 v[92:93], v[22:23], v[56:57], v[92:93] op_sel_hi:[1,0,1] neg_lo:[1,0,0] neg_hi:[1,0,0]
	v_pk_fma_f32 v[92:93], v[24:25], v[56:57], v[92:93] op_sel:[0,1,0] op_sel_hi:[1,1,1] neg_lo:[1,0,0] neg_hi:[1,0,0]
	ds_read_b128 v[2:5], v32 offset:12704
	ds_read_b128 v[6:9], v32 offset:12720
	ds_read_b128 v[10:13], v32 offset:12736
	ds_read_b128 v[14:17], v32 offset:12752
	ds_read_b128 v[18:21], v32 offset:12768
	ds_read_b128 v[22:25], v32 offset:12784
	s_waitcnt lgkmcnt(6)
	v_pk_fma_f32 v[92:93], v[120:121], v[58:59], v[92:93] op_sel_hi:[1,0,1] neg_lo:[1,0,0] neg_hi:[1,0,0]
	v_pk_fma_f32 v[92:93], v[122:123], v[58:59], v[92:93] op_sel:[0,1,0] op_sel_hi:[1,1,1] neg_lo:[1,0,0] neg_hi:[1,0,0]
	v_pk_fma_f32 v[92:93], v[124:125], v[60:61], v[92:93] op_sel_hi:[1,0,1] neg_lo:[1,0,0] neg_hi:[1,0,0]
	v_pk_fma_f32 v[92:93], v[126:127], v[60:61], v[92:93] op_sel:[0,1,0] op_sel_hi:[1,1,1] neg_lo:[1,0,0] neg_hi:[1,0,0]
	v_pk_fma_f32 v[92:93], v[128:129], v[62:63], v[92:93] op_sel_hi:[1,0,1] neg_lo:[1,0,0] neg_hi:[1,0,0]
	v_pk_fma_f32 v[92:93], v[130:131], v[62:63], v[92:93] op_sel:[0,1,0] op_sel_hi:[1,1,1] neg_lo:[1,0,0] neg_hi:[1,0,0]
	v_pk_fma_f32 v[92:93], v[132:133], v[64:65], v[92:93] op_sel_hi:[1,0,1] neg_lo:[1,0,0] neg_hi:[1,0,0]
	v_pk_fma_f32 v[92:93], v[134:135], v[64:65], v[92:93] op_sel:[0,1,0] op_sel_hi:[1,1,1] neg_lo:[1,0,0] neg_hi:[1,0,0]
	v_pk_fma_f32 v[92:93], v[144:145], v[66:67], v[92:93] op_sel_hi:[1,0,1] neg_lo:[1,0,0] neg_hi:[1,0,0]
	v_pk_fma_f32 v[92:93], v[146:147], v[66:67], v[92:93] op_sel:[0,1,0] op_sel_hi:[1,1,1] neg_lo:[1,0,0] neg_hi:[1,0,0]
	v_pk_fma_f32 v[92:93], v[148:149], v[68:69], v[92:93] op_sel_hi:[1,0,1] neg_lo:[1,0,0] neg_hi:[1,0,0]
	v_pk_fma_f32 v[92:93], v[150:151], v[68:69], v[92:93] op_sel:[0,1,0] op_sel_hi:[1,1,1] neg_lo:[1,0,0] neg_hi:[1,0,0]
	ds_read_b128 v[120:123], v32 offset:12800
	ds_read_b128 v[124:127], v32 offset:12816
	ds_read_b128 v[128:131], v32 offset:12832
	ds_read_b128 v[132:135], v32 offset:12848
	ds_read_b128 v[144:147], v32 offset:12864
	ds_read_b128 v[148:151], v32 offset:12880
	s_waitcnt lgkmcnt(6)
	v_pk_fma_f32 v[92:93], v[2:3], v[70:71], v[92:93] op_sel_hi:[1,0,1] neg_lo:[1,0,0] neg_hi:[1,0,0]
	v_pk_fma_f32 v[92:93], v[4:5], v[70:71], v[92:93] op_sel:[0,1,0] op_sel_hi:[1,1,1] neg_lo:[1,0,0] neg_hi:[1,0,0]
	v_pk_fma_f32 v[92:93], v[6:7], v[72:73], v[92:93] op_sel_hi:[1,0,1] neg_lo:[1,0,0] neg_hi:[1,0,0]
	v_pk_fma_f32 v[92:93], v[8:9], v[72:73], v[92:93] op_sel:[0,1,0] op_sel_hi:[1,1,1] neg_lo:[1,0,0] neg_hi:[1,0,0]
	v_pk_fma_f32 v[92:93], v[10:11], v[74:75], v[92:93] op_sel_hi:[1,0,1] neg_lo:[1,0,0] neg_hi:[1,0,0]
	v_pk_fma_f32 v[92:93], v[12:13], v[74:75], v[92:93] op_sel:[0,1,0] op_sel_hi:[1,1,1] neg_lo:[1,0,0] neg_hi:[1,0,0]
	v_pk_fma_f32 v[92:93], v[14:15], v[76:77], v[92:93] op_sel_hi:[1,0,1] neg_lo:[1,0,0] neg_hi:[1,0,0]
	v_pk_fma_f32 v[92:93], v[16:17], v[76:77], v[92:93] op_sel:[0,1,0] op_sel_hi:[1,1,1] neg_lo:[1,0,0] neg_hi:[1,0,0]
	v_pk_fma_f32 v[92:93], v[18:19], v[78:79], v[92:93] op_sel_hi:[1,0,1] neg_lo:[1,0,0] neg_hi:[1,0,0]
	v_pk_fma_f32 v[92:93], v[20:21], v[78:79], v[92:93] op_sel:[0,1,0] op_sel_hi:[1,1,1] neg_lo:[1,0,0] neg_hi:[1,0,0]
	v_pk_fma_f32 v[92:93], v[22:23], v[80:81], v[92:93] op_sel_hi:[1,0,1] neg_lo:[1,0,0] neg_hi:[1,0,0]
	v_pk_fma_f32 v[92:93], v[24:25], v[80:81], v[92:93] op_sel:[0,1,0] op_sel_hi:[1,1,1] neg_lo:[1,0,0] neg_hi:[1,0,0]
	ds_read_u16 v26, v30 offset:13056
	ds_read_u16 v27, v30 offset:13328
	ds_read_b64 v[28:29], v31 offset:192
	ds_read_b128 v[2:5], v32 offset:13056
	ds_read_b128 v[6:9], v32 offset:13072
	ds_read_b128 v[10:13], v32 offset:13088
	ds_read_b128 v[14:17], v32 offset:13104
	ds_read_b128 v[18:21], v32 offset:13120
	ds_read_b128 v[22:25], v32 offset:13136
	s_waitcnt lgkmcnt(9)
	v_pk_fma_f32 v[92:93], v[120:121], v[82:83], v[92:93] op_sel_hi:[1,0,1] neg_lo:[1,0,0] neg_hi:[1,0,0]
	v_pk_fma_f32 v[92:93], v[122:123], v[82:83], v[92:93] op_sel:[0,1,0] op_sel_hi:[1,1,1] neg_lo:[1,0,0] neg_hi:[1,0,0]
	v_pk_fma_f32 v[92:93], v[124:125], v[84:85], v[92:93] op_sel_hi:[1,0,1] neg_lo:[1,0,0] neg_hi:[1,0,0]
	v_pk_fma_f32 v[92:93], v[126:127], v[84:85], v[92:93] op_sel:[0,1,0] op_sel_hi:[1,1,1] neg_lo:[1,0,0] neg_hi:[1,0,0]
	v_pk_fma_f32 v[92:93], v[128:129], v[86:87], v[92:93] op_sel_hi:[1,0,1] neg_lo:[1,0,0] neg_hi:[1,0,0]
	v_pk_fma_f32 v[92:93], v[130:131], v[86:87], v[92:93] op_sel:[0,1,0] op_sel_hi:[1,1,1] neg_lo:[1,0,0] neg_hi:[1,0,0]
	v_pk_fma_f32 v[92:93], v[132:133], v[88:89], v[92:93] op_sel_hi:[1,0,1] neg_lo:[1,0,0] neg_hi:[1,0,0]
	v_pk_fma_f32 v[92:93], v[134:135], v[88:89], v[92:93] op_sel:[0,1,0] op_sel_hi:[1,1,1] neg_lo:[1,0,0] neg_hi:[1,0,0]
	v_pk_fma_f32 v[92:93], v[144:145], v[90:91], v[92:93] op_sel_hi:[1,0,1] neg_lo:[1,0,0] neg_hi:[1,0,0]
	v_pk_fma_f32 v[92:93], v[146:147], v[90:91], v[92:93] op_sel:[0,1,0] op_sel_hi:[1,1,1] neg_lo:[1,0,0] neg_hi:[1,0,0]
	v_fma_f32 v93, -v149, v92, v93
	ds_read_b128 v[120:123], v32 offset:13152
	ds_read_b128 v[124:127], v32 offset:13168
	ds_read_b128 v[128:131], v32 offset:13184
	ds_read_b128 v[132:135], v32 offset:13200
	ds_read_b128 v[144:147], v32 offset:13216
	ds_read_b128 v[148:151], v32 offset:13232
	s_waitcnt lgkmcnt(6)
	v_lshlrev_b32_e32 v26, 16, v26
	v_lshlrev_b32_e32 v27, 16, v27
	v_pk_mul_f32 v[94:95], v[26:27], v[28:29]
	v_pk_fma_f32 v[94:95], v[2:3], v[46:47], v[94:95] op_sel_hi:[1,0,1] neg_lo:[1,0,0] neg_hi:[1,0,0]
	v_pk_fma_f32 v[94:95], v[4:5], v[46:47], v[94:95] op_sel:[0,1,0] op_sel_hi:[1,1,1] neg_lo:[1,0,0] neg_hi:[1,0,0]
	v_pk_fma_f32 v[94:95], v[6:7], v[48:49], v[94:95] op_sel_hi:[1,0,1] neg_lo:[1,0,0] neg_hi:[1,0,0]
	v_pk_fma_f32 v[94:95], v[8:9], v[48:49], v[94:95] op_sel:[0,1,0] op_sel_hi:[1,1,1] neg_lo:[1,0,0] neg_hi:[1,0,0]
	v_pk_fma_f32 v[94:95], v[10:11], v[50:51], v[94:95] op_sel_hi:[1,0,1] neg_lo:[1,0,0] neg_hi:[1,0,0]
	v_pk_fma_f32 v[94:95], v[12:13], v[50:51], v[94:95] op_sel:[0,1,0] op_sel_hi:[1,1,1] neg_lo:[1,0,0] neg_hi:[1,0,0]
	v_pk_fma_f32 v[94:95], v[14:15], v[52:53], v[94:95] op_sel_hi:[1,0,1] neg_lo:[1,0,0] neg_hi:[1,0,0]
	v_pk_fma_f32 v[94:95], v[16:17], v[52:53], v[94:95] op_sel:[0,1,0] op_sel_hi:[1,1,1] neg_lo:[1,0,0] neg_hi:[1,0,0]
	v_pk_fma_f32 v[94:95], v[18:19], v[54:55], v[94:95] op_sel_hi:[1,0,1] neg_lo:[1,0,0] neg_hi:[1,0,0]
	v_pk_fma_f32 v[94:95], v[20:21], v[54:55], v[94:95] op_sel:[0,1,0] op_sel_hi:[1,1,1] neg_lo:[1,0,0] neg_hi:[1,0,0]
	v_pk_fma_f32 v[94:95], v[22:23], v[56:57], v[94:95] op_sel_hi:[1,0,1] neg_lo:[1,0,0] neg_hi:[1,0,0]
	v_pk_fma_f32 v[94:95], v[24:25], v[56:57], v[94:95] op_sel:[0,1,0] op_sel_hi:[1,1,1] neg_lo:[1,0,0] neg_hi:[1,0,0]
	ds_read_b128 v[2:5], v32 offset:13248
	ds_read_b128 v[6:9], v32 offset:13264
	ds_read_b128 v[10:13], v32 offset:13280
	ds_read_b128 v[14:17], v32 offset:13296
	ds_read_b128 v[18:21], v32 offset:13312
	ds_read_b128 v[22:25], v32 offset:13328
	s_waitcnt lgkmcnt(6)
	v_pk_fma_f32 v[94:95], v[120:121], v[58:59], v[94:95] op_sel_hi:[1,0,1] neg_lo:[1,0,0] neg_hi:[1,0,0]
	v_pk_fma_f32 v[94:95], v[122:123], v[58:59], v[94:95] op_sel:[0,1,0] op_sel_hi:[1,1,1] neg_lo:[1,0,0] neg_hi:[1,0,0]
	v_pk_fma_f32 v[94:95], v[124:125], v[60:61], v[94:95] op_sel_hi:[1,0,1] neg_lo:[1,0,0] neg_hi:[1,0,0]
	v_pk_fma_f32 v[94:95], v[126:127], v[60:61], v[94:95] op_sel:[0,1,0] op_sel_hi:[1,1,1] neg_lo:[1,0,0] neg_hi:[1,0,0]
	v_pk_fma_f32 v[94:95], v[128:129], v[62:63], v[94:95] op_sel_hi:[1,0,1] neg_lo:[1,0,0] neg_hi:[1,0,0]
	v_pk_fma_f32 v[94:95], v[130:131], v[62:63], v[94:95] op_sel:[0,1,0] op_sel_hi:[1,1,1] neg_lo:[1,0,0] neg_hi:[1,0,0]
	v_pk_fma_f32 v[94:95], v[132:133], v[64:65], v[94:95] op_sel_hi:[1,0,1] neg_lo:[1,0,0] neg_hi:[1,0,0]
	v_pk_fma_f32 v[94:95], v[134:135], v[64:65], v[94:95] op_sel:[0,1,0] op_sel_hi:[1,1,1] neg_lo:[1,0,0] neg_hi:[1,0,0]
	v_pk_fma_f32 v[94:95], v[144:145], v[66:67], v[94:95] op_sel_hi:[1,0,1] neg_lo:[1,0,0] neg_hi:[1,0,0]
	v_pk_fma_f32 v[94:95], v[146:147], v[66:67], v[94:95] op_sel:[0,1,0] op_sel_hi:[1,1,1] neg_lo:[1,0,0] neg_hi:[1,0,0]
	v_pk_fma_f32 v[94:95], v[148:149], v[68:69], v[94:95] op_sel_hi:[1,0,1] neg_lo:[1,0,0] neg_hi:[1,0,0]
	v_pk_fma_f32 v[94:95], v[150:151], v[68:69], v[94:95] op_sel:[0,1,0] op_sel_hi:[1,1,1] neg_lo:[1,0,0] neg_hi:[1,0,0]
	ds_read_b128 v[120:123], v32 offset:13344
	ds_read_b128 v[124:127], v32 offset:13360
	ds_read_b128 v[128:131], v32 offset:13376
	ds_read_b128 v[132:135], v32 offset:13392
	ds_read_b128 v[144:147], v32 offset:13408
	ds_read_b128 v[148:151], v32 offset:13424
	s_waitcnt lgkmcnt(6)
	v_pk_fma_f32 v[94:95], v[2:3], v[70:71], v[94:95] op_sel_hi:[1,0,1] neg_lo:[1,0,0] neg_hi:[1,0,0]
	v_pk_fma_f32 v[94:95], v[4:5], v[70:71], v[94:95] op_sel:[0,1,0] op_sel_hi:[1,1,1] neg_lo:[1,0,0] neg_hi:[1,0,0]
	v_pk_fma_f32 v[94:95], v[6:7], v[72:73], v[94:95] op_sel_hi:[1,0,1] neg_lo:[1,0,0] neg_hi:[1,0,0]
	v_pk_fma_f32 v[94:95], v[8:9], v[72:73], v[94:95] op_sel:[0,1,0] op_sel_hi:[1,1,1] neg_lo:[1,0,0] neg_hi:[1,0,0]
	v_pk_fma_f32 v[94:95], v[10:11], v[74:75], v[94:95] op_sel_hi:[1,0,1] neg_lo:[1,0,0] neg_hi:[1,0,0]
	v_pk_fma_f32 v[94:95], v[12:13], v[74:75], v[94:95] op_sel:[0,1,0] op_sel_hi:[1,1,1] neg_lo:[1,0,0] neg_hi:[1,0,0]
	v_pk_fma_f32 v[94:95], v[14:15], v[76:77], v[94:95] op_sel_hi:[1,0,1] neg_lo:[1,0,0] neg_hi:[1,0,0]
	v_pk_fma_f32 v[94:95], v[16:17], v[76:77], v[94:95] op_sel:[0,1,0] op_sel_hi:[1,1,1] neg_lo:[1,0,0] neg_hi:[1,0,0]
	v_pk_fma_f32 v[94:95], v[18:19], v[78:79], v[94:95] op_sel_hi:[1,0,1] neg_lo:[1,0,0] neg_hi:[1,0,0]
	v_pk_fma_f32 v[94:95], v[20:21], v[78:79], v[94:95] op_sel:[0,1,0] op_sel_hi:[1,1,1] neg_lo:[1,0,0] neg_hi:[1,0,0]
	v_pk_fma_f32 v[94:95], v[22:23], v[80:81], v[94:95] op_sel_hi:[1,0,1] neg_lo:[1,0,0] neg_hi:[1,0,0]
	v_pk_fma_f32 v[94:95], v[24:25], v[80:81], v[94:95] op_sel:[0,1,0] op_sel_hi:[1,1,1] neg_lo:[1,0,0] neg_hi:[1,0,0]
	ds_read_b128 v[2:5], v32 offset:13440
	s_waitcnt lgkmcnt(1)
	v_pk_fma_f32 v[94:95], v[120:121], v[82:83], v[94:95] op_sel_hi:[1,0,1] neg_lo:[1,0,0] neg_hi:[1,0,0]
	v_pk_fma_f32 v[94:95], v[122:123], v[82:83], v[94:95] op_sel:[0,1,0] op_sel_hi:[1,1,1] neg_lo:[1,0,0] neg_hi:[1,0,0]
	v_pk_fma_f32 v[94:95], v[124:125], v[84:85], v[94:95] op_sel_hi:[1,0,1] neg_lo:[1,0,0] neg_hi:[1,0,0]
	v_pk_fma_f32 v[94:95], v[126:127], v[84:85], v[94:95] op_sel:[0,1,0] op_sel_hi:[1,1,1] neg_lo:[1,0,0] neg_hi:[1,0,0]
	v_pk_fma_f32 v[94:95], v[128:129], v[86:87], v[94:95] op_sel_hi:[1,0,1] neg_lo:[1,0,0] neg_hi:[1,0,0]
	v_pk_fma_f32 v[94:95], v[130:131], v[86:87], v[94:95] op_sel:[0,1,0] op_sel_hi:[1,1,1] neg_lo:[1,0,0] neg_hi:[1,0,0]
	v_pk_fma_f32 v[94:95], v[132:133], v[88:89], v[94:95] op_sel_hi:[1,0,1] neg_lo:[1,0,0] neg_hi:[1,0,0]
	v_pk_fma_f32 v[94:95], v[134:135], v[88:89], v[94:95] op_sel:[0,1,0] op_sel_hi:[1,1,1] neg_lo:[1,0,0] neg_hi:[1,0,0]
	v_pk_fma_f32 v[94:95], v[144:145], v[90:91], v[94:95] op_sel_hi:[1,0,1] neg_lo:[1,0,0] neg_hi:[1,0,0]
	v_pk_fma_f32 v[94:95], v[146:147], v[90:91], v[94:95] op_sel:[0,1,0] op_sel_hi:[1,1,1] neg_lo:[1,0,0] neg_hi:[1,0,0]
	v_pk_fma_f32 v[94:95], v[148:149], v[92:93], v[94:95] op_sel_hi:[1,0,1] neg_lo:[1,0,0] neg_hi:[1,0,0]
	v_pk_fma_f32 v[94:95], v[150:151], v[92:93], v[94:95] op_sel:[0,1,0] op_sel_hi:[1,1,1] neg_lo:[1,0,0] neg_hi:[1,0,0]
	ds_read_u16 v152, v30 offset:13600
	ds_read_u16 v153, v30 offset:13872
	ds_read_b64 v[154:155], v31 offset:200
	ds_read_b128 v[120:123], v32 offset:13600
	ds_read_b128 v[124:127], v32 offset:13616
	ds_read_b128 v[128:131], v32 offset:13632
	ds_read_b128 v[132:135], v32 offset:13648
	ds_read_b128 v[144:147], v32 offset:13664
	ds_read_b128 v[148:151], v32 offset:13680
	s_waitcnt lgkmcnt(9)
	v_fma_f32 v95, -v3, v94, v95
	ds_read_b128 v[2:5], v32 offset:13696
	ds_read_b128 v[6:9], v32 offset:13712
	ds_read_b128 v[10:13], v32 offset:13728
	ds_read_b128 v[14:17], v32 offset:13744
	ds_read_b128 v[18:21], v32 offset:13760
	ds_read_b128 v[22:25], v32 offset:13776
	s_waitcnt lgkmcnt(6)
	v_lshlrev_b32_e32 v152, 16, v152
	v_lshlrev_b32_e32 v153, 16, v153
	v_pk_mul_f32 v[96:97], v[152:153], v[154:155]
	v_pk_fma_f32 v[96:97], v[120:121], v[46:47], v[96:97] op_sel_hi:[1,0,1] neg_lo:[1,0,0] neg_hi:[1,0,0]
	v_pk_fma_f32 v[96:97], v[122:123], v[46:47], v[96:97] op_sel:[0,1,0] op_sel_hi:[1,1,1] neg_lo:[1,0,0] neg_hi:[1,0,0]
	v_pk_fma_f32 v[96:97], v[124:125], v[48:49], v[96:97] op_sel_hi:[1,0,1] neg_lo:[1,0,0] neg_hi:[1,0,0]
	v_pk_fma_f32 v[96:97], v[126:127], v[48:49], v[96:97] op_sel:[0,1,0] op_sel_hi:[1,1,1] neg_lo:[1,0,0] neg_hi:[1,0,0]
	v_pk_fma_f32 v[96:97], v[128:129], v[50:51], v[96:97] op_sel_hi:[1,0,1] neg_lo:[1,0,0] neg_hi:[1,0,0]
	v_pk_fma_f32 v[96:97], v[130:131], v[50:51], v[96:97] op_sel:[0,1,0] op_sel_hi:[1,1,1] neg_lo:[1,0,0] neg_hi:[1,0,0]
	v_pk_fma_f32 v[96:97], v[132:133], v[52:53], v[96:97] op_sel_hi:[1,0,1] neg_lo:[1,0,0] neg_hi:[1,0,0]
	v_pk_fma_f32 v[96:97], v[134:135], v[52:53], v[96:97] op_sel:[0,1,0] op_sel_hi:[1,1,1] neg_lo:[1,0,0] neg_hi:[1,0,0]
	v_pk_fma_f32 v[96:97], v[144:145], v[54:55], v[96:97] op_sel_hi:[1,0,1] neg_lo:[1,0,0] neg_hi:[1,0,0]
	v_pk_fma_f32 v[96:97], v[146:147], v[54:55], v[96:97] op_sel:[0,1,0] op_sel_hi:[1,1,1] neg_lo:[1,0,0] neg_hi:[1,0,0]
	v_pk_fma_f32 v[96:97], v[148:149], v[56:57], v[96:97] op_sel_hi:[1,0,1] neg_lo:[1,0,0] neg_hi:[1,0,0]
	v_pk_fma_f32 v[96:97], v[150:151], v[56:57], v[96:97] op_sel:[0,1,0] op_sel_hi:[1,1,1] neg_lo:[1,0,0] neg_hi:[1,0,0]
	ds_read_b128 v[120:123], v32 offset:13792
	ds_read_b128 v[124:127], v32 offset:13808
	ds_read_b128 v[128:131], v32 offset:13824
	ds_read_b128 v[132:135], v32 offset:13840
	ds_read_b128 v[144:147], v32 offset:13856
	ds_read_b128 v[148:151], v32 offset:13872
	s_waitcnt lgkmcnt(6)
	v_pk_fma_f32 v[96:97], v[2:3], v[58:59], v[96:97] op_sel_hi:[1,0,1] neg_lo:[1,0,0] neg_hi:[1,0,0]
	v_pk_fma_f32 v[96:97], v[4:5], v[58:59], v[96:97] op_sel:[0,1,0] op_sel_hi:[1,1,1] neg_lo:[1,0,0] neg_hi:[1,0,0]
	v_pk_fma_f32 v[96:97], v[6:7], v[60:61], v[96:97] op_sel_hi:[1,0,1] neg_lo:[1,0,0] neg_hi:[1,0,0]
	v_pk_fma_f32 v[96:97], v[8:9], v[60:61], v[96:97] op_sel:[0,1,0] op_sel_hi:[1,1,1] neg_lo:[1,0,0] neg_hi:[1,0,0]
	v_pk_fma_f32 v[96:97], v[10:11], v[62:63], v[96:97] op_sel_hi:[1,0,1] neg_lo:[1,0,0] neg_hi:[1,0,0]
	v_pk_fma_f32 v[96:97], v[12:13], v[62:63], v[96:97] op_sel:[0,1,0] op_sel_hi:[1,1,1] neg_lo:[1,0,0] neg_hi:[1,0,0]
	v_pk_fma_f32 v[96:97], v[14:15], v[64:65], v[96:97] op_sel_hi:[1,0,1] neg_lo:[1,0,0] neg_hi:[1,0,0]
	v_pk_fma_f32 v[96:97], v[16:17], v[64:65], v[96:97] op_sel:[0,1,0] op_sel_hi:[1,1,1] neg_lo:[1,0,0] neg_hi:[1,0,0]
	v_pk_fma_f32 v[96:97], v[18:19], v[66:67], v[96:97] op_sel_hi:[1,0,1] neg_lo:[1,0,0] neg_hi:[1,0,0]
	v_pk_fma_f32 v[96:97], v[20:21], v[66:67], v[96:97] op_sel:[0,1,0] op_sel_hi:[1,1,1] neg_lo:[1,0,0] neg_hi:[1,0,0]
	v_pk_fma_f32 v[96:97], v[22:23], v[68:69], v[96:97] op_sel_hi:[1,0,1] neg_lo:[1,0,0] neg_hi:[1,0,0]
	v_pk_fma_f32 v[96:97], v[24:25], v[68:69], v[96:97] op_sel:[0,1,0] op_sel_hi:[1,1,1] neg_lo:[1,0,0] neg_hi:[1,0,0]
	ds_read_b128 v[2:5], v32 offset:13888
	ds_read_b128 v[6:9], v32 offset:13904
	ds_read_b128 v[10:13], v32 offset:13920
	ds_read_b128 v[14:17], v32 offset:13936
	ds_read_b128 v[18:21], v32 offset:13952
	ds_read_b128 v[22:25], v32 offset:13968
	s_waitcnt lgkmcnt(6)
	v_pk_fma_f32 v[96:97], v[120:121], v[70:71], v[96:97] op_sel_hi:[1,0,1] neg_lo:[1,0,0] neg_hi:[1,0,0]
	v_pk_fma_f32 v[96:97], v[122:123], v[70:71], v[96:97] op_sel:[0,1,0] op_sel_hi:[1,1,1] neg_lo:[1,0,0] neg_hi:[1,0,0]
	v_pk_fma_f32 v[96:97], v[124:125], v[72:73], v[96:97] op_sel_hi:[1,0,1] neg_lo:[1,0,0] neg_hi:[1,0,0]
	v_pk_fma_f32 v[96:97], v[126:127], v[72:73], v[96:97] op_sel:[0,1,0] op_sel_hi:[1,1,1] neg_lo:[1,0,0] neg_hi:[1,0,0]
	v_pk_fma_f32 v[96:97], v[128:129], v[74:75], v[96:97] op_sel_hi:[1,0,1] neg_lo:[1,0,0] neg_hi:[1,0,0]
	v_pk_fma_f32 v[96:97], v[130:131], v[74:75], v[96:97] op_sel:[0,1,0] op_sel_hi:[1,1,1] neg_lo:[1,0,0] neg_hi:[1,0,0]
	v_pk_fma_f32 v[96:97], v[132:133], v[76:77], v[96:97] op_sel_hi:[1,0,1] neg_lo:[1,0,0] neg_hi:[1,0,0]
	v_pk_fma_f32 v[96:97], v[134:135], v[76:77], v[96:97] op_sel:[0,1,0] op_sel_hi:[1,1,1] neg_lo:[1,0,0] neg_hi:[1,0,0]
	v_pk_fma_f32 v[96:97], v[144:145], v[78:79], v[96:97] op_sel_hi:[1,0,1] neg_lo:[1,0,0] neg_hi:[1,0,0]
	v_pk_fma_f32 v[96:97], v[146:147], v[78:79], v[96:97] op_sel:[0,1,0] op_sel_hi:[1,1,1] neg_lo:[1,0,0] neg_hi:[1,0,0]
	v_pk_fma_f32 v[96:97], v[148:149], v[80:81], v[96:97] op_sel_hi:[1,0,1] neg_lo:[1,0,0] neg_hi:[1,0,0]
	v_pk_fma_f32 v[96:97], v[150:151], v[80:81], v[96:97] op_sel:[0,1,0] op_sel_hi:[1,1,1] neg_lo:[1,0,0] neg_hi:[1,0,0]
	ds_read_b128 v[120:123], v32 offset:13984
	ds_read_b128 v[124:127], v32 offset:14000
	s_waitcnt lgkmcnt(2)
	v_pk_fma_f32 v[96:97], v[2:3], v[82:83], v[96:97] op_sel_hi:[1,0,1] neg_lo:[1,0,0] neg_hi:[1,0,0]
	v_pk_fma_f32 v[96:97], v[4:5], v[82:83], v[96:97] op_sel:[0,1,0] op_sel_hi:[1,1,1] neg_lo:[1,0,0] neg_hi:[1,0,0]
	v_pk_fma_f32 v[96:97], v[6:7], v[84:85], v[96:97] op_sel_hi:[1,0,1] neg_lo:[1,0,0] neg_hi:[1,0,0]
	v_pk_fma_f32 v[96:97], v[8:9], v[84:85], v[96:97] op_sel:[0,1,0] op_sel_hi:[1,1,1] neg_lo:[1,0,0] neg_hi:[1,0,0]
	v_pk_fma_f32 v[96:97], v[10:11], v[86:87], v[96:97] op_sel_hi:[1,0,1] neg_lo:[1,0,0] neg_hi:[1,0,0]
	v_pk_fma_f32 v[96:97], v[12:13], v[86:87], v[96:97] op_sel:[0,1,0] op_sel_hi:[1,1,1] neg_lo:[1,0,0] neg_hi:[1,0,0]
	v_pk_fma_f32 v[96:97], v[14:15], v[88:89], v[96:97] op_sel_hi:[1,0,1] neg_lo:[1,0,0] neg_hi:[1,0,0]
	v_pk_fma_f32 v[96:97], v[16:17], v[88:89], v[96:97] op_sel:[0,1,0] op_sel_hi:[1,1,1] neg_lo:[1,0,0] neg_hi:[1,0,0]
	v_pk_fma_f32 v[96:97], v[18:19], v[90:91], v[96:97] op_sel_hi:[1,0,1] neg_lo:[1,0,0] neg_hi:[1,0,0]
	v_pk_fma_f32 v[96:97], v[20:21], v[90:91], v[96:97] op_sel:[0,1,0] op_sel_hi:[1,1,1] neg_lo:[1,0,0] neg_hi:[1,0,0]
	v_pk_fma_f32 v[96:97], v[22:23], v[92:93], v[96:97] op_sel_hi:[1,0,1] neg_lo:[1,0,0] neg_hi:[1,0,0]
	v_pk_fma_f32 v[96:97], v[24:25], v[92:93], v[96:97] op_sel:[0,1,0] op_sel_hi:[1,1,1] neg_lo:[1,0,0] neg_hi:[1,0,0]
	ds_read_u16 v26, v30 offset:14144
	ds_read_u16 v27, v30 offset:14416
	ds_read_b64 v[28:29], v31 offset:208
	ds_read_b128 v[2:5], v32 offset:14144
	ds_read_b128 v[6:9], v32 offset:14160
	ds_read_b128 v[10:13], v32 offset:14176
	ds_read_b128 v[14:17], v32 offset:14192
	ds_read_b128 v[18:21], v32 offset:14208
	ds_read_b128 v[22:25], v32 offset:14224
	s_waitcnt lgkmcnt(9)
	v_pk_fma_f32 v[96:97], v[120:121], v[94:95], v[96:97] op_sel_hi:[1,0,1] neg_lo:[1,0,0] neg_hi:[1,0,0]
	v_pk_fma_f32 v[96:97], v[122:123], v[94:95], v[96:97] op_sel:[0,1,0] op_sel_hi:[1,1,1] neg_lo:[1,0,0] neg_hi:[1,0,0]
	v_fma_f32 v97, -v125, v96, v97
	ds_read_b128 v[120:123], v32 offset:14240
	ds_read_b128 v[124:127], v32 offset:14256
	ds_read_b128 v[128:131], v32 offset:14272
	ds_read_b128 v[132:135], v32 offset:14288
	ds_read_b128 v[144:147], v32 offset:14304
	ds_read_b128 v[148:151], v32 offset:14320
	s_waitcnt lgkmcnt(6)
	v_lshlrev_b32_e32 v26, 16, v26
	v_lshlrev_b32_e32 v27, 16, v27
	v_pk_mul_f32 v[106:107], v[26:27], v[28:29]
	v_pk_fma_f32 v[106:107], v[2:3], v[46:47], v[106:107] op_sel_hi:[1,0,1] neg_lo:[1,0,0] neg_hi:[1,0,0]
	v_pk_fma_f32 v[106:107], v[4:5], v[46:47], v[106:107] op_sel:[0,1,0] op_sel_hi:[1,1,1] neg_lo:[1,0,0] neg_hi:[1,0,0]
	v_pk_fma_f32 v[106:107], v[6:7], v[48:49], v[106:107] op_sel_hi:[1,0,1] neg_lo:[1,0,0] neg_hi:[1,0,0]
	v_pk_fma_f32 v[106:107], v[8:9], v[48:49], v[106:107] op_sel:[0,1,0] op_sel_hi:[1,1,1] neg_lo:[1,0,0] neg_hi:[1,0,0]
	v_pk_fma_f32 v[106:107], v[10:11], v[50:51], v[106:107] op_sel_hi:[1,0,1] neg_lo:[1,0,0] neg_hi:[1,0,0]
	v_pk_fma_f32 v[106:107], v[12:13], v[50:51], v[106:107] op_sel:[0,1,0] op_sel_hi:[1,1,1] neg_lo:[1,0,0] neg_hi:[1,0,0]
	v_pk_fma_f32 v[106:107], v[14:15], v[52:53], v[106:107] op_sel_hi:[1,0,1] neg_lo:[1,0,0] neg_hi:[1,0,0]
	v_pk_fma_f32 v[106:107], v[16:17], v[52:53], v[106:107] op_sel:[0,1,0] op_sel_hi:[1,1,1] neg_lo:[1,0,0] neg_hi:[1,0,0]
	v_pk_fma_f32 v[106:107], v[18:19], v[54:55], v[106:107] op_sel_hi:[1,0,1] neg_lo:[1,0,0] neg_hi:[1,0,0]
	v_pk_fma_f32 v[106:107], v[20:21], v[54:55], v[106:107] op_sel:[0,1,0] op_sel_hi:[1,1,1] neg_lo:[1,0,0] neg_hi:[1,0,0]
	v_pk_fma_f32 v[106:107], v[22:23], v[56:57], v[106:107] op_sel_hi:[1,0,1] neg_lo:[1,0,0] neg_hi:[1,0,0]
	v_pk_fma_f32 v[106:107], v[24:25], v[56:57], v[106:107] op_sel:[0,1,0] op_sel_hi:[1,1,1] neg_lo:[1,0,0] neg_hi:[1,0,0]
	ds_read_b128 v[2:5], v32 offset:14336
	ds_read_b128 v[6:9], v32 offset:14352
	ds_read_b128 v[10:13], v32 offset:14368
	ds_read_b128 v[14:17], v32 offset:14384
	ds_read_b128 v[18:21], v32 offset:14400
	ds_read_b128 v[22:25], v32 offset:14416
	s_waitcnt lgkmcnt(6)
	v_pk_fma_f32 v[106:107], v[120:121], v[58:59], v[106:107] op_sel_hi:[1,0,1] neg_lo:[1,0,0] neg_hi:[1,0,0]
	v_pk_fma_f32 v[106:107], v[122:123], v[58:59], v[106:107] op_sel:[0,1,0] op_sel_hi:[1,1,1] neg_lo:[1,0,0] neg_hi:[1,0,0]
	v_pk_fma_f32 v[106:107], v[124:125], v[60:61], v[106:107] op_sel_hi:[1,0,1] neg_lo:[1,0,0] neg_hi:[1,0,0]
	v_pk_fma_f32 v[106:107], v[126:127], v[60:61], v[106:107] op_sel:[0,1,0] op_sel_hi:[1,1,1] neg_lo:[1,0,0] neg_hi:[1,0,0]
	v_pk_fma_f32 v[106:107], v[128:129], v[62:63], v[106:107] op_sel_hi:[1,0,1] neg_lo:[1,0,0] neg_hi:[1,0,0]
	v_pk_fma_f32 v[106:107], v[130:131], v[62:63], v[106:107] op_sel:[0,1,0] op_sel_hi:[1,1,1] neg_lo:[1,0,0] neg_hi:[1,0,0]
	v_pk_fma_f32 v[106:107], v[132:133], v[64:65], v[106:107] op_sel_hi:[1,0,1] neg_lo:[1,0,0] neg_hi:[1,0,0]
	v_pk_fma_f32 v[106:107], v[134:135], v[64:65], v[106:107] op_sel:[0,1,0] op_sel_hi:[1,1,1] neg_lo:[1,0,0] neg_hi:[1,0,0]
	v_pk_fma_f32 v[106:107], v[144:145], v[66:67], v[106:107] op_sel_hi:[1,0,1] neg_lo:[1,0,0] neg_hi:[1,0,0]
	v_pk_fma_f32 v[106:107], v[146:147], v[66:67], v[106:107] op_sel:[0,1,0] op_sel_hi:[1,1,1] neg_lo:[1,0,0] neg_hi:[1,0,0]
	v_pk_fma_f32 v[106:107], v[148:149], v[68:69], v[106:107] op_sel_hi:[1,0,1] neg_lo:[1,0,0] neg_hi:[1,0,0]
	v_pk_fma_f32 v[106:107], v[150:151], v[68:69], v[106:107] op_sel:[0,1,0] op_sel_hi:[1,1,1] neg_lo:[1,0,0] neg_hi:[1,0,0]
	ds_read_b128 v[120:123], v32 offset:14432
	ds_read_b128 v[124:127], v32 offset:14448
	ds_read_b128 v[128:131], v32 offset:14464
	ds_read_b128 v[132:135], v32 offset:14480
	ds_read_b128 v[144:147], v32 offset:14496
	ds_read_b128 v[148:151], v32 offset:14512
	s_waitcnt lgkmcnt(6)
	v_pk_fma_f32 v[106:107], v[2:3], v[70:71], v[106:107] op_sel_hi:[1,0,1] neg_lo:[1,0,0] neg_hi:[1,0,0]
	v_pk_fma_f32 v[106:107], v[4:5], v[70:71], v[106:107] op_sel:[0,1,0] op_sel_hi:[1,1,1] neg_lo:[1,0,0] neg_hi:[1,0,0]
	v_pk_fma_f32 v[106:107], v[6:7], v[72:73], v[106:107] op_sel_hi:[1,0,1] neg_lo:[1,0,0] neg_hi:[1,0,0]
	v_pk_fma_f32 v[106:107], v[8:9], v[72:73], v[106:107] op_sel:[0,1,0] op_sel_hi:[1,1,1] neg_lo:[1,0,0] neg_hi:[1,0,0]
	v_pk_fma_f32 v[106:107], v[10:11], v[74:75], v[106:107] op_sel_hi:[1,0,1] neg_lo:[1,0,0] neg_hi:[1,0,0]
	v_pk_fma_f32 v[106:107], v[12:13], v[74:75], v[106:107] op_sel:[0,1,0] op_sel_hi:[1,1,1] neg_lo:[1,0,0] neg_hi:[1,0,0]
	v_pk_fma_f32 v[106:107], v[14:15], v[76:77], v[106:107] op_sel_hi:[1,0,1] neg_lo:[1,0,0] neg_hi:[1,0,0]
	v_pk_fma_f32 v[106:107], v[16:17], v[76:77], v[106:107] op_sel:[0,1,0] op_sel_hi:[1,1,1] neg_lo:[1,0,0] neg_hi:[1,0,0]
	v_pk_fma_f32 v[106:107], v[18:19], v[78:79], v[106:107] op_sel_hi:[1,0,1] neg_lo:[1,0,0] neg_hi:[1,0,0]
	v_pk_fma_f32 v[106:107], v[20:21], v[78:79], v[106:107] op_sel:[0,1,0] op_sel_hi:[1,1,1] neg_lo:[1,0,0] neg_hi:[1,0,0]
	v_pk_fma_f32 v[106:107], v[22:23], v[80:81], v[106:107] op_sel_hi:[1,0,1] neg_lo:[1,0,0] neg_hi:[1,0,0]
	v_pk_fma_f32 v[106:107], v[24:25], v[80:81], v[106:107] op_sel:[0,1,0] op_sel_hi:[1,1,1] neg_lo:[1,0,0] neg_hi:[1,0,0]
	ds_read_b128 v[2:5], v32 offset:14528
	ds_read_b128 v[6:9], v32 offset:14544
	ds_read_b128 v[10:13], v32 offset:14560
	s_waitcnt lgkmcnt(3)
	v_pk_fma_f32 v[106:107], v[120:121], v[82:83], v[106:107] op_sel_hi:[1,0,1] neg_lo:[1,0,0] neg_hi:[1,0,0]
	v_pk_fma_f32 v[106:107], v[122:123], v[82:83], v[106:107] op_sel:[0,1,0] op_sel_hi:[1,1,1] neg_lo:[1,0,0] neg_hi:[1,0,0]
	v_pk_fma_f32 v[106:107], v[124:125], v[84:85], v[106:107] op_sel_hi:[1,0,1] neg_lo:[1,0,0] neg_hi:[1,0,0]
	v_pk_fma_f32 v[106:107], v[126:127], v[84:85], v[106:107] op_sel:[0,1,0] op_sel_hi:[1,1,1] neg_lo:[1,0,0] neg_hi:[1,0,0]
	v_pk_fma_f32 v[106:107], v[128:129], v[86:87], v[106:107] op_sel_hi:[1,0,1] neg_lo:[1,0,0] neg_hi:[1,0,0]
	v_pk_fma_f32 v[106:107], v[130:131], v[86:87], v[106:107] op_sel:[0,1,0] op_sel_hi:[1,1,1] neg_lo:[1,0,0] neg_hi:[1,0,0]
	v_pk_fma_f32 v[106:107], v[132:133], v[88:89], v[106:107] op_sel_hi:[1,0,1] neg_lo:[1,0,0] neg_hi:[1,0,0]
	v_pk_fma_f32 v[106:107], v[134:135], v[88:89], v[106:107] op_sel:[0,1,0] op_sel_hi:[1,1,1] neg_lo:[1,0,0] neg_hi:[1,0,0]
	v_pk_fma_f32 v[106:107], v[144:145], v[90:91], v[106:107] op_sel_hi:[1,0,1] neg_lo:[1,0,0] neg_hi:[1,0,0]
	v_pk_fma_f32 v[106:107], v[146:147], v[90:91], v[106:107] op_sel:[0,1,0] op_sel_hi:[1,1,1] neg_lo:[1,0,0] neg_hi:[1,0,0]
	v_pk_fma_f32 v[106:107], v[148:149], v[92:93], v[106:107] op_sel_hi:[1,0,1] neg_lo:[1,0,0] neg_hi:[1,0,0]
	v_pk_fma_f32 v[106:107], v[150:151], v[92:93], v[106:107] op_sel:[0,1,0] op_sel_hi:[1,1,1] neg_lo:[1,0,0] neg_hi:[1,0,0]
	ds_read_u16 v152, v30 offset:14688
	ds_read_u16 v153, v30 offset:14960
	ds_read_b64 v[154:155], v31 offset:216
	ds_read_b128 v[120:123], v32 offset:14688
	ds_read_b128 v[124:127], v32 offset:14704
	ds_read_b128 v[128:131], v32 offset:14720
	ds_read_b128 v[132:135], v32 offset:14736
	ds_read_b128 v[144:147], v32 offset:14752
	ds_read_b128 v[148:151], v32 offset:14768
	s_waitcnt lgkmcnt(9)
	v_pk_fma_f32 v[106:107], v[2:3], v[94:95], v[106:107] op_sel_hi:[1,0,1] neg_lo:[1,0,0] neg_hi:[1,0,0]
	v_pk_fma_f32 v[106:107], v[4:5], v[94:95], v[106:107] op_sel:[0,1,0] op_sel_hi:[1,1,1] neg_lo:[1,0,0] neg_hi:[1,0,0]
	v_pk_fma_f32 v[106:107], v[6:7], v[96:97], v[106:107] op_sel_hi:[1,0,1] neg_lo:[1,0,0] neg_hi:[1,0,0]
	v_pk_fma_f32 v[106:107], v[8:9], v[96:97], v[106:107] op_sel:[0,1,0] op_sel_hi:[1,1,1] neg_lo:[1,0,0] neg_hi:[1,0,0]
	v_fma_f32 v107, -v11, v106, v107
	ds_read_b128 v[2:5], v32 offset:14784
	ds_read_b128 v[6:9], v32 offset:14800
	ds_read_b128 v[10:13], v32 offset:14816
	ds_read_b128 v[14:17], v32 offset:14832
	ds_read_b128 v[18:21], v32 offset:14848
	ds_read_b128 v[22:25], v32 offset:14864
	s_waitcnt lgkmcnt(6)
	v_lshlrev_b32_e32 v152, 16, v152
	v_lshlrev_b32_e32 v153, 16, v153
	v_pk_mul_f32 v[108:109], v[152:153], v[154:155]
	v_pk_fma_f32 v[108:109], v[120:121], v[46:47], v[108:109] op_sel_hi:[1,0,1] neg_lo:[1,0,0] neg_hi:[1,0,0]
	v_pk_fma_f32 v[108:109], v[122:123], v[46:47], v[108:109] op_sel:[0,1,0] op_sel_hi:[1,1,1] neg_lo:[1,0,0] neg_hi:[1,0,0]
	v_pk_fma_f32 v[108:109], v[124:125], v[48:49], v[108:109] op_sel_hi:[1,0,1] neg_lo:[1,0,0] neg_hi:[1,0,0]
	v_pk_fma_f32 v[108:109], v[126:127], v[48:49], v[108:109] op_sel:[0,1,0] op_sel_hi:[1,1,1] neg_lo:[1,0,0] neg_hi:[1,0,0]
	v_pk_fma_f32 v[108:109], v[128:129], v[50:51], v[108:109] op_sel_hi:[1,0,1] neg_lo:[1,0,0] neg_hi:[1,0,0]
	v_pk_fma_f32 v[108:109], v[130:131], v[50:51], v[108:109] op_sel:[0,1,0] op_sel_hi:[1,1,1] neg_lo:[1,0,0] neg_hi:[1,0,0]
	v_pk_fma_f32 v[108:109], v[132:133], v[52:53], v[108:109] op_sel_hi:[1,0,1] neg_lo:[1,0,0] neg_hi:[1,0,0]
	v_pk_fma_f32 v[108:109], v[134:135], v[52:53], v[108:109] op_sel:[0,1,0] op_sel_hi:[1,1,1] neg_lo:[1,0,0] neg_hi:[1,0,0]
	v_pk_fma_f32 v[108:109], v[144:145], v[54:55], v[108:109] op_sel_hi:[1,0,1] neg_lo:[1,0,0] neg_hi:[1,0,0]
	v_pk_fma_f32 v[108:109], v[146:147], v[54:55], v[108:109] op_sel:[0,1,0] op_sel_hi:[1,1,1] neg_lo:[1,0,0] neg_hi:[1,0,0]
	v_pk_fma_f32 v[108:109], v[148:149], v[56:57], v[108:109] op_sel_hi:[1,0,1] neg_lo:[1,0,0] neg_hi:[1,0,0]
	v_pk_fma_f32 v[108:109], v[150:151], v[56:57], v[108:109] op_sel:[0,1,0] op_sel_hi:[1,1,1] neg_lo:[1,0,0] neg_hi:[1,0,0]
	ds_read_b128 v[120:123], v32 offset:14880
	ds_read_b128 v[124:127], v32 offset:14896
	ds_read_b128 v[128:131], v32 offset:14912
	ds_read_b128 v[132:135], v32 offset:14928
	ds_read_b128 v[144:147], v32 offset:14944
	ds_read_b128 v[148:151], v32 offset:14960
	s_waitcnt lgkmcnt(6)
	v_pk_fma_f32 v[108:109], v[2:3], v[58:59], v[108:109] op_sel_hi:[1,0,1] neg_lo:[1,0,0] neg_hi:[1,0,0]
	v_pk_fma_f32 v[108:109], v[4:5], v[58:59], v[108:109] op_sel:[0,1,0] op_sel_hi:[1,1,1] neg_lo:[1,0,0] neg_hi:[1,0,0]
	v_pk_fma_f32 v[108:109], v[6:7], v[60:61], v[108:109] op_sel_hi:[1,0,1] neg_lo:[1,0,0] neg_hi:[1,0,0]
	v_pk_fma_f32 v[108:109], v[8:9], v[60:61], v[108:109] op_sel:[0,1,0] op_sel_hi:[1,1,1] neg_lo:[1,0,0] neg_hi:[1,0,0]
	v_pk_fma_f32 v[108:109], v[10:11], v[62:63], v[108:109] op_sel_hi:[1,0,1] neg_lo:[1,0,0] neg_hi:[1,0,0]
	v_pk_fma_f32 v[108:109], v[12:13], v[62:63], v[108:109] op_sel:[0,1,0] op_sel_hi:[1,1,1] neg_lo:[1,0,0] neg_hi:[1,0,0]
	v_pk_fma_f32 v[108:109], v[14:15], v[64:65], v[108:109] op_sel_hi:[1,0,1] neg_lo:[1,0,0] neg_hi:[1,0,0]
	v_pk_fma_f32 v[108:109], v[16:17], v[64:65], v[108:109] op_sel:[0,1,0] op_sel_hi:[1,1,1] neg_lo:[1,0,0] neg_hi:[1,0,0]
	v_pk_fma_f32 v[108:109], v[18:19], v[66:67], v[108:109] op_sel_hi:[1,0,1] neg_lo:[1,0,0] neg_hi:[1,0,0]
	v_pk_fma_f32 v[108:109], v[20:21], v[66:67], v[108:109] op_sel:[0,1,0] op_sel_hi:[1,1,1] neg_lo:[1,0,0] neg_hi:[1,0,0]
	v_pk_fma_f32 v[108:109], v[22:23], v[68:69], v[108:109] op_sel_hi:[1,0,1] neg_lo:[1,0,0] neg_hi:[1,0,0]
	v_pk_fma_f32 v[108:109], v[24:25], v[68:69], v[108:109] op_sel:[0,1,0] op_sel_hi:[1,1,1] neg_lo:[1,0,0] neg_hi:[1,0,0]
	ds_read_b128 v[2:5], v32 offset:14976
	ds_read_b128 v[6:9], v32 offset:14992
	ds_read_b128 v[10:13], v32 offset:15008
	ds_read_b128 v[14:17], v32 offset:15024
	ds_read_b128 v[18:21], v32 offset:15040
	ds_read_b128 v[22:25], v32 offset:15056
	s_waitcnt lgkmcnt(6)
	v_pk_fma_f32 v[108:109], v[120:121], v[70:71], v[108:109] op_sel_hi:[1,0,1] neg_lo:[1,0,0] neg_hi:[1,0,0]
	v_pk_fma_f32 v[108:109], v[122:123], v[70:71], v[108:109] op_sel:[0,1,0] op_sel_hi:[1,1,1] neg_lo:[1,0,0] neg_hi:[1,0,0]
	v_pk_fma_f32 v[108:109], v[124:125], v[72:73], v[108:109] op_sel_hi:[1,0,1] neg_lo:[1,0,0] neg_hi:[1,0,0]
	v_pk_fma_f32 v[108:109], v[126:127], v[72:73], v[108:109] op_sel:[0,1,0] op_sel_hi:[1,1,1] neg_lo:[1,0,0] neg_hi:[1,0,0]
	v_pk_fma_f32 v[108:109], v[128:129], v[74:75], v[108:109] op_sel_hi:[1,0,1] neg_lo:[1,0,0] neg_hi:[1,0,0]
	v_pk_fma_f32 v[108:109], v[130:131], v[74:75], v[108:109] op_sel:[0,1,0] op_sel_hi:[1,1,1] neg_lo:[1,0,0] neg_hi:[1,0,0]
	v_pk_fma_f32 v[108:109], v[132:133], v[76:77], v[108:109] op_sel_hi:[1,0,1] neg_lo:[1,0,0] neg_hi:[1,0,0]
	v_pk_fma_f32 v[108:109], v[134:135], v[76:77], v[108:109] op_sel:[0,1,0] op_sel_hi:[1,1,1] neg_lo:[1,0,0] neg_hi:[1,0,0]
	v_pk_fma_f32 v[108:109], v[144:145], v[78:79], v[108:109] op_sel_hi:[1,0,1] neg_lo:[1,0,0] neg_hi:[1,0,0]
	v_pk_fma_f32 v[108:109], v[146:147], v[78:79], v[108:109] op_sel:[0,1,0] op_sel_hi:[1,1,1] neg_lo:[1,0,0] neg_hi:[1,0,0]
	v_pk_fma_f32 v[108:109], v[148:149], v[80:81], v[108:109] op_sel_hi:[1,0,1] neg_lo:[1,0,0] neg_hi:[1,0,0]
	v_pk_fma_f32 v[108:109], v[150:151], v[80:81], v[108:109] op_sel:[0,1,0] op_sel_hi:[1,1,1] neg_lo:[1,0,0] neg_hi:[1,0,0]
	ds_read_b128 v[120:123], v32 offset:15072
	ds_read_b128 v[124:127], v32 offset:15088
	ds_read_b128 v[128:131], v32 offset:15104
	ds_read_b128 v[132:135], v32 offset:15120
	s_waitcnt lgkmcnt(4)
	v_pk_fma_f32 v[108:109], v[2:3], v[82:83], v[108:109] op_sel_hi:[1,0,1] neg_lo:[1,0,0] neg_hi:[1,0,0]
	v_pk_fma_f32 v[108:109], v[4:5], v[82:83], v[108:109] op_sel:[0,1,0] op_sel_hi:[1,1,1] neg_lo:[1,0,0] neg_hi:[1,0,0]
	v_pk_fma_f32 v[108:109], v[6:7], v[84:85], v[108:109] op_sel_hi:[1,0,1] neg_lo:[1,0,0] neg_hi:[1,0,0]
	v_pk_fma_f32 v[108:109], v[8:9], v[84:85], v[108:109] op_sel:[0,1,0] op_sel_hi:[1,1,1] neg_lo:[1,0,0] neg_hi:[1,0,0]
	v_pk_fma_f32 v[108:109], v[10:11], v[86:87], v[108:109] op_sel_hi:[1,0,1] neg_lo:[1,0,0] neg_hi:[1,0,0]
	v_pk_fma_f32 v[108:109], v[12:13], v[86:87], v[108:109] op_sel:[0,1,0] op_sel_hi:[1,1,1] neg_lo:[1,0,0] neg_hi:[1,0,0]
	v_pk_fma_f32 v[108:109], v[14:15], v[88:89], v[108:109] op_sel_hi:[1,0,1] neg_lo:[1,0,0] neg_hi:[1,0,0]
	v_pk_fma_f32 v[108:109], v[16:17], v[88:89], v[108:109] op_sel:[0,1,0] op_sel_hi:[1,1,1] neg_lo:[1,0,0] neg_hi:[1,0,0]
	v_pk_fma_f32 v[108:109], v[18:19], v[90:91], v[108:109] op_sel_hi:[1,0,1] neg_lo:[1,0,0] neg_hi:[1,0,0]
	v_pk_fma_f32 v[108:109], v[20:21], v[90:91], v[108:109] op_sel:[0,1,0] op_sel_hi:[1,1,1] neg_lo:[1,0,0] neg_hi:[1,0,0]
	v_pk_fma_f32 v[108:109], v[22:23], v[92:93], v[108:109] op_sel_hi:[1,0,1] neg_lo:[1,0,0] neg_hi:[1,0,0]
	v_pk_fma_f32 v[108:109], v[24:25], v[92:93], v[108:109] op_sel:[0,1,0] op_sel_hi:[1,1,1] neg_lo:[1,0,0] neg_hi:[1,0,0]
	ds_read_u16 v26, v30 offset:15232
	ds_read_u16 v27, v30 offset:15504
	ds_read_b64 v[28:29], v31 offset:224
	ds_read_b128 v[2:5], v32 offset:15232
	ds_read_b128 v[6:9], v32 offset:15248
	ds_read_b128 v[10:13], v32 offset:15264
	ds_read_b128 v[14:17], v32 offset:15280
	ds_read_b128 v[18:21], v32 offset:15296
	ds_read_b128 v[22:25], v32 offset:15312
	s_waitcnt lgkmcnt(9)
	v_pk_fma_f32 v[108:109], v[120:121], v[94:95], v[108:109] op_sel_hi:[1,0,1] neg_lo:[1,0,0] neg_hi:[1,0,0]
	v_pk_fma_f32 v[108:109], v[122:123], v[94:95], v[108:109] op_sel:[0,1,0] op_sel_hi:[1,1,1] neg_lo:[1,0,0] neg_hi:[1,0,0]
	v_pk_fma_f32 v[108:109], v[124:125], v[96:97], v[108:109] op_sel_hi:[1,0,1] neg_lo:[1,0,0] neg_hi:[1,0,0]
	v_pk_fma_f32 v[108:109], v[126:127], v[96:97], v[108:109] op_sel:[0,1,0] op_sel_hi:[1,1,1] neg_lo:[1,0,0] neg_hi:[1,0,0]
	v_pk_fma_f32 v[108:109], v[128:129], v[106:107], v[108:109] op_sel_hi:[1,0,1] neg_lo:[1,0,0] neg_hi:[1,0,0]
	v_pk_fma_f32 v[108:109], v[130:131], v[106:107], v[108:109] op_sel:[0,1,0] op_sel_hi:[1,1,1] neg_lo:[1,0,0] neg_hi:[1,0,0]
	v_fma_f32 v109, -v133, v108, v109
	ds_read_b128 v[120:123], v32 offset:15328
	ds_read_b128 v[124:127], v32 offset:15344
	ds_read_b128 v[128:131], v32 offset:15360
	ds_read_b128 v[132:135], v32 offset:15376
	ds_read_b128 v[144:147], v32 offset:15392
	ds_read_b128 v[148:151], v32 offset:15408
	s_waitcnt lgkmcnt(6)
	v_lshlrev_b32_e32 v26, 16, v26
	v_lshlrev_b32_e32 v27, 16, v27
	v_pk_mul_f32 v[110:111], v[26:27], v[28:29]
	v_pk_fma_f32 v[110:111], v[2:3], v[46:47], v[110:111] op_sel_hi:[1,0,1] neg_lo:[1,0,0] neg_hi:[1,0,0]
	v_pk_fma_f32 v[110:111], v[4:5], v[46:47], v[110:111] op_sel:[0,1,0] op_sel_hi:[1,1,1] neg_lo:[1,0,0] neg_hi:[1,0,0]
	v_pk_fma_f32 v[110:111], v[6:7], v[48:49], v[110:111] op_sel_hi:[1,0,1] neg_lo:[1,0,0] neg_hi:[1,0,0]
	v_pk_fma_f32 v[110:111], v[8:9], v[48:49], v[110:111] op_sel:[0,1,0] op_sel_hi:[1,1,1] neg_lo:[1,0,0] neg_hi:[1,0,0]
	v_pk_fma_f32 v[110:111], v[10:11], v[50:51], v[110:111] op_sel_hi:[1,0,1] neg_lo:[1,0,0] neg_hi:[1,0,0]
	v_pk_fma_f32 v[110:111], v[12:13], v[50:51], v[110:111] op_sel:[0,1,0] op_sel_hi:[1,1,1] neg_lo:[1,0,0] neg_hi:[1,0,0]
	v_pk_fma_f32 v[110:111], v[14:15], v[52:53], v[110:111] op_sel_hi:[1,0,1] neg_lo:[1,0,0] neg_hi:[1,0,0]
	v_pk_fma_f32 v[110:111], v[16:17], v[52:53], v[110:111] op_sel:[0,1,0] op_sel_hi:[1,1,1] neg_lo:[1,0,0] neg_hi:[1,0,0]
	v_pk_fma_f32 v[110:111], v[18:19], v[54:55], v[110:111] op_sel_hi:[1,0,1] neg_lo:[1,0,0] neg_hi:[1,0,0]
	v_pk_fma_f32 v[110:111], v[20:21], v[54:55], v[110:111] op_sel:[0,1,0] op_sel_hi:[1,1,1] neg_lo:[1,0,0] neg_hi:[1,0,0]
	v_pk_fma_f32 v[110:111], v[22:23], v[56:57], v[110:111] op_sel_hi:[1,0,1] neg_lo:[1,0,0] neg_hi:[1,0,0]
	v_pk_fma_f32 v[110:111], v[24:25], v[56:57], v[110:111] op_sel:[0,1,0] op_sel_hi:[1,1,1] neg_lo:[1,0,0] neg_hi:[1,0,0]
	ds_read_b128 v[2:5], v32 offset:15424
	ds_read_b128 v[6:9], v32 offset:15440
	ds_read_b128 v[10:13], v32 offset:15456
	ds_read_b128 v[14:17], v32 offset:15472
	ds_read_b128 v[18:21], v32 offset:15488
	ds_read_b128 v[22:25], v32 offset:15504
	s_waitcnt lgkmcnt(6)
	v_pk_fma_f32 v[110:111], v[120:121], v[58:59], v[110:111] op_sel_hi:[1,0,1] neg_lo:[1,0,0] neg_hi:[1,0,0]
	v_pk_fma_f32 v[110:111], v[122:123], v[58:59], v[110:111] op_sel:[0,1,0] op_sel_hi:[1,1,1] neg_lo:[1,0,0] neg_hi:[1,0,0]
	v_pk_fma_f32 v[110:111], v[124:125], v[60:61], v[110:111] op_sel_hi:[1,0,1] neg_lo:[1,0,0] neg_hi:[1,0,0]
	v_pk_fma_f32 v[110:111], v[126:127], v[60:61], v[110:111] op_sel:[0,1,0] op_sel_hi:[1,1,1] neg_lo:[1,0,0] neg_hi:[1,0,0]
	v_pk_fma_f32 v[110:111], v[128:129], v[62:63], v[110:111] op_sel_hi:[1,0,1] neg_lo:[1,0,0] neg_hi:[1,0,0]
	v_pk_fma_f32 v[110:111], v[130:131], v[62:63], v[110:111] op_sel:[0,1,0] op_sel_hi:[1,1,1] neg_lo:[1,0,0] neg_hi:[1,0,0]
	v_pk_fma_f32 v[110:111], v[132:133], v[64:65], v[110:111] op_sel_hi:[1,0,1] neg_lo:[1,0,0] neg_hi:[1,0,0]
	v_pk_fma_f32 v[110:111], v[134:135], v[64:65], v[110:111] op_sel:[0,1,0] op_sel_hi:[1,1,1] neg_lo:[1,0,0] neg_hi:[1,0,0]
	v_pk_fma_f32 v[110:111], v[144:145], v[66:67], v[110:111] op_sel_hi:[1,0,1] neg_lo:[1,0,0] neg_hi:[1,0,0]
	v_pk_fma_f32 v[110:111], v[146:147], v[66:67], v[110:111] op_sel:[0,1,0] op_sel_hi:[1,1,1] neg_lo:[1,0,0] neg_hi:[1,0,0]
	v_pk_fma_f32 v[110:111], v[148:149], v[68:69], v[110:111] op_sel_hi:[1,0,1] neg_lo:[1,0,0] neg_hi:[1,0,0]
	v_pk_fma_f32 v[110:111], v[150:151], v[68:69], v[110:111] op_sel:[0,1,0] op_sel_hi:[1,1,1] neg_lo:[1,0,0] neg_hi:[1,0,0]
	ds_read_b128 v[120:123], v32 offset:15520
	ds_read_b128 v[124:127], v32 offset:15536
	ds_read_b128 v[128:131], v32 offset:15552
	ds_read_b128 v[132:135], v32 offset:15568
	ds_read_b128 v[144:147], v32 offset:15584
	ds_read_b128 v[148:151], v32 offset:15600
	s_waitcnt lgkmcnt(6)
	v_pk_fma_f32 v[110:111], v[2:3], v[70:71], v[110:111] op_sel_hi:[1,0,1] neg_lo:[1,0,0] neg_hi:[1,0,0]
	v_pk_fma_f32 v[110:111], v[4:5], v[70:71], v[110:111] op_sel:[0,1,0] op_sel_hi:[1,1,1] neg_lo:[1,0,0] neg_hi:[1,0,0]
	v_pk_fma_f32 v[110:111], v[6:7], v[72:73], v[110:111] op_sel_hi:[1,0,1] neg_lo:[1,0,0] neg_hi:[1,0,0]
	v_pk_fma_f32 v[110:111], v[8:9], v[72:73], v[110:111] op_sel:[0,1,0] op_sel_hi:[1,1,1] neg_lo:[1,0,0] neg_hi:[1,0,0]
	v_pk_fma_f32 v[110:111], v[10:11], v[74:75], v[110:111] op_sel_hi:[1,0,1] neg_lo:[1,0,0] neg_hi:[1,0,0]
	v_pk_fma_f32 v[110:111], v[12:13], v[74:75], v[110:111] op_sel:[0,1,0] op_sel_hi:[1,1,1] neg_lo:[1,0,0] neg_hi:[1,0,0]
	v_pk_fma_f32 v[110:111], v[14:15], v[76:77], v[110:111] op_sel_hi:[1,0,1] neg_lo:[1,0,0] neg_hi:[1,0,0]
	v_pk_fma_f32 v[110:111], v[16:17], v[76:77], v[110:111] op_sel:[0,1,0] op_sel_hi:[1,1,1] neg_lo:[1,0,0] neg_hi:[1,0,0]
	v_pk_fma_f32 v[110:111], v[18:19], v[78:79], v[110:111] op_sel_hi:[1,0,1] neg_lo:[1,0,0] neg_hi:[1,0,0]
	v_pk_fma_f32 v[110:111], v[20:21], v[78:79], v[110:111] op_sel:[0,1,0] op_sel_hi:[1,1,1] neg_lo:[1,0,0] neg_hi:[1,0,0]
	v_pk_fma_f32 v[110:111], v[22:23], v[80:81], v[110:111] op_sel_hi:[1,0,1] neg_lo:[1,0,0] neg_hi:[1,0,0]
	v_pk_fma_f32 v[110:111], v[24:25], v[80:81], v[110:111] op_sel:[0,1,0] op_sel_hi:[1,1,1] neg_lo:[1,0,0] neg_hi:[1,0,0]
	ds_read_b128 v[2:5], v32 offset:15616
	ds_read_b128 v[6:9], v32 offset:15632
	ds_read_b128 v[10:13], v32 offset:15648
	ds_read_b128 v[14:17], v32 offset:15664
	ds_read_b128 v[18:21], v32 offset:15680
	s_waitcnt lgkmcnt(5)
	v_pk_fma_f32 v[110:111], v[120:121], v[82:83], v[110:111] op_sel_hi:[1,0,1] neg_lo:[1,0,0] neg_hi:[1,0,0]
	v_pk_fma_f32 v[110:111], v[122:123], v[82:83], v[110:111] op_sel:[0,1,0] op_sel_hi:[1,1,1] neg_lo:[1,0,0] neg_hi:[1,0,0]
	v_pk_fma_f32 v[110:111], v[124:125], v[84:85], v[110:111] op_sel_hi:[1,0,1] neg_lo:[1,0,0] neg_hi:[1,0,0]
	v_pk_fma_f32 v[110:111], v[126:127], v[84:85], v[110:111] op_sel:[0,1,0] op_sel_hi:[1,1,1] neg_lo:[1,0,0] neg_hi:[1,0,0]
	v_pk_fma_f32 v[110:111], v[128:129], v[86:87], v[110:111] op_sel_hi:[1,0,1] neg_lo:[1,0,0] neg_hi:[1,0,0]
	v_pk_fma_f32 v[110:111], v[130:131], v[86:87], v[110:111] op_sel:[0,1,0] op_sel_hi:[1,1,1] neg_lo:[1,0,0] neg_hi:[1,0,0]
	v_pk_fma_f32 v[110:111], v[132:133], v[88:89], v[110:111] op_sel_hi:[1,0,1] neg_lo:[1,0,0] neg_hi:[1,0,0]
	v_pk_fma_f32 v[110:111], v[134:135], v[88:89], v[110:111] op_sel:[0,1,0] op_sel_hi:[1,1,1] neg_lo:[1,0,0] neg_hi:[1,0,0]
	v_pk_fma_f32 v[110:111], v[144:145], v[90:91], v[110:111] op_sel_hi:[1,0,1] neg_lo:[1,0,0] neg_hi:[1,0,0]
	v_pk_fma_f32 v[110:111], v[146:147], v[90:91], v[110:111] op_sel:[0,1,0] op_sel_hi:[1,1,1] neg_lo:[1,0,0] neg_hi:[1,0,0]
	v_pk_fma_f32 v[110:111], v[148:149], v[92:93], v[110:111] op_sel_hi:[1,0,1] neg_lo:[1,0,0] neg_hi:[1,0,0]
	v_pk_fma_f32 v[110:111], v[150:151], v[92:93], v[110:111] op_sel:[0,1,0] op_sel_hi:[1,1,1] neg_lo:[1,0,0] neg_hi:[1,0,0]
	ds_read_u16 v152, v30 offset:15776
	ds_read_u16 v153, v30 offset:16048
	ds_read_b64 v[154:155], v31 offset:232
	ds_read_b128 v[120:123], v32 offset:15776
	ds_read_b128 v[124:127], v32 offset:15792
	ds_read_b128 v[128:131], v32 offset:15808
	ds_read_b128 v[132:135], v32 offset:15824
	ds_read_b128 v[144:147], v32 offset:15840
	ds_read_b128 v[148:151], v32 offset:15856
	s_waitcnt lgkmcnt(9)
	v_pk_fma_f32 v[110:111], v[2:3], v[94:95], v[110:111] op_sel_hi:[1,0,1] neg_lo:[1,0,0] neg_hi:[1,0,0]
	v_pk_fma_f32 v[110:111], v[4:5], v[94:95], v[110:111] op_sel:[0,1,0] op_sel_hi:[1,1,1] neg_lo:[1,0,0] neg_hi:[1,0,0]
	v_pk_fma_f32 v[110:111], v[6:7], v[96:97], v[110:111] op_sel_hi:[1,0,1] neg_lo:[1,0,0] neg_hi:[1,0,0]
	v_pk_fma_f32 v[110:111], v[8:9], v[96:97], v[110:111] op_sel:[0,1,0] op_sel_hi:[1,1,1] neg_lo:[1,0,0] neg_hi:[1,0,0]
	v_pk_fma_f32 v[110:111], v[10:11], v[106:107], v[110:111] op_sel_hi:[1,0,1] neg_lo:[1,0,0] neg_hi:[1,0,0]
	v_pk_fma_f32 v[110:111], v[12:13], v[106:107], v[110:111] op_sel:[0,1,0] op_sel_hi:[1,1,1] neg_lo:[1,0,0] neg_hi:[1,0,0]
	v_pk_fma_f32 v[110:111], v[14:15], v[108:109], v[110:111] op_sel_hi:[1,0,1] neg_lo:[1,0,0] neg_hi:[1,0,0]
	v_pk_fma_f32 v[110:111], v[16:17], v[108:109], v[110:111] op_sel:[0,1,0] op_sel_hi:[1,1,1] neg_lo:[1,0,0] neg_hi:[1,0,0]
	v_fma_f32 v111, -v19, v110, v111
	ds_read_b128 v[2:5], v32 offset:15872
	ds_read_b128 v[6:9], v32 offset:15888
	ds_read_b128 v[10:13], v32 offset:15904
	ds_read_b128 v[14:17], v32 offset:15920
	ds_read_b128 v[18:21], v32 offset:15936
	ds_read_b128 v[22:25], v32 offset:15952
	s_waitcnt lgkmcnt(6)
	v_lshlrev_b32_e32 v152, 16, v152
	v_lshlrev_b32_e32 v153, 16, v153
	v_pk_mul_f32 v[112:113], v[152:153], v[154:155]
	v_pk_fma_f32 v[112:113], v[120:121], v[46:47], v[112:113] op_sel_hi:[1,0,1] neg_lo:[1,0,0] neg_hi:[1,0,0]
	v_pk_fma_f32 v[112:113], v[122:123], v[46:47], v[112:113] op_sel:[0,1,0] op_sel_hi:[1,1,1] neg_lo:[1,0,0] neg_hi:[1,0,0]
	v_pk_fma_f32 v[112:113], v[124:125], v[48:49], v[112:113] op_sel_hi:[1,0,1] neg_lo:[1,0,0] neg_hi:[1,0,0]
	v_pk_fma_f32 v[112:113], v[126:127], v[48:49], v[112:113] op_sel:[0,1,0] op_sel_hi:[1,1,1] neg_lo:[1,0,0] neg_hi:[1,0,0]
	v_pk_fma_f32 v[112:113], v[128:129], v[50:51], v[112:113] op_sel_hi:[1,0,1] neg_lo:[1,0,0] neg_hi:[1,0,0]
	v_pk_fma_f32 v[112:113], v[130:131], v[50:51], v[112:113] op_sel:[0,1,0] op_sel_hi:[1,1,1] neg_lo:[1,0,0] neg_hi:[1,0,0]
	v_pk_fma_f32 v[112:113], v[132:133], v[52:53], v[112:113] op_sel_hi:[1,0,1] neg_lo:[1,0,0] neg_hi:[1,0,0]
	v_pk_fma_f32 v[112:113], v[134:135], v[52:53], v[112:113] op_sel:[0,1,0] op_sel_hi:[1,1,1] neg_lo:[1,0,0] neg_hi:[1,0,0]
	v_pk_fma_f32 v[112:113], v[144:145], v[54:55], v[112:113] op_sel_hi:[1,0,1] neg_lo:[1,0,0] neg_hi:[1,0,0]
	v_pk_fma_f32 v[112:113], v[146:147], v[54:55], v[112:113] op_sel:[0,1,0] op_sel_hi:[1,1,1] neg_lo:[1,0,0] neg_hi:[1,0,0]
	v_pk_fma_f32 v[112:113], v[148:149], v[56:57], v[112:113] op_sel_hi:[1,0,1] neg_lo:[1,0,0] neg_hi:[1,0,0]
	v_pk_fma_f32 v[112:113], v[150:151], v[56:57], v[112:113] op_sel:[0,1,0] op_sel_hi:[1,1,1] neg_lo:[1,0,0] neg_hi:[1,0,0]
	ds_read_b128 v[120:123], v32 offset:15968
	ds_read_b128 v[124:127], v32 offset:15984
	ds_read_b128 v[128:131], v32 offset:16000
	ds_read_b128 v[132:135], v32 offset:16016
	ds_read_b128 v[144:147], v32 offset:16032
	ds_read_b128 v[148:151], v32 offset:16048
	s_waitcnt lgkmcnt(6)
	v_pk_fma_f32 v[112:113], v[2:3], v[58:59], v[112:113] op_sel_hi:[1,0,1] neg_lo:[1,0,0] neg_hi:[1,0,0]
	v_pk_fma_f32 v[112:113], v[4:5], v[58:59], v[112:113] op_sel:[0,1,0] op_sel_hi:[1,1,1] neg_lo:[1,0,0] neg_hi:[1,0,0]
	v_pk_fma_f32 v[112:113], v[6:7], v[60:61], v[112:113] op_sel_hi:[1,0,1] neg_lo:[1,0,0] neg_hi:[1,0,0]
	v_pk_fma_f32 v[112:113], v[8:9], v[60:61], v[112:113] op_sel:[0,1,0] op_sel_hi:[1,1,1] neg_lo:[1,0,0] neg_hi:[1,0,0]
	v_pk_fma_f32 v[112:113], v[10:11], v[62:63], v[112:113] op_sel_hi:[1,0,1] neg_lo:[1,0,0] neg_hi:[1,0,0]
	v_pk_fma_f32 v[112:113], v[12:13], v[62:63], v[112:113] op_sel:[0,1,0] op_sel_hi:[1,1,1] neg_lo:[1,0,0] neg_hi:[1,0,0]
	v_pk_fma_f32 v[112:113], v[14:15], v[64:65], v[112:113] op_sel_hi:[1,0,1] neg_lo:[1,0,0] neg_hi:[1,0,0]
	v_pk_fma_f32 v[112:113], v[16:17], v[64:65], v[112:113] op_sel:[0,1,0] op_sel_hi:[1,1,1] neg_lo:[1,0,0] neg_hi:[1,0,0]
	v_pk_fma_f32 v[112:113], v[18:19], v[66:67], v[112:113] op_sel_hi:[1,0,1] neg_lo:[1,0,0] neg_hi:[1,0,0]
	v_pk_fma_f32 v[112:113], v[20:21], v[66:67], v[112:113] op_sel:[0,1,0] op_sel_hi:[1,1,1] neg_lo:[1,0,0] neg_hi:[1,0,0]
	v_pk_fma_f32 v[112:113], v[22:23], v[68:69], v[112:113] op_sel_hi:[1,0,1] neg_lo:[1,0,0] neg_hi:[1,0,0]
	v_pk_fma_f32 v[112:113], v[24:25], v[68:69], v[112:113] op_sel:[0,1,0] op_sel_hi:[1,1,1] neg_lo:[1,0,0] neg_hi:[1,0,0]
	ds_read_b128 v[2:5], v32 offset:16064
	ds_read_b128 v[6:9], v32 offset:16080
	ds_read_b128 v[10:13], v32 offset:16096
	ds_read_b128 v[14:17], v32 offset:16112
	ds_read_b128 v[18:21], v32 offset:16128
	ds_read_b128 v[22:25], v32 offset:16144
	s_waitcnt lgkmcnt(6)
	v_pk_fma_f32 v[112:113], v[120:121], v[70:71], v[112:113] op_sel_hi:[1,0,1] neg_lo:[1,0,0] neg_hi:[1,0,0]
	v_pk_fma_f32 v[112:113], v[122:123], v[70:71], v[112:113] op_sel:[0,1,0] op_sel_hi:[1,1,1] neg_lo:[1,0,0] neg_hi:[1,0,0]
	v_pk_fma_f32 v[112:113], v[124:125], v[72:73], v[112:113] op_sel_hi:[1,0,1] neg_lo:[1,0,0] neg_hi:[1,0,0]
	v_pk_fma_f32 v[112:113], v[126:127], v[72:73], v[112:113] op_sel:[0,1,0] op_sel_hi:[1,1,1] neg_lo:[1,0,0] neg_hi:[1,0,0]
	v_pk_fma_f32 v[112:113], v[128:129], v[74:75], v[112:113] op_sel_hi:[1,0,1] neg_lo:[1,0,0] neg_hi:[1,0,0]
	v_pk_fma_f32 v[112:113], v[130:131], v[74:75], v[112:113] op_sel:[0,1,0] op_sel_hi:[1,1,1] neg_lo:[1,0,0] neg_hi:[1,0,0]
	v_pk_fma_f32 v[112:113], v[132:133], v[76:77], v[112:113] op_sel_hi:[1,0,1] neg_lo:[1,0,0] neg_hi:[1,0,0]
	v_pk_fma_f32 v[112:113], v[134:135], v[76:77], v[112:113] op_sel:[0,1,0] op_sel_hi:[1,1,1] neg_lo:[1,0,0] neg_hi:[1,0,0]
	v_pk_fma_f32 v[112:113], v[144:145], v[78:79], v[112:113] op_sel_hi:[1,0,1] neg_lo:[1,0,0] neg_hi:[1,0,0]
	v_pk_fma_f32 v[112:113], v[146:147], v[78:79], v[112:113] op_sel:[0,1,0] op_sel_hi:[1,1,1] neg_lo:[1,0,0] neg_hi:[1,0,0]
	v_pk_fma_f32 v[112:113], v[148:149], v[80:81], v[112:113] op_sel_hi:[1,0,1] neg_lo:[1,0,0] neg_hi:[1,0,0]
	v_pk_fma_f32 v[112:113], v[150:151], v[80:81], v[112:113] op_sel:[0,1,0] op_sel_hi:[1,1,1] neg_lo:[1,0,0] neg_hi:[1,0,0]
	ds_read_b128 v[120:123], v32 offset:16160
	ds_read_b128 v[124:127], v32 offset:16176
	ds_read_b128 v[128:131], v32 offset:16192
	ds_read_b128 v[132:135], v32 offset:16208
	ds_read_b128 v[144:147], v32 offset:16224
	ds_read_b128 v[148:151], v32 offset:16240
	s_waitcnt lgkmcnt(6)
	v_pk_fma_f32 v[112:113], v[2:3], v[82:83], v[112:113] op_sel_hi:[1,0,1] neg_lo:[1,0,0] neg_hi:[1,0,0]
	v_pk_fma_f32 v[112:113], v[4:5], v[82:83], v[112:113] op_sel:[0,1,0] op_sel_hi:[1,1,1] neg_lo:[1,0,0] neg_hi:[1,0,0]
	v_pk_fma_f32 v[112:113], v[6:7], v[84:85], v[112:113] op_sel_hi:[1,0,1] neg_lo:[1,0,0] neg_hi:[1,0,0]
	v_pk_fma_f32 v[112:113], v[8:9], v[84:85], v[112:113] op_sel:[0,1,0] op_sel_hi:[1,1,1] neg_lo:[1,0,0] neg_hi:[1,0,0]
	v_pk_fma_f32 v[112:113], v[10:11], v[86:87], v[112:113] op_sel_hi:[1,0,1] neg_lo:[1,0,0] neg_hi:[1,0,0]
	v_pk_fma_f32 v[112:113], v[12:13], v[86:87], v[112:113] op_sel:[0,1,0] op_sel_hi:[1,1,1] neg_lo:[1,0,0] neg_hi:[1,0,0]
	v_pk_fma_f32 v[112:113], v[14:15], v[88:89], v[112:113] op_sel_hi:[1,0,1] neg_lo:[1,0,0] neg_hi:[1,0,0]
	v_pk_fma_f32 v[112:113], v[16:17], v[88:89], v[112:113] op_sel:[0,1,0] op_sel_hi:[1,1,1] neg_lo:[1,0,0] neg_hi:[1,0,0]
	v_pk_fma_f32 v[112:113], v[18:19], v[90:91], v[112:113] op_sel_hi:[1,0,1] neg_lo:[1,0,0] neg_hi:[1,0,0]
	v_pk_fma_f32 v[112:113], v[20:21], v[90:91], v[112:113] op_sel:[0,1,0] op_sel_hi:[1,1,1] neg_lo:[1,0,0] neg_hi:[1,0,0]
	v_pk_fma_f32 v[112:113], v[22:23], v[92:93], v[112:113] op_sel_hi:[1,0,1] neg_lo:[1,0,0] neg_hi:[1,0,0]
	v_pk_fma_f32 v[112:113], v[24:25], v[92:93], v[112:113] op_sel:[0,1,0] op_sel_hi:[1,1,1] neg_lo:[1,0,0] neg_hi:[1,0,0]
	ds_read_u16 v26, v30 offset:16320
	ds_read_u16 v27, v30 offset:16592
	ds_read_b64 v[28:29], v31 offset:240
	ds_read_b128 v[2:5], v32 offset:16320
	ds_read_b128 v[6:9], v32 offset:16336
	ds_read_b128 v[10:13], v32 offset:16352
	ds_read_b128 v[14:17], v32 offset:16368
	ds_read_b128 v[18:21], v32 offset:16384
	ds_read_b128 v[22:25], v32 offset:16400
	s_waitcnt lgkmcnt(9)
	v_pk_fma_f32 v[112:113], v[120:121], v[94:95], v[112:113] op_sel_hi:[1,0,1] neg_lo:[1,0,0] neg_hi:[1,0,0]
	v_pk_fma_f32 v[112:113], v[122:123], v[94:95], v[112:113] op_sel:[0,1,0] op_sel_hi:[1,1,1] neg_lo:[1,0,0] neg_hi:[1,0,0]
	v_pk_fma_f32 v[112:113], v[124:125], v[96:97], v[112:113] op_sel_hi:[1,0,1] neg_lo:[1,0,0] neg_hi:[1,0,0]
	v_pk_fma_f32 v[112:113], v[126:127], v[96:97], v[112:113] op_sel:[0,1,0] op_sel_hi:[1,1,1] neg_lo:[1,0,0] neg_hi:[1,0,0]
	v_pk_fma_f32 v[112:113], v[128:129], v[106:107], v[112:113] op_sel_hi:[1,0,1] neg_lo:[1,0,0] neg_hi:[1,0,0]
	v_pk_fma_f32 v[112:113], v[130:131], v[106:107], v[112:113] op_sel:[0,1,0] op_sel_hi:[1,1,1] neg_lo:[1,0,0] neg_hi:[1,0,0]
	v_pk_fma_f32 v[112:113], v[132:133], v[108:109], v[112:113] op_sel_hi:[1,0,1] neg_lo:[1,0,0] neg_hi:[1,0,0]
	v_pk_fma_f32 v[112:113], v[134:135], v[108:109], v[112:113] op_sel:[0,1,0] op_sel_hi:[1,1,1] neg_lo:[1,0,0] neg_hi:[1,0,0]
	v_pk_fma_f32 v[112:113], v[144:145], v[110:111], v[112:113] op_sel_hi:[1,0,1] neg_lo:[1,0,0] neg_hi:[1,0,0]
	v_pk_fma_f32 v[112:113], v[146:147], v[110:111], v[112:113] op_sel:[0,1,0] op_sel_hi:[1,1,1] neg_lo:[1,0,0] neg_hi:[1,0,0]
	v_fma_f32 v113, -v149, v112, v113
	ds_read_b128 v[120:123], v32 offset:16416
	ds_read_b128 v[124:127], v32 offset:16432
	ds_read_b128 v[128:131], v32 offset:16448
	ds_read_b128 v[132:135], v32 offset:16464
	ds_read_b128 v[144:147], v32 offset:16480
	ds_read_b128 v[148:151], v32 offset:16496
	s_waitcnt lgkmcnt(6)
	v_lshlrev_b32_e32 v26, 16, v26
	v_lshlrev_b32_e32 v27, 16, v27
	v_pk_mul_f32 v[114:115], v[26:27], v[28:29]
	v_pk_fma_f32 v[114:115], v[2:3], v[46:47], v[114:115] op_sel_hi:[1,0,1] neg_lo:[1,0,0] neg_hi:[1,0,0]
	v_pk_fma_f32 v[114:115], v[4:5], v[46:47], v[114:115] op_sel:[0,1,0] op_sel_hi:[1,1,1] neg_lo:[1,0,0] neg_hi:[1,0,0]
	v_pk_fma_f32 v[114:115], v[6:7], v[48:49], v[114:115] op_sel_hi:[1,0,1] neg_lo:[1,0,0] neg_hi:[1,0,0]
	v_pk_fma_f32 v[114:115], v[8:9], v[48:49], v[114:115] op_sel:[0,1,0] op_sel_hi:[1,1,1] neg_lo:[1,0,0] neg_hi:[1,0,0]
	v_pk_fma_f32 v[114:115], v[10:11], v[50:51], v[114:115] op_sel_hi:[1,0,1] neg_lo:[1,0,0] neg_hi:[1,0,0]
	v_pk_fma_f32 v[114:115], v[12:13], v[50:51], v[114:115] op_sel:[0,1,0] op_sel_hi:[1,1,1] neg_lo:[1,0,0] neg_hi:[1,0,0]
	v_pk_fma_f32 v[114:115], v[14:15], v[52:53], v[114:115] op_sel_hi:[1,0,1] neg_lo:[1,0,0] neg_hi:[1,0,0]
	v_pk_fma_f32 v[114:115], v[16:17], v[52:53], v[114:115] op_sel:[0,1,0] op_sel_hi:[1,1,1] neg_lo:[1,0,0] neg_hi:[1,0,0]
	v_pk_fma_f32 v[114:115], v[18:19], v[54:55], v[114:115] op_sel_hi:[1,0,1] neg_lo:[1,0,0] neg_hi:[1,0,0]
	v_pk_fma_f32 v[114:115], v[20:21], v[54:55], v[114:115] op_sel:[0,1,0] op_sel_hi:[1,1,1] neg_lo:[1,0,0] neg_hi:[1,0,0]
	v_pk_fma_f32 v[114:115], v[22:23], v[56:57], v[114:115] op_sel_hi:[1,0,1] neg_lo:[1,0,0] neg_hi:[1,0,0]
	v_pk_fma_f32 v[114:115], v[24:25], v[56:57], v[114:115] op_sel:[0,1,0] op_sel_hi:[1,1,1] neg_lo:[1,0,0] neg_hi:[1,0,0]
	ds_read_b128 v[2:5], v32 offset:16512
	ds_read_b128 v[6:9], v32 offset:16528
	ds_read_b128 v[10:13], v32 offset:16544
	ds_read_b128 v[14:17], v32 offset:16560
	ds_read_b128 v[18:21], v32 offset:16576
	ds_read_b128 v[22:25], v32 offset:16592
	s_waitcnt lgkmcnt(6)
	v_pk_fma_f32 v[114:115], v[120:121], v[58:59], v[114:115] op_sel_hi:[1,0,1] neg_lo:[1,0,0] neg_hi:[1,0,0]
	v_pk_fma_f32 v[114:115], v[122:123], v[58:59], v[114:115] op_sel:[0,1,0] op_sel_hi:[1,1,1] neg_lo:[1,0,0] neg_hi:[1,0,0]
	v_pk_fma_f32 v[114:115], v[124:125], v[60:61], v[114:115] op_sel_hi:[1,0,1] neg_lo:[1,0,0] neg_hi:[1,0,0]
	v_pk_fma_f32 v[114:115], v[126:127], v[60:61], v[114:115] op_sel:[0,1,0] op_sel_hi:[1,1,1] neg_lo:[1,0,0] neg_hi:[1,0,0]
	v_pk_fma_f32 v[114:115], v[128:129], v[62:63], v[114:115] op_sel_hi:[1,0,1] neg_lo:[1,0,0] neg_hi:[1,0,0]
	v_pk_fma_f32 v[114:115], v[130:131], v[62:63], v[114:115] op_sel:[0,1,0] op_sel_hi:[1,1,1] neg_lo:[1,0,0] neg_hi:[1,0,0]
	v_pk_fma_f32 v[114:115], v[132:133], v[64:65], v[114:115] op_sel_hi:[1,0,1] neg_lo:[1,0,0] neg_hi:[1,0,0]
	v_pk_fma_f32 v[114:115], v[134:135], v[64:65], v[114:115] op_sel:[0,1,0] op_sel_hi:[1,1,1] neg_lo:[1,0,0] neg_hi:[1,0,0]
	v_pk_fma_f32 v[114:115], v[144:145], v[66:67], v[114:115] op_sel_hi:[1,0,1] neg_lo:[1,0,0] neg_hi:[1,0,0]
	v_pk_fma_f32 v[114:115], v[146:147], v[66:67], v[114:115] op_sel:[0,1,0] op_sel_hi:[1,1,1] neg_lo:[1,0,0] neg_hi:[1,0,0]
	v_pk_fma_f32 v[114:115], v[148:149], v[68:69], v[114:115] op_sel_hi:[1,0,1] neg_lo:[1,0,0] neg_hi:[1,0,0]
	v_pk_fma_f32 v[114:115], v[150:151], v[68:69], v[114:115] op_sel:[0,1,0] op_sel_hi:[1,1,1] neg_lo:[1,0,0] neg_hi:[1,0,0]
	ds_read_b128 v[120:123], v32 offset:16608
	ds_read_b128 v[124:127], v32 offset:16624
	ds_read_b128 v[128:131], v32 offset:16640
	ds_read_b128 v[132:135], v32 offset:16656
	ds_read_b128 v[144:147], v32 offset:16672
	ds_read_b128 v[148:151], v32 offset:16688
	s_waitcnt lgkmcnt(6)
	v_pk_fma_f32 v[114:115], v[2:3], v[70:71], v[114:115] op_sel_hi:[1,0,1] neg_lo:[1,0,0] neg_hi:[1,0,0]
	v_pk_fma_f32 v[114:115], v[4:5], v[70:71], v[114:115] op_sel:[0,1,0] op_sel_hi:[1,1,1] neg_lo:[1,0,0] neg_hi:[1,0,0]
	v_pk_fma_f32 v[114:115], v[6:7], v[72:73], v[114:115] op_sel_hi:[1,0,1] neg_lo:[1,0,0] neg_hi:[1,0,0]
	v_pk_fma_f32 v[114:115], v[8:9], v[72:73], v[114:115] op_sel:[0,1,0] op_sel_hi:[1,1,1] neg_lo:[1,0,0] neg_hi:[1,0,0]
	v_pk_fma_f32 v[114:115], v[10:11], v[74:75], v[114:115] op_sel_hi:[1,0,1] neg_lo:[1,0,0] neg_hi:[1,0,0]
	v_pk_fma_f32 v[114:115], v[12:13], v[74:75], v[114:115] op_sel:[0,1,0] op_sel_hi:[1,1,1] neg_lo:[1,0,0] neg_hi:[1,0,0]
	v_pk_fma_f32 v[114:115], v[14:15], v[76:77], v[114:115] op_sel_hi:[1,0,1] neg_lo:[1,0,0] neg_hi:[1,0,0]
	v_pk_fma_f32 v[114:115], v[16:17], v[76:77], v[114:115] op_sel:[0,1,0] op_sel_hi:[1,1,1] neg_lo:[1,0,0] neg_hi:[1,0,0]
	v_pk_fma_f32 v[114:115], v[18:19], v[78:79], v[114:115] op_sel_hi:[1,0,1] neg_lo:[1,0,0] neg_hi:[1,0,0]
	v_pk_fma_f32 v[114:115], v[20:21], v[78:79], v[114:115] op_sel:[0,1,0] op_sel_hi:[1,1,1] neg_lo:[1,0,0] neg_hi:[1,0,0]
	v_pk_fma_f32 v[114:115], v[22:23], v[80:81], v[114:115] op_sel_hi:[1,0,1] neg_lo:[1,0,0] neg_hi:[1,0,0]
	v_pk_fma_f32 v[114:115], v[24:25], v[80:81], v[114:115] op_sel:[0,1,0] op_sel_hi:[1,1,1] neg_lo:[1,0,0] neg_hi:[1,0,0]
	ds_read_b128 v[2:5], v32 offset:16704
	ds_read_b128 v[6:9], v32 offset:16720
	ds_read_b128 v[10:13], v32 offset:16736
	ds_read_b128 v[14:17], v32 offset:16752
	ds_read_b128 v[18:21], v32 offset:16768
	ds_read_b128 v[22:25], v32 offset:16784
	s_waitcnt lgkmcnt(6)
	v_pk_fma_f32 v[114:115], v[120:121], v[82:83], v[114:115] op_sel_hi:[1,0,1] neg_lo:[1,0,0] neg_hi:[1,0,0]
	v_pk_fma_f32 v[114:115], v[122:123], v[82:83], v[114:115] op_sel:[0,1,0] op_sel_hi:[1,1,1] neg_lo:[1,0,0] neg_hi:[1,0,0]
	v_pk_fma_f32 v[114:115], v[124:125], v[84:85], v[114:115] op_sel_hi:[1,0,1] neg_lo:[1,0,0] neg_hi:[1,0,0]
	v_pk_fma_f32 v[114:115], v[126:127], v[84:85], v[114:115] op_sel:[0,1,0] op_sel_hi:[1,1,1] neg_lo:[1,0,0] neg_hi:[1,0,0]
	v_pk_fma_f32 v[114:115], v[128:129], v[86:87], v[114:115] op_sel_hi:[1,0,1] neg_lo:[1,0,0] neg_hi:[1,0,0]
	v_pk_fma_f32 v[114:115], v[130:131], v[86:87], v[114:115] op_sel:[0,1,0] op_sel_hi:[1,1,1] neg_lo:[1,0,0] neg_hi:[1,0,0]
	v_pk_fma_f32 v[114:115], v[132:133], v[88:89], v[114:115] op_sel_hi:[1,0,1] neg_lo:[1,0,0] neg_hi:[1,0,0]
	v_pk_fma_f32 v[114:115], v[134:135], v[88:89], v[114:115] op_sel:[0,1,0] op_sel_hi:[1,1,1] neg_lo:[1,0,0] neg_hi:[1,0,0]
	v_pk_fma_f32 v[114:115], v[144:145], v[90:91], v[114:115] op_sel_hi:[1,0,1] neg_lo:[1,0,0] neg_hi:[1,0,0]
	v_pk_fma_f32 v[114:115], v[146:147], v[90:91], v[114:115] op_sel:[0,1,0] op_sel_hi:[1,1,1] neg_lo:[1,0,0] neg_hi:[1,0,0]
	v_pk_fma_f32 v[114:115], v[148:149], v[92:93], v[114:115] op_sel_hi:[1,0,1] neg_lo:[1,0,0] neg_hi:[1,0,0]
	v_pk_fma_f32 v[114:115], v[150:151], v[92:93], v[114:115] op_sel:[0,1,0] op_sel_hi:[1,1,1] neg_lo:[1,0,0] neg_hi:[1,0,0]
	ds_read_b128 v[120:123], v32 offset:16800
	s_waitcnt lgkmcnt(1)
	v_pk_fma_f32 v[114:115], v[2:3], v[94:95], v[114:115] op_sel_hi:[1,0,1] neg_lo:[1,0,0] neg_hi:[1,0,0]
	v_pk_fma_f32 v[114:115], v[4:5], v[94:95], v[114:115] op_sel:[0,1,0] op_sel_hi:[1,1,1] neg_lo:[1,0,0] neg_hi:[1,0,0]
	v_pk_fma_f32 v[114:115], v[6:7], v[96:97], v[114:115] op_sel_hi:[1,0,1] neg_lo:[1,0,0] neg_hi:[1,0,0]
	v_pk_fma_f32 v[114:115], v[8:9], v[96:97], v[114:115] op_sel:[0,1,0] op_sel_hi:[1,1,1] neg_lo:[1,0,0] neg_hi:[1,0,0]
	v_pk_fma_f32 v[114:115], v[10:11], v[106:107], v[114:115] op_sel_hi:[1,0,1] neg_lo:[1,0,0] neg_hi:[1,0,0]
	v_pk_fma_f32 v[114:115], v[12:13], v[106:107], v[114:115] op_sel:[0,1,0] op_sel_hi:[1,1,1] neg_lo:[1,0,0] neg_hi:[1,0,0]
	v_pk_fma_f32 v[114:115], v[14:15], v[108:109], v[114:115] op_sel_hi:[1,0,1] neg_lo:[1,0,0] neg_hi:[1,0,0]
	v_pk_fma_f32 v[114:115], v[16:17], v[108:109], v[114:115] op_sel:[0,1,0] op_sel_hi:[1,1,1] neg_lo:[1,0,0] neg_hi:[1,0,0]
	v_pk_fma_f32 v[114:115], v[18:19], v[110:111], v[114:115] op_sel_hi:[1,0,1] neg_lo:[1,0,0] neg_hi:[1,0,0]
	v_pk_fma_f32 v[114:115], v[20:21], v[110:111], v[114:115] op_sel:[0,1,0] op_sel_hi:[1,1,1] neg_lo:[1,0,0] neg_hi:[1,0,0]
	v_pk_fma_f32 v[114:115], v[22:23], v[112:113], v[114:115] op_sel_hi:[1,0,1] neg_lo:[1,0,0] neg_hi:[1,0,0]
	v_pk_fma_f32 v[114:115], v[24:25], v[112:113], v[114:115] op_sel:[0,1,0] op_sel_hi:[1,1,1] neg_lo:[1,0,0] neg_hi:[1,0,0]
	ds_read_u16 v26, v30 offset:16864
	ds_read_u16 v27, v30 offset:17136
	ds_read_b64 v[28:29], v31 offset:248
	ds_read_b128 v[2:5], v32 offset:16864
	ds_read_b128 v[6:9], v32 offset:16880
	ds_read_b128 v[10:13], v32 offset:16896
	ds_read_b128 v[14:17], v32 offset:16912
	ds_read_b128 v[18:21], v32 offset:16928
	ds_read_b128 v[22:25], v32 offset:16944
	s_waitcnt lgkmcnt(9)
	v_fma_f32 v115, -v121, v114, v115
	ds_read_b128 v[120:123], v32 offset:16960
	ds_read_b128 v[124:127], v32 offset:16976
	ds_read_b128 v[128:131], v32 offset:16992
	ds_read_b128 v[132:135], v32 offset:17008
	ds_read_b128 v[144:147], v32 offset:17024
	ds_read_b128 v[148:151], v32 offset:17040
	s_waitcnt lgkmcnt(6)
	v_lshlrev_b32_e32 v26, 16, v26
	v_lshlrev_b32_e32 v27, 16, v27
	v_pk_mul_f32 v[116:117], v[26:27], v[28:29]
	v_pk_fma_f32 v[116:117], v[2:3], v[46:47], v[116:117] op_sel_hi:[1,0,1] neg_lo:[1,0,0] neg_hi:[1,0,0]
	v_pk_fma_f32 v[116:117], v[4:5], v[46:47], v[116:117] op_sel:[0,1,0] op_sel_hi:[1,1,1] neg_lo:[1,0,0] neg_hi:[1,0,0]
	v_pk_fma_f32 v[116:117], v[6:7], v[48:49], v[116:117] op_sel_hi:[1,0,1] neg_lo:[1,0,0] neg_hi:[1,0,0]
	v_pk_fma_f32 v[116:117], v[8:9], v[48:49], v[116:117] op_sel:[0,1,0] op_sel_hi:[1,1,1] neg_lo:[1,0,0] neg_hi:[1,0,0]
	v_pk_fma_f32 v[116:117], v[10:11], v[50:51], v[116:117] op_sel_hi:[1,0,1] neg_lo:[1,0,0] neg_hi:[1,0,0]
	v_pk_fma_f32 v[116:117], v[12:13], v[50:51], v[116:117] op_sel:[0,1,0] op_sel_hi:[1,1,1] neg_lo:[1,0,0] neg_hi:[1,0,0]
	v_pk_fma_f32 v[116:117], v[14:15], v[52:53], v[116:117] op_sel_hi:[1,0,1] neg_lo:[1,0,0] neg_hi:[1,0,0]
	v_pk_fma_f32 v[116:117], v[16:17], v[52:53], v[116:117] op_sel:[0,1,0] op_sel_hi:[1,1,1] neg_lo:[1,0,0] neg_hi:[1,0,0]
	v_pk_fma_f32 v[116:117], v[18:19], v[54:55], v[116:117] op_sel_hi:[1,0,1] neg_lo:[1,0,0] neg_hi:[1,0,0]
	v_pk_fma_f32 v[116:117], v[20:21], v[54:55], v[116:117] op_sel:[0,1,0] op_sel_hi:[1,1,1] neg_lo:[1,0,0] neg_hi:[1,0,0]
	v_pk_fma_f32 v[116:117], v[22:23], v[56:57], v[116:117] op_sel_hi:[1,0,1] neg_lo:[1,0,0] neg_hi:[1,0,0]
	v_pk_fma_f32 v[116:117], v[24:25], v[56:57], v[116:117] op_sel:[0,1,0] op_sel_hi:[1,1,1] neg_lo:[1,0,0] neg_hi:[1,0,0]
	ds_read_b128 v[2:5], v32 offset:17056
	ds_read_b128 v[6:9], v32 offset:17072
	ds_read_b128 v[10:13], v32 offset:17088
	ds_read_b128 v[14:17], v32 offset:17104
	ds_read_b128 v[18:21], v32 offset:17120
	ds_read_b128 v[22:25], v32 offset:17136
	s_waitcnt lgkmcnt(6)
	v_pk_fma_f32 v[116:117], v[120:121], v[58:59], v[116:117] op_sel_hi:[1,0,1] neg_lo:[1,0,0] neg_hi:[1,0,0]
	v_pk_fma_f32 v[116:117], v[122:123], v[58:59], v[116:117] op_sel:[0,1,0] op_sel_hi:[1,1,1] neg_lo:[1,0,0] neg_hi:[1,0,0]
	v_pk_fma_f32 v[116:117], v[124:125], v[60:61], v[116:117] op_sel_hi:[1,0,1] neg_lo:[1,0,0] neg_hi:[1,0,0]
	v_pk_fma_f32 v[116:117], v[126:127], v[60:61], v[116:117] op_sel:[0,1,0] op_sel_hi:[1,1,1] neg_lo:[1,0,0] neg_hi:[1,0,0]
	v_pk_fma_f32 v[116:117], v[128:129], v[62:63], v[116:117] op_sel_hi:[1,0,1] neg_lo:[1,0,0] neg_hi:[1,0,0]
	v_pk_fma_f32 v[116:117], v[130:131], v[62:63], v[116:117] op_sel:[0,1,0] op_sel_hi:[1,1,1] neg_lo:[1,0,0] neg_hi:[1,0,0]
	v_pk_fma_f32 v[116:117], v[132:133], v[64:65], v[116:117] op_sel_hi:[1,0,1] neg_lo:[1,0,0] neg_hi:[1,0,0]
	v_pk_fma_f32 v[116:117], v[134:135], v[64:65], v[116:117] op_sel:[0,1,0] op_sel_hi:[1,1,1] neg_lo:[1,0,0] neg_hi:[1,0,0]
	v_pk_fma_f32 v[116:117], v[144:145], v[66:67], v[116:117] op_sel_hi:[1,0,1] neg_lo:[1,0,0] neg_hi:[1,0,0]
	v_pk_fma_f32 v[116:117], v[146:147], v[66:67], v[116:117] op_sel:[0,1,0] op_sel_hi:[1,1,1] neg_lo:[1,0,0] neg_hi:[1,0,0]
	v_pk_fma_f32 v[116:117], v[148:149], v[68:69], v[116:117] op_sel_hi:[1,0,1] neg_lo:[1,0,0] neg_hi:[1,0,0]
	v_pk_fma_f32 v[116:117], v[150:151], v[68:69], v[116:117] op_sel:[0,1,0] op_sel_hi:[1,1,1] neg_lo:[1,0,0] neg_hi:[1,0,0]
	ds_read_b128 v[120:123], v32 offset:17152
	ds_read_b128 v[124:127], v32 offset:17168
	ds_read_b128 v[128:131], v32 offset:17184
	ds_read_b128 v[132:135], v32 offset:17200
	ds_read_b128 v[144:147], v32 offset:17216
	ds_read_b128 v[148:151], v32 offset:17232
	s_waitcnt lgkmcnt(6)
	v_pk_fma_f32 v[116:117], v[2:3], v[70:71], v[116:117] op_sel_hi:[1,0,1] neg_lo:[1,0,0] neg_hi:[1,0,0]
	v_pk_fma_f32 v[116:117], v[4:5], v[70:71], v[116:117] op_sel:[0,1,0] op_sel_hi:[1,1,1] neg_lo:[1,0,0] neg_hi:[1,0,0]
	v_pk_fma_f32 v[116:117], v[6:7], v[72:73], v[116:117] op_sel_hi:[1,0,1] neg_lo:[1,0,0] neg_hi:[1,0,0]
	v_pk_fma_f32 v[116:117], v[8:9], v[72:73], v[116:117] op_sel:[0,1,0] op_sel_hi:[1,1,1] neg_lo:[1,0,0] neg_hi:[1,0,0]
	v_pk_fma_f32 v[116:117], v[10:11], v[74:75], v[116:117] op_sel_hi:[1,0,1] neg_lo:[1,0,0] neg_hi:[1,0,0]
	v_pk_fma_f32 v[116:117], v[12:13], v[74:75], v[116:117] op_sel:[0,1,0] op_sel_hi:[1,1,1] neg_lo:[1,0,0] neg_hi:[1,0,0]
	v_pk_fma_f32 v[116:117], v[14:15], v[76:77], v[116:117] op_sel_hi:[1,0,1] neg_lo:[1,0,0] neg_hi:[1,0,0]
	v_pk_fma_f32 v[116:117], v[16:17], v[76:77], v[116:117] op_sel:[0,1,0] op_sel_hi:[1,1,1] neg_lo:[1,0,0] neg_hi:[1,0,0]
	v_pk_fma_f32 v[116:117], v[18:19], v[78:79], v[116:117] op_sel_hi:[1,0,1] neg_lo:[1,0,0] neg_hi:[1,0,0]
	v_pk_fma_f32 v[116:117], v[20:21], v[78:79], v[116:117] op_sel:[0,1,0] op_sel_hi:[1,1,1] neg_lo:[1,0,0] neg_hi:[1,0,0]
	v_pk_fma_f32 v[116:117], v[22:23], v[80:81], v[116:117] op_sel_hi:[1,0,1] neg_lo:[1,0,0] neg_hi:[1,0,0]
	v_pk_fma_f32 v[116:117], v[24:25], v[80:81], v[116:117] op_sel:[0,1,0] op_sel_hi:[1,1,1] neg_lo:[1,0,0] neg_hi:[1,0,0]
	ds_read_b128 v[2:5], v32 offset:17248
	ds_read_b128 v[6:9], v32 offset:17264
	ds_read_b128 v[10:13], v32 offset:17280
	ds_read_b128 v[14:17], v32 offset:17296
	ds_read_b128 v[18:21], v32 offset:17312
	ds_read_b128 v[22:25], v32 offset:17328
	s_waitcnt lgkmcnt(6)
	v_pk_fma_f32 v[116:117], v[120:121], v[82:83], v[116:117] op_sel_hi:[1,0,1] neg_lo:[1,0,0] neg_hi:[1,0,0]
	v_pk_fma_f32 v[116:117], v[122:123], v[82:83], v[116:117] op_sel:[0,1,0] op_sel_hi:[1,1,1] neg_lo:[1,0,0] neg_hi:[1,0,0]
	v_pk_fma_f32 v[116:117], v[124:125], v[84:85], v[116:117] op_sel_hi:[1,0,1] neg_lo:[1,0,0] neg_hi:[1,0,0]
	v_pk_fma_f32 v[116:117], v[126:127], v[84:85], v[116:117] op_sel:[0,1,0] op_sel_hi:[1,1,1] neg_lo:[1,0,0] neg_hi:[1,0,0]
	v_pk_fma_f32 v[116:117], v[128:129], v[86:87], v[116:117] op_sel_hi:[1,0,1] neg_lo:[1,0,0] neg_hi:[1,0,0]
	v_pk_fma_f32 v[116:117], v[130:131], v[86:87], v[116:117] op_sel:[0,1,0] op_sel_hi:[1,1,1] neg_lo:[1,0,0] neg_hi:[1,0,0]
	v_pk_fma_f32 v[116:117], v[132:133], v[88:89], v[116:117] op_sel_hi:[1,0,1] neg_lo:[1,0,0] neg_hi:[1,0,0]
	v_pk_fma_f32 v[116:117], v[134:135], v[88:89], v[116:117] op_sel:[0,1,0] op_sel_hi:[1,1,1] neg_lo:[1,0,0] neg_hi:[1,0,0]
	v_pk_fma_f32 v[116:117], v[144:145], v[90:91], v[116:117] op_sel_hi:[1,0,1] neg_lo:[1,0,0] neg_hi:[1,0,0]
	v_pk_fma_f32 v[116:117], v[146:147], v[90:91], v[116:117] op_sel:[0,1,0] op_sel_hi:[1,1,1] neg_lo:[1,0,0] neg_hi:[1,0,0]
	v_pk_fma_f32 v[116:117], v[148:149], v[92:93], v[116:117] op_sel_hi:[1,0,1] neg_lo:[1,0,0] neg_hi:[1,0,0]
	v_pk_fma_f32 v[116:117], v[150:151], v[92:93], v[116:117] op_sel:[0,1,0] op_sel_hi:[1,1,1] neg_lo:[1,0,0] neg_hi:[1,0,0]
	ds_read_b128 v[120:123], v32 offset:17344
	ds_read_b128 v[124:127], v32 offset:17360
	s_waitcnt lgkmcnt(2)
	v_pk_fma_f32 v[116:117], v[2:3], v[94:95], v[116:117] op_sel_hi:[1,0,1] neg_lo:[1,0,0] neg_hi:[1,0,0]
	v_pk_fma_f32 v[116:117], v[4:5], v[94:95], v[116:117] op_sel:[0,1,0] op_sel_hi:[1,1,1] neg_lo:[1,0,0] neg_hi:[1,0,0]
	v_pk_fma_f32 v[116:117], v[6:7], v[96:97], v[116:117] op_sel_hi:[1,0,1] neg_lo:[1,0,0] neg_hi:[1,0,0]
	v_pk_fma_f32 v[116:117], v[8:9], v[96:97], v[116:117] op_sel:[0,1,0] op_sel_hi:[1,1,1] neg_lo:[1,0,0] neg_hi:[1,0,0]
	v_pk_fma_f32 v[116:117], v[10:11], v[106:107], v[116:117] op_sel_hi:[1,0,1] neg_lo:[1,0,0] neg_hi:[1,0,0]
	v_pk_fma_f32 v[116:117], v[12:13], v[106:107], v[116:117] op_sel:[0,1,0] op_sel_hi:[1,1,1] neg_lo:[1,0,0] neg_hi:[1,0,0]
	v_pk_fma_f32 v[116:117], v[14:15], v[108:109], v[116:117] op_sel_hi:[1,0,1] neg_lo:[1,0,0] neg_hi:[1,0,0]
	v_pk_fma_f32 v[116:117], v[16:17], v[108:109], v[116:117] op_sel:[0,1,0] op_sel_hi:[1,1,1] neg_lo:[1,0,0] neg_hi:[1,0,0]
	v_pk_fma_f32 v[116:117], v[18:19], v[110:111], v[116:117] op_sel_hi:[1,0,1] neg_lo:[1,0,0] neg_hi:[1,0,0]
	v_pk_fma_f32 v[116:117], v[20:21], v[110:111], v[116:117] op_sel:[0,1,0] op_sel_hi:[1,1,1] neg_lo:[1,0,0] neg_hi:[1,0,0]
	v_pk_fma_f32 v[116:117], v[22:23], v[112:113], v[116:117] op_sel_hi:[1,0,1] neg_lo:[1,0,0] neg_hi:[1,0,0]
	v_pk_fma_f32 v[116:117], v[24:25], v[112:113], v[116:117] op_sel:[0,1,0] op_sel_hi:[1,1,1] neg_lo:[1,0,0] neg_hi:[1,0,0]
	s_waitcnt lgkmcnt(0)
	v_pk_fma_f32 v[116:117], v[120:121], v[114:115], v[116:117] op_sel_hi:[1,0,1] neg_lo:[1,0,0] neg_hi:[1,0,0]
	v_pk_fma_f32 v[116:117], v[122:123], v[114:115], v[116:117] op_sel:[0,1,0] op_sel_hi:[1,1,1] neg_lo:[1,0,0] neg_hi:[1,0,0]
	v_fma_f32 v117, -v125, v116, v117
	s_and_saveexec_b64 s[56:57], s[4:5]
	ds_add_u32 v169, v170 offset:36352
	s_or_b64 exec, exec, s[56:57]
	ds_read_b32 v2, v169 offset:36352
	s_add_i32 s7, s3, 16
	s_waitcnt lgkmcnt(0)
	v_cmp_gt_u32_e32 vcc, s7, v2
	s_and_saveexec_b64 s[56:57], vcc
	s_cbranch_execz .LBB0_519
	s_mov_b64 s[58:59], 0

.LBB0_519:
	s_or_b64 exec, exec, s[56:57]
	v_lshl_add_u32 v34, v102, 1, v143
	v_add_u32_e32 v35, 0xb000, v34
	v_cvt_pk_bf16_f32 v33, v46, v47
	ds_write_b16 v34, v33 offset:45056
	ds_write_b16_d16_hi v34, v33 offset:45584
	v_cvt_pk_bf16_f32 v36, v48, v49
	ds_write_b16 v34, v36 offset:46112
	ds_write_b16_d16_hi v34, v36 offset:46640
	v_cvt_pk_bf16_f32 v33, v50, v51
	ds_write_b16 v34, v33 offset:47168
	ds_write_b16_d16_hi v34, v33 offset:47696
	v_cvt_pk_bf16_f32 v36, v52, v53
	ds_write_b16 v34, v36 offset:48224
	ds_write_b16_d16_hi v34, v36 offset:48752
	v_cvt_pk_bf16_f32 v33, v54, v55
	ds_write_b16 v34, v33 offset:49280
	ds_write_b16_d16_hi v34, v33 offset:49808
	v_cvt_pk_bf16_f32 v36, v56, v57
	ds_write_b16 v34, v36 offset:50336
	ds_write_b16_d16_hi v34, v36 offset:50864
	v_cvt_pk_bf16_f32 v33, v58, v59
	ds_write_b16 v34, v33 offset:51392
	ds_write_b16_d16_hi v34, v33 offset:51920
	v_cvt_pk_bf16_f32 v36, v60, v61
	ds_write_b16 v34, v36 offset:52448
	ds_write_b16_d16_hi v34, v36 offset:52976
	v_cvt_pk_bf16_f32 v33, v62, v63
	ds_write_b16 v34, v33 offset:53504
	ds_write_b16_d16_hi v34, v33 offset:54032
	v_cvt_pk_bf16_f32 v36, v64, v65
	ds_write_b16 v34, v36 offset:54560
	ds_write_b16_d16_hi v34, v36 offset:55088
	v_cvt_pk_bf16_f32 v33, v66, v67
	ds_write_b16 v34, v33 offset:55616
	ds_write_b16_d16_hi v34, v33 offset:56144
	v_cvt_pk_bf16_f32 v36, v68, v69
	ds_write_b16 v34, v36 offset:56672
	ds_write_b16_d16_hi v34, v36 offset:57200
	v_cvt_pk_bf16_f32 v33, v70, v71
	ds_write_b16 v34, v33 offset:57728
	ds_write_b16_d16_hi v34, v33 offset:58256
	v_cvt_pk_bf16_f32 v36, v72, v73
	ds_write_b16 v34, v36 offset:58784
	ds_write_b16_d16_hi v34, v36 offset:59312
	v_cvt_pk_bf16_f32 v33, v74, v75
	ds_write_b16 v34, v33 offset:59840
	ds_write_b16_d16_hi v34, v33 offset:60368
	v_cvt_pk_bf16_f32 v36, v76, v77
	ds_write_b16 v34, v36 offset:60896
	ds_write_b16_d16_hi v34, v36 offset:61424
	v_cvt_pk_bf16_f32 v33, v78, v79
	ds_write_b16 v34, v33 offset:61952
	ds_write_b16_d16_hi v34, v33 offset:62480
	v_cvt_pk_bf16_f32 v36, v80, v81
	ds_write_b16 v34, v36 offset:63008
	ds_write_b16_d16_hi v34, v36 offset:63536
	v_cvt_pk_bf16_f32 v33, v82, v83
	ds_write_b16 v34, v33 offset:64064
	ds_write_b16_d16_hi v34, v33 offset:64592
	v_cvt_pk_bf16_f32 v36, v84, v85
	ds_write_b16 v34, v36 offset:65120
	ds_write_b16_d16_hi v35, v36 offset:20592
	v_cvt_pk_bf16_f32 v33, v86, v87
	ds_write_b16 v35, v33 offset:21120
	ds_write_b16_d16_hi v35, v33 offset:21648
	v_cvt_pk_bf16_f32 v36, v88, v89
	ds_write_b16 v35, v36 offset:22176
	ds_write_b16_d16_hi v35, v36 offset:22704
	v_cvt_pk_bf16_f32 v33, v90, v91
	ds_write_b16 v35, v33 offset:23232
	ds_write_b16_d16_hi v35, v33 offset:23760
	v_cvt_pk_bf16_f32 v36, v92, v93
	ds_write_b16 v35, v36 offset:24288
	ds_write_b16_d16_hi v35, v36 offset:24816
	v_cvt_pk_bf16_f32 v33, v94, v95
	ds_write_b16 v35, v33 offset:25344
	ds_write_b16_d16_hi v35, v33 offset:25872
	v_cvt_pk_bf16_f32 v36, v96, v97
	ds_write_b16 v35, v36 offset:26400
	ds_write_b16_d16_hi v35, v36 offset:26928
	v_cvt_pk_bf16_f32 v33, v106, v107
	ds_write_b16 v35, v33 offset:27456
	ds_write_b16_d16_hi v35, v33 offset:27984
	v_cvt_pk_bf16_f32 v36, v108, v109
	ds_write_b16 v35, v36 offset:28512
	ds_write_b16_d16_hi v35, v36 offset:29040
	v_cvt_pk_bf16_f32 v33, v110, v111
	ds_write_b16 v35, v33 offset:29568
	ds_write_b16_d16_hi v35, v33 offset:30096
	v_cvt_pk_bf16_f32 v36, v112, v113
	ds_write_b16 v35, v36 offset:30624
	ds_write_b16_d16_hi v35, v36 offset:31152
	v_cvt_pk_bf16_f32 v33, v114, v115
	ds_write_b16 v35, v33 offset:31680
	ds_write_b16_d16_hi v35, v33 offset:32208
	v_cvt_pk_bf16_f32 v36, v116, v117
	ds_write_b16 v35, v36 offset:32736
	ds_write_b16_d16_hi v35, v36 offset:33264
	s_waitcnt lgkmcnt(0)
	s_and_saveexec_b64 s[56:57], s[4:5]
	ds_add_u32 v169, v170 offset:36352
	s_or_b64 exec, exec, s[56:57]
	ds_read_b32 v2, v169 offset:36352
	s_add_i32 s3, s3, 20
	s_waitcnt lgkmcnt(0)
	v_cmp_gt_u32_e32 vcc, s3, v2
	s_and_saveexec_b64 s[56:57], vcc
	s_cbranch_execz .LBB0_446
	s_mov_b64 s[58:59], 0
